# GEMM K loops: back-to-back s_setprio 0 / s_setprio 1 between the two MFMA blocks of a super-phase removed
# speedup vs baseline: 1.0017x; 1.0017x over previous
.LBB0_179:
	s_add_u32 s29, s56, 0xfffc0080
	s_addc_u32 s30, s57, -1
	s_add_i32 s31, 0, 0x10000
	s_cmp_eq_u32 s28, 12
	s_cselect_b32 s61, s6, s30
	s_cselect_b32 s60, s7, s29
	s_cselect_b32 s59, s24, s27
	s_cselect_b32 s58, s25, s26
	s_add_i32 s29, 0, 0x14000
	v_add_u32_e32 v156, s31, v145
	v_add_u32_e32 v162, s29, v145
	ds_read_b128 v[140:143], v156
	ds_read_b128 v[148:151], v156 offset:1024
	ds_read_b128 v[152:155], v156 offset:2048
	ds_read_b128 v[156:159], v156 offset:3072
	ds_read_b128 v[178:181], v162
	ds_read_b128 v[182:185], v162 offset:1024
	ds_read_b128 v[186:189], v162 offset:2048
	ds_read_b128 v[190:193], v162 offset:3072
	v_lshl_add_u64 v[174:175], s[56:57], 0, v[136:137]
	s_add_i32 m0, s65, 0xc000
	ds_read_b128 v[194:197], v147
	ds_read_b128 v[198:201], v147 offset:1024
	ds_read_b128 v[202:205], v147 offset:2048
	ds_read_b128 v[220:223], v147 offset:3072
	ds_read_b128 v[228:231], v147 offset:4096
	ds_read_b128 v[232:235], v147 offset:5120
	ds_read_b128 v[236:239], v147 offset:6144
	ds_read_b128 v[240:243], v147 offset:7168
	global_load_lds_dwordx4 v[174:175], off
	v_lshl_add_u64 v[174:175], s[56:57], 0, v[138:139]
	s_add_i32 m0, s65, 0xe000
	s_nop 0
	global_load_lds_dwordx4 v[174:175], off
	s_waitcnt vmcnt(8)
	s_waitcnt lgkmcnt(0)
	s_barrier
	s_setprio 1
	s_waitcnt lgkmcnt(0)
	v_mfma_f32_16x16x32_bf16 v[124:127], v[140:143], v[194:197], v[124:127]
	v_mfma_f32_16x16x32_bf16 v[120:123], v[152:155], v[194:197], v[120:123]
	v_mfma_f32_16x16x32_bf16 v[108:111], v[140:143], v[202:205], v[108:111]
	v_mfma_f32_16x16x32_bf16 v[104:107], v[152:155], v[202:205], v[104:107]
	v_mfma_f32_16x16x32_bf16 v[92:95], v[140:143], v[228:231], v[92:95]
	v_mfma_f32_16x16x32_bf16 v[88:91], v[152:155], v[228:231], v[88:91]
	v_mfma_f32_16x16x32_bf16 v[76:79], v[140:143], v[236:239], v[76:79]
	v_mfma_f32_16x16x32_bf16 v[72:75], v[152:155], v[236:239], v[72:75]
	v_mfma_f32_16x16x32_bf16 v[124:127], v[148:151], v[198:201], v[124:127]
	v_mfma_f32_16x16x32_bf16 v[120:123], v[156:159], v[198:201], v[120:123]
	v_mfma_f32_16x16x32_bf16 v[108:111], v[148:151], v[220:223], v[108:111]
	v_mfma_f32_16x16x32_bf16 v[104:107], v[156:159], v[220:223], v[104:107]
	v_mfma_f32_16x16x32_bf16 v[92:95], v[148:151], v[232:235], v[92:95]
	v_mfma_f32_16x16x32_bf16 v[88:91], v[156:159], v[232:235], v[88:91]
	v_mfma_f32_16x16x32_bf16 v[76:79], v[148:151], v[240:243], v[76:79]
	v_mfma_f32_16x16x32_bf16 v[72:75], v[156:159], v[240:243], v[72:75]
	v_mfma_f32_16x16x32_bf16 v[116:119], v[178:181], v[194:197], v[116:119]
	v_mfma_f32_16x16x32_bf16 v[112:115], v[186:189], v[194:197], v[112:115]
	v_mfma_f32_16x16x32_bf16 v[100:103], v[178:181], v[202:205], v[100:103]
	v_mfma_f32_16x16x32_bf16 v[96:99], v[186:189], v[202:205], v[96:99]
	v_mfma_f32_16x16x32_bf16 v[84:87], v[178:181], v[228:231], v[84:87]
	v_mfma_f32_16x16x32_bf16 v[80:83], v[186:189], v[228:231], v[80:83]
	v_mfma_f32_16x16x32_bf16 v[68:71], v[178:181], v[236:239], v[68:71]
	v_mfma_f32_16x16x32_bf16 v[64:67], v[186:189], v[236:239], v[64:67]
	v_mfma_f32_16x16x32_bf16 v[116:119], v[182:185], v[198:201], v[116:119]
	v_mfma_f32_16x16x32_bf16 v[112:115], v[190:193], v[198:201], v[112:115]
	v_mfma_f32_16x16x32_bf16 v[100:103], v[182:185], v[220:223], v[100:103]
	v_mfma_f32_16x16x32_bf16 v[96:99], v[190:193], v[220:223], v[96:99]
	v_mfma_f32_16x16x32_bf16 v[84:87], v[182:185], v[232:235], v[84:87]
	v_mfma_f32_16x16x32_bf16 v[80:83], v[190:193], v[232:235], v[80:83]
	v_mfma_f32_16x16x32_bf16 v[68:71], v[182:185], v[240:243], v[68:71]
	v_mfma_f32_16x16x32_bf16 v[64:67], v[190:193], v[240:243], v[64:67]
	s_setprio 0
	s_barrier
	s_add_i32 s30, s31, s64
	v_lshl_add_u64 v[174:175], s[58:59], 0, v[132:133]
	s_mov_b32 m0, s30
	ds_read_b128 v[194:197], v147 offset:16384
	ds_read_b128 v[198:201], v147 offset:17408
	ds_read_b128 v[202:205], v147 offset:18432
	ds_read_b128 v[220:223], v147 offset:19456
	ds_read_b128 v[228:231], v147 offset:20480
	ds_read_b128 v[232:235], v147 offset:21504
	ds_read_b128 v[236:239], v147 offset:22528
	ds_read_b128 v[240:243], v147 offset:23552
	global_load_lds_dwordx4 v[174:175], off
	s_add_i32 m0, s30, 0x2000
	s_add_u32 s30, s58, 0x40000
	v_lshl_add_u64 v[176:177], s[58:59], 0, v[128:129]
	s_addc_u32 s31, s59, 0
	s_add_i32 s29, s29, s64
	global_load_lds_dwordx4 v[176:177], off
	v_lshl_add_u64 v[244:245], s[30:31], 0, v[132:133]
	s_mov_b32 m0, s29
	v_lshl_add_u64 v[246:247], s[60:61], 0, v[130:131]
	global_load_lds_dwordx4 v[244:245], off
	v_lshl_add_u64 v[244:245], s[30:31], 0, v[128:129]
	s_add_i32 m0, s29, 0x2000
	s_nop 0
	global_load_lds_dwordx4 v[244:245], off
	v_lshl_add_u64 v[244:245], s[60:61], 0, v[134:135]
	s_mov_b32 m0, s65
	s_nop 0
	global_load_lds_dwordx4 v[244:245], off
	s_mov_b32 m0, s66
	s_nop 0
	global_load_lds_dwordx4 v[246:247], off
	s_waitcnt vmcnt(8)
	s_waitcnt lgkmcnt(0)
	s_barrier
	s_setprio 1
	s_waitcnt lgkmcnt(0)
	v_mfma_f32_16x16x32_bf16 v[60:63], v[140:143], v[194:197], v[60:63]
	v_mfma_f32_16x16x32_bf16 v[56:59], v[152:155], v[194:197], v[56:59]
	v_mfma_f32_16x16x32_bf16 v[44:47], v[140:143], v[202:205], v[44:47]
	v_mfma_f32_16x16x32_bf16 v[40:43], v[152:155], v[202:205], v[40:43]
	v_mfma_f32_16x16x32_bf16 v[28:31], v[140:143], v[228:231], v[28:31]
	v_mfma_f32_16x16x32_bf16 v[24:27], v[152:155], v[228:231], v[24:27]
	v_mfma_f32_16x16x32_bf16 v[12:15], v[140:143], v[236:239], v[12:15]
	v_mfma_f32_16x16x32_bf16 v[8:11], v[152:155], v[236:239], v[8:11]
	v_mfma_f32_16x16x32_bf16 v[60:63], v[148:151], v[198:201], v[60:63]
	v_mfma_f32_16x16x32_bf16 v[56:59], v[156:159], v[198:201], v[56:59]
	v_mfma_f32_16x16x32_bf16 v[44:47], v[148:151], v[220:223], v[44:47]
	v_mfma_f32_16x16x32_bf16 v[40:43], v[156:159], v[220:223], v[40:43]
	v_mfma_f32_16x16x32_bf16 v[28:31], v[148:151], v[232:235], v[28:31]
	v_mfma_f32_16x16x32_bf16 v[24:27], v[156:159], v[232:235], v[24:27]
	v_mfma_f32_16x16x32_bf16 v[12:15], v[148:151], v[240:243], v[12:15]
	v_mfma_f32_16x16x32_bf16 v[8:11], v[156:159], v[240:243], v[8:11]
	v_mfma_f32_16x16x32_bf16 v[52:55], v[178:181], v[194:197], v[52:55]
	v_mfma_f32_16x16x32_bf16 v[48:51], v[186:189], v[194:197], v[48:51]
	v_mfma_f32_16x16x32_bf16 v[36:39], v[178:181], v[202:205], v[36:39]
	v_mfma_f32_16x16x32_bf16 v[32:35], v[186:189], v[202:205], v[32:35]
	v_mfma_f32_16x16x32_bf16 v[20:23], v[178:181], v[228:231], v[20:23]
	v_mfma_f32_16x16x32_bf16 v[16:19], v[186:189], v[228:231], v[16:19]
	v_mfma_f32_16x16x32_bf16 v[4:7], v[178:181], v[236:239], v[4:7]
	v_mfma_f32_16x16x32_bf16 v[0:3], v[186:189], v[236:239], v[0:3]
	v_mfma_f32_16x16x32_bf16 v[52:55], v[182:185], v[198:201], v[52:55]
	v_mfma_f32_16x16x32_bf16 v[48:51], v[190:193], v[198:201], v[48:51]
	v_mfma_f32_16x16x32_bf16 v[36:39], v[182:185], v[220:223], v[36:39]
	v_mfma_f32_16x16x32_bf16 v[32:35], v[190:193], v[220:223], v[32:35]
	v_mfma_f32_16x16x32_bf16 v[20:23], v[182:185], v[232:235], v[20:23]
	v_mfma_f32_16x16x32_bf16 v[16:19], v[190:193], v[232:235], v[16:19]
	v_mfma_f32_16x16x32_bf16 v[4:7], v[182:185], v[240:243], v[4:7]
	v_mfma_f32_16x16x32_bf16 v[0:3], v[190:193], v[240:243], v[0:3]
	s_setprio 0
	s_barrier
	s_add_i32 s29, 0, 0x18000
	s_add_i32 s49, 0, 0x1c000
	v_add_u32_e32 v156, s29, v145
	v_add_u32_e32 v162, s49, v145
	ds_read_b128 v[140:143], v156
	ds_read_b128 v[148:151], v156 offset:1024
	ds_read_b128 v[152:155], v156 offset:2048
	ds_read_b128 v[156:159], v156 offset:3072
	ds_read_b128 v[178:181], v162
	ds_read_b128 v[182:185], v162 offset:1024
	ds_read_b128 v[186:189], v162 offset:2048
	ds_read_b128 v[190:193], v162 offset:3072
	s_add_u32 s30, s60, 0x40000
	s_addc_u32 s31, s61, 0
	s_mov_b32 m0, s67
	v_lshl_add_u64 v[248:249], s[30:31], 0, v[134:135]
	ds_read_b128 v[194:197], v147 offset:32768
	ds_read_b128 v[198:201], v147 offset:33792
	ds_read_b128 v[202:205], v147 offset:34816
	ds_read_b128 v[220:223], v147 offset:35840
	ds_read_b128 v[228:231], v147 offset:36864
	ds_read_b128 v[232:235], v147 offset:37888
	ds_read_b128 v[236:239], v147 offset:38912
	ds_read_b128 v[240:243], v147 offset:39936
	global_load_lds_dwordx4 v[248:249], off
	v_lshl_add_u64 v[248:249], s[30:31], 0, v[130:131]
	s_mov_b32 m0, s68
	s_nop 0
	global_load_lds_dwordx4 v[248:249], off
	s_waitcnt vmcnt(8)
	s_waitcnt lgkmcnt(0)
	s_barrier
	s_setprio 1
	s_waitcnt lgkmcnt(0)
	v_mfma_f32_16x16x32_bf16 v[124:127], v[140:143], v[194:197], v[124:127]
	v_mfma_f32_16x16x32_bf16 v[120:123], v[152:155], v[194:197], v[120:123]
	v_mfma_f32_16x16x32_bf16 v[108:111], v[140:143], v[202:205], v[108:111]
	v_mfma_f32_16x16x32_bf16 v[104:107], v[152:155], v[202:205], v[104:107]
	v_mfma_f32_16x16x32_bf16 v[92:95], v[140:143], v[228:231], v[92:95]
	v_mfma_f32_16x16x32_bf16 v[88:91], v[152:155], v[228:231], v[88:91]
	v_mfma_f32_16x16x32_bf16 v[76:79], v[140:143], v[236:239], v[76:79]
	v_mfma_f32_16x16x32_bf16 v[72:75], v[152:155], v[236:239], v[72:75]
	v_mfma_f32_16x16x32_bf16 v[124:127], v[148:151], v[198:201], v[124:127]
	v_mfma_f32_16x16x32_bf16 v[120:123], v[156:159], v[198:201], v[120:123]
	v_mfma_f32_16x16x32_bf16 v[108:111], v[148:151], v[220:223], v[108:111]
	v_mfma_f32_16x16x32_bf16 v[104:107], v[156:159], v[220:223], v[104:107]
	v_mfma_f32_16x16x32_bf16 v[92:95], v[148:151], v[232:235], v[92:95]
	v_mfma_f32_16x16x32_bf16 v[88:91], v[156:159], v[232:235], v[88:91]
	v_mfma_f32_16x16x32_bf16 v[76:79], v[148:151], v[240:243], v[76:79]
	v_mfma_f32_16x16x32_bf16 v[72:75], v[156:159], v[240:243], v[72:75]
	v_mfma_f32_16x16x32_bf16 v[116:119], v[178:181], v[194:197], v[116:119]
	v_mfma_f32_16x16x32_bf16 v[112:115], v[186:189], v[194:197], v[112:115]
	v_mfma_f32_16x16x32_bf16 v[100:103], v[178:181], v[202:205], v[100:103]
	v_mfma_f32_16x16x32_bf16 v[96:99], v[186:189], v[202:205], v[96:99]
	v_mfma_f32_16x16x32_bf16 v[84:87], v[178:181], v[228:231], v[84:87]
	v_mfma_f32_16x16x32_bf16 v[80:83], v[186:189], v[228:231], v[80:83]
	v_mfma_f32_16x16x32_bf16 v[68:71], v[178:181], v[236:239], v[68:71]
	v_mfma_f32_16x16x32_bf16 v[64:67], v[186:189], v[236:239], v[64:67]
	v_mfma_f32_16x16x32_bf16 v[116:119], v[182:185], v[198:201], v[116:119]
	v_mfma_f32_16x16x32_bf16 v[112:115], v[190:193], v[198:201], v[112:115]
	v_mfma_f32_16x16x32_bf16 v[100:103], v[182:185], v[220:223], v[100:103]
	v_mfma_f32_16x16x32_bf16 v[96:99], v[190:193], v[220:223], v[96:99]
	v_mfma_f32_16x16x32_bf16 v[84:87], v[182:185], v[232:235], v[84:87]
	v_mfma_f32_16x16x32_bf16 v[80:83], v[190:193], v[232:235], v[80:83]
	v_mfma_f32_16x16x32_bf16 v[68:71], v[182:185], v[240:243], v[68:71]
	v_mfma_f32_16x16x32_bf16 v[64:67], v[190:193], v[240:243], v[64:67]
	s_setprio 0
	s_barrier
	s_add_i32 s29, s29, s64
	v_lshl_add_u64 v[174:175], v[174:175], 0, s[4:5]
	s_mov_b32 m0, s29
	ds_read_b128 v[194:197], v147 offset:49152
	ds_read_b128 v[198:201], v147 offset:50176
	ds_read_b128 v[202:205], v147 offset:51200
	ds_read_b128 v[220:223], v147 offset:52224
	ds_read_b128 v[228:231], v147 offset:53248
	ds_read_b128 v[232:235], v147 offset:54272
	ds_read_b128 v[236:239], v147 offset:55296
	ds_read_b128 v[240:243], v147 offset:56320
	global_load_lds_dwordx4 v[174:175], off
	s_add_i32 m0, s29, 0x2000
	s_add_u32 s30, s58, 0x40080
	v_lshl_add_u64 v[174:175], v[176:177], 0, s[4:5]
	s_addc_u32 s31, s59, 0
	s_add_i32 s29, s49, s64
	global_load_lds_dwordx4 v[174:175], off
	v_lshl_add_u64 v[174:175], s[30:31], 0, v[132:133]
	s_mov_b32 m0, s29
	s_nop 0
	global_load_lds_dwordx4 v[174:175], off
	v_lshl_add_u64 v[174:175], s[30:31], 0, v[128:129]
	s_add_i32 m0, s29, 0x2000
	s_nop 0
	global_load_lds_dwordx4 v[174:175], off
	v_lshl_add_u64 v[174:175], v[244:245], 0, s[4:5]
	s_mov_b32 m0, s73
	s_nop 0
	global_load_lds_dwordx4 v[174:175], off
	v_lshl_add_u64 v[174:175], v[246:247], 0, s[4:5]
	s_mov_b32 m0, s74
	s_nop 0
	global_load_lds_dwordx4 v[174:175], off
	s_waitcnt vmcnt(8)
	s_waitcnt lgkmcnt(0)
	s_barrier
	s_setprio 1
	s_waitcnt lgkmcnt(0)
	v_mfma_f32_16x16x32_bf16 v[60:63], v[140:143], v[194:197], v[60:63]
	v_mfma_f32_16x16x32_bf16 v[56:59], v[152:155], v[194:197], v[56:59]
	v_mfma_f32_16x16x32_bf16 v[44:47], v[140:143], v[202:205], v[44:47]
	v_mfma_f32_16x16x32_bf16 v[40:43], v[152:155], v[202:205], v[40:43]
	v_mfma_f32_16x16x32_bf16 v[28:31], v[140:143], v[228:231], v[28:31]
	v_mfma_f32_16x16x32_bf16 v[24:27], v[152:155], v[228:231], v[24:27]
	v_mfma_f32_16x16x32_bf16 v[12:15], v[140:143], v[236:239], v[12:15]
	v_mfma_f32_16x16x32_bf16 v[8:11], v[152:155], v[236:239], v[8:11]
	v_mfma_f32_16x16x32_bf16 v[60:63], v[148:151], v[198:201], v[60:63]
	v_mfma_f32_16x16x32_bf16 v[56:59], v[156:159], v[198:201], v[56:59]
	v_mfma_f32_16x16x32_bf16 v[44:47], v[148:151], v[220:223], v[44:47]
	v_mfma_f32_16x16x32_bf16 v[40:43], v[156:159], v[220:223], v[40:43]
	v_mfma_f32_16x16x32_bf16 v[28:31], v[148:151], v[232:235], v[28:31]
	v_mfma_f32_16x16x32_bf16 v[24:27], v[156:159], v[232:235], v[24:27]
	v_mfma_f32_16x16x32_bf16 v[12:15], v[148:151], v[240:243], v[12:15]
	v_mfma_f32_16x16x32_bf16 v[8:11], v[156:159], v[240:243], v[8:11]
	v_mfma_f32_16x16x32_bf16 v[52:55], v[178:181], v[194:197], v[52:55]
	v_mfma_f32_16x16x32_bf16 v[48:51], v[186:189], v[194:197], v[48:51]
	v_mfma_f32_16x16x32_bf16 v[36:39], v[178:181], v[202:205], v[36:39]
	v_mfma_f32_16x16x32_bf16 v[32:35], v[186:189], v[202:205], v[32:35]
	v_mfma_f32_16x16x32_bf16 v[20:23], v[178:181], v[228:231], v[20:23]
	v_mfma_f32_16x16x32_bf16 v[16:19], v[186:189], v[228:231], v[16:19]
	v_mfma_f32_16x16x32_bf16 v[4:7], v[178:181], v[236:239], v[4:7]
	v_mfma_f32_16x16x32_bf16 v[0:3], v[186:189], v[236:239], v[0:3]
	v_mfma_f32_16x16x32_bf16 v[52:55], v[182:185], v[198:201], v[52:55]
	v_mfma_f32_16x16x32_bf16 v[48:51], v[190:193], v[198:201], v[48:51]
	v_mfma_f32_16x16x32_bf16 v[36:39], v[182:185], v[220:223], v[36:39]
	v_mfma_f32_16x16x32_bf16 v[32:35], v[190:193], v[220:223], v[32:35]
	v_mfma_f32_16x16x32_bf16 v[20:23], v[182:185], v[232:235], v[20:23]
	v_mfma_f32_16x16x32_bf16 v[16:19], v[190:193], v[232:235], v[16:19]
	v_mfma_f32_16x16x32_bf16 v[4:7], v[182:185], v[240:243], v[4:7]
	v_mfma_f32_16x16x32_bf16 v[0:3], v[190:193], v[240:243], v[0:3]
	s_setprio 0
	s_barrier
	s_add_i32 s28, s28, 2
	s_add_u32 s56, s56, 0x100
	s_addc_u32 s57, s57, 0
	s_add_u32 s26, s26, 0x100
	s_addc_u32 s27, s27, 0
	s_cmp_gt_u32 s28, 13
	s_cbranch_scc0 .LBB0_179
	s_and_b64 vcc, exec, s[46:47]
	s_cbranch_vccz .LBB0_182
	s_barrier

.LBB0_204:
	s_add_u32 s28, s42, 0xfffc0080
	s_addc_u32 s29, s43, -1
	s_add_i32 s30, 0, 0x10000
	s_cmp_eq_u32 s27, 12
	s_cselect_b32 s63, s6, s29
	s_cselect_b32 s62, s7, s28
	s_cselect_b32 s61, s23, s26
	s_cselect_b32 s60, s24, s25
	s_add_i32 s31, 0, 0x14000
	v_add_u32_e32 v140, s30, v221
	v_add_u32_e32 v156, s31, v221
	ds_read_b128 v[128:131], v140
	ds_read_b128 v[132:135], v140 offset:1024
	ds_read_b128 v[136:139], v140 offset:2048
	ds_read_b128 v[140:143], v140 offset:3072
	ds_read_b128 v[144:147], v156
	ds_read_b128 v[148:151], v156 offset:1024
	ds_read_b128 v[152:155], v156 offset:2048
	ds_read_b128 v[156:159], v156 offset:3072
	v_lshl_add_u64 v[174:175], s[42:43], 0, v[184:185]
	s_add_i32 m0, s67, 0xc000
	ds_read_b128 v[188:191], v223
	ds_read_b128 v[192:195], v223 offset:1024
	ds_read_b128 v[196:199], v223 offset:2048
	ds_read_b128 v[200:203], v223 offset:3072
	ds_read_b128 v[228:231], v223 offset:4096
	ds_read_b128 v[232:235], v223 offset:5120
	ds_read_b128 v[236:239], v223 offset:6144
	ds_read_b128 v[240:243], v223 offset:7168
	global_load_lds_dwordx4 v[174:175], off
	v_lshl_add_u64 v[174:175], s[42:43], 0, v[186:187]
	s_add_i32 m0, s67, 0xe000
	s_nop 0
	global_load_lds_dwordx4 v[174:175], off
	s_waitcnt vmcnt(8)
	s_waitcnt lgkmcnt(0)
	s_barrier
	s_setprio 1
	s_waitcnt lgkmcnt(0)
	v_mfma_f32_16x16x32_bf16 v[124:127], v[128:131], v[188:191], v[124:127]
	v_mfma_f32_16x16x32_bf16 v[120:123], v[136:139], v[188:191], v[120:123]
	v_mfma_f32_16x16x32_bf16 v[116:119], v[128:131], v[196:199], v[116:119]
	v_mfma_f32_16x16x32_bf16 v[108:111], v[136:139], v[196:199], v[108:111]
	v_mfma_f32_16x16x32_bf16 v[100:103], v[128:131], v[228:231], v[100:103]
	v_mfma_f32_16x16x32_bf16 v[92:95], v[136:139], v[228:231], v[92:95]
	v_mfma_f32_16x16x32_bf16 v[84:87], v[128:131], v[236:239], v[84:87]
	v_mfma_f32_16x16x32_bf16 v[76:79], v[136:139], v[236:239], v[76:79]
	v_mfma_f32_16x16x32_bf16 v[124:127], v[132:135], v[192:195], v[124:127]
	v_mfma_f32_16x16x32_bf16 v[120:123], v[140:143], v[192:195], v[120:123]
	v_mfma_f32_16x16x32_bf16 v[116:119], v[132:135], v[200:203], v[116:119]
	v_mfma_f32_16x16x32_bf16 v[108:111], v[140:143], v[200:203], v[108:111]
	v_mfma_f32_16x16x32_bf16 v[100:103], v[132:135], v[232:235], v[100:103]
	v_mfma_f32_16x16x32_bf16 v[92:95], v[140:143], v[232:235], v[92:95]
	v_mfma_f32_16x16x32_bf16 v[84:87], v[132:135], v[240:243], v[84:87]
	v_mfma_f32_16x16x32_bf16 v[76:79], v[140:143], v[240:243], v[76:79]
	v_mfma_f32_16x16x32_bf16 v[112:115], v[144:147], v[188:191], v[112:115]
	v_mfma_f32_16x16x32_bf16 v[104:107], v[152:155], v[188:191], v[104:107]
	v_mfma_f32_16x16x32_bf16 v[96:99], v[144:147], v[196:199], v[96:99]
	v_mfma_f32_16x16x32_bf16 v[88:91], v[152:155], v[196:199], v[88:91]
	v_mfma_f32_16x16x32_bf16 v[80:83], v[144:147], v[228:231], v[80:83]
	v_mfma_f32_16x16x32_bf16 v[72:75], v[152:155], v[228:231], v[72:75]
	v_mfma_f32_16x16x32_bf16 v[68:71], v[144:147], v[236:239], v[68:71]
	v_mfma_f32_16x16x32_bf16 v[64:67], v[152:155], v[236:239], v[64:67]
	v_mfma_f32_16x16x32_bf16 v[112:115], v[148:151], v[192:195], v[112:115]
	v_mfma_f32_16x16x32_bf16 v[104:107], v[156:159], v[192:195], v[104:107]
	v_mfma_f32_16x16x32_bf16 v[96:99], v[148:151], v[200:203], v[96:99]
	v_mfma_f32_16x16x32_bf16 v[88:91], v[156:159], v[200:203], v[88:91]
	v_mfma_f32_16x16x32_bf16 v[80:83], v[148:151], v[232:235], v[80:83]
	v_mfma_f32_16x16x32_bf16 v[72:75], v[156:159], v[232:235], v[72:75]
	v_mfma_f32_16x16x32_bf16 v[68:71], v[148:151], v[240:243], v[68:71]
	v_mfma_f32_16x16x32_bf16 v[64:67], v[156:159], v[240:243], v[64:67]
	s_setprio 0
	s_barrier
	s_add_i32 s28, s30, s66
	v_lshl_add_u64 v[174:175], s[60:61], 0, v[162:163]
	s_mov_b32 m0, s28
	ds_read_b128 v[188:191], v223 offset:16384
	ds_read_b128 v[192:195], v223 offset:17408
	ds_read_b128 v[196:199], v223 offset:18432
	ds_read_b128 v[200:203], v223 offset:19456
	ds_read_b128 v[228:231], v223 offset:20480
	ds_read_b128 v[232:235], v223 offset:21504
	ds_read_b128 v[236:239], v223 offset:22528
	ds_read_b128 v[240:243], v223 offset:23552
	global_load_lds_dwordx4 v[174:175], off
	s_add_i32 m0, s28, 0x2000
	s_add_u32 s28, s60, 0x40000
	v_lshl_add_u64 v[176:177], s[60:61], 0, v[178:179]
	s_addc_u32 s29, s61, 0
	s_add_i32 s30, s31, s66
	global_load_lds_dwordx4 v[176:177], off
	v_lshl_add_u64 v[204:205], s[28:29], 0, v[162:163]
	s_mov_b32 m0, s30
	v_lshl_add_u64 v[244:245], s[62:63], 0, v[180:181]
	global_load_lds_dwordx4 v[204:205], off
	v_lshl_add_u64 v[204:205], s[28:29], 0, v[178:179]
	s_add_i32 m0, s30, 0x2000
	s_nop 0
	global_load_lds_dwordx4 v[204:205], off
	v_lshl_add_u64 v[204:205], s[62:63], 0, v[182:183]
	s_mov_b32 m0, s67
	s_nop 0
	global_load_lds_dwordx4 v[204:205], off
	s_mov_b32 m0, s68
	s_nop 0
	global_load_lds_dwordx4 v[244:245], off
	s_waitcnt vmcnt(8)
	s_waitcnt lgkmcnt(0)
	s_barrier
	s_setprio 1
	s_waitcnt lgkmcnt(0)
	v_mfma_f32_16x16x32_bf16 v[60:63], v[128:131], v[188:191], v[60:63]
	v_mfma_f32_16x16x32_bf16 v[56:59], v[136:139], v[188:191], v[56:59]
	v_mfma_f32_16x16x32_bf16 v[52:55], v[128:131], v[196:199], v[52:55]
	v_mfma_f32_16x16x32_bf16 v[44:47], v[136:139], v[196:199], v[44:47]
	v_mfma_f32_16x16x32_bf16 v[36:39], v[128:131], v[228:231], v[36:39]
	v_mfma_f32_16x16x32_bf16 v[28:31], v[136:139], v[228:231], v[28:31]
	v_mfma_f32_16x16x32_bf16 v[20:23], v[128:131], v[236:239], v[20:23]
	v_mfma_f32_16x16x32_bf16 v[12:15], v[136:139], v[236:239], v[12:15]
	v_mfma_f32_16x16x32_bf16 v[60:63], v[132:135], v[192:195], v[60:63]
	v_mfma_f32_16x16x32_bf16 v[56:59], v[140:143], v[192:195], v[56:59]
	v_mfma_f32_16x16x32_bf16 v[52:55], v[132:135], v[200:203], v[52:55]
	v_mfma_f32_16x16x32_bf16 v[44:47], v[140:143], v[200:203], v[44:47]
	v_mfma_f32_16x16x32_bf16 v[36:39], v[132:135], v[232:235], v[36:39]
	v_mfma_f32_16x16x32_bf16 v[28:31], v[140:143], v[232:235], v[28:31]
	v_mfma_f32_16x16x32_bf16 v[20:23], v[132:135], v[240:243], v[20:23]
	v_mfma_f32_16x16x32_bf16 v[12:15], v[140:143], v[240:243], v[12:15]
	v_mfma_f32_16x16x32_bf16 v[48:51], v[144:147], v[188:191], v[48:51]
	v_mfma_f32_16x16x32_bf16 v[40:43], v[152:155], v[188:191], v[40:43]
	v_mfma_f32_16x16x32_bf16 v[32:35], v[144:147], v[196:199], v[32:35]
	v_mfma_f32_16x16x32_bf16 v[24:27], v[152:155], v[196:199], v[24:27]
	v_mfma_f32_16x16x32_bf16 v[16:19], v[144:147], v[228:231], v[16:19]
	v_mfma_f32_16x16x32_bf16 v[8:11], v[152:155], v[228:231], v[8:11]
	v_mfma_f32_16x16x32_bf16 v[4:7], v[144:147], v[236:239], v[4:7]
	v_mfma_f32_16x16x32_bf16 v[0:3], v[152:155], v[236:239], v[0:3]
	v_mfma_f32_16x16x32_bf16 v[48:51], v[148:151], v[192:195], v[48:51]
	v_mfma_f32_16x16x32_bf16 v[40:43], v[156:159], v[192:195], v[40:43]
	v_mfma_f32_16x16x32_bf16 v[32:35], v[148:151], v[200:203], v[32:35]
	v_mfma_f32_16x16x32_bf16 v[24:27], v[156:159], v[200:203], v[24:27]
	v_mfma_f32_16x16x32_bf16 v[16:19], v[148:151], v[232:235], v[16:19]
	v_mfma_f32_16x16x32_bf16 v[8:11], v[156:159], v[232:235], v[8:11]
	v_mfma_f32_16x16x32_bf16 v[4:7], v[148:151], v[240:243], v[4:7]
	v_mfma_f32_16x16x32_bf16 v[0:3], v[156:159], v[240:243], v[0:3]
	s_setprio 0
	s_barrier
	s_add_i32 s30, 0, 0x18000
	s_add_i32 s31, 0, 0x1c000
	v_add_u32_e32 v140, s30, v221
	v_add_u32_e32 v156, s31, v221
	ds_read_b128 v[128:131], v140
	ds_read_b128 v[132:135], v140 offset:1024
	ds_read_b128 v[136:139], v140 offset:2048
	ds_read_b128 v[140:143], v140 offset:3072
	ds_read_b128 v[144:147], v156
	ds_read_b128 v[148:151], v156 offset:1024
	ds_read_b128 v[152:155], v156 offset:2048
	ds_read_b128 v[156:159], v156 offset:3072
	s_add_u32 s28, s62, 0x40000
	s_addc_u32 s29, s63, 0
	s_mov_b32 m0, s69
	v_lshl_add_u64 v[246:247], s[28:29], 0, v[182:183]
	ds_read_b128 v[188:191], v223 offset:32768
	ds_read_b128 v[192:195], v223 offset:33792
	ds_read_b128 v[196:199], v223 offset:34816
	ds_read_b128 v[200:203], v223 offset:35840
	ds_read_b128 v[228:231], v223 offset:36864
	ds_read_b128 v[232:235], v223 offset:37888
	ds_read_b128 v[236:239], v223 offset:38912
	ds_read_b128 v[240:243], v223 offset:39936
	global_load_lds_dwordx4 v[246:247], off
	v_lshl_add_u64 v[246:247], s[28:29], 0, v[180:181]
	s_mov_b32 m0, s70
	s_nop 0
	global_load_lds_dwordx4 v[246:247], off
	s_waitcnt vmcnt(8)
	s_waitcnt lgkmcnt(0)
	s_barrier
	s_setprio 1
	s_waitcnt lgkmcnt(0)
	v_mfma_f32_16x16x32_bf16 v[124:127], v[128:131], v[188:191], v[124:127]
	v_mfma_f32_16x16x32_bf16 v[120:123], v[136:139], v[188:191], v[120:123]
	v_mfma_f32_16x16x32_bf16 v[116:119], v[128:131], v[196:199], v[116:119]
	v_mfma_f32_16x16x32_bf16 v[108:111], v[136:139], v[196:199], v[108:111]
	v_mfma_f32_16x16x32_bf16 v[100:103], v[128:131], v[228:231], v[100:103]
	v_mfma_f32_16x16x32_bf16 v[92:95], v[136:139], v[228:231], v[92:95]
	v_mfma_f32_16x16x32_bf16 v[84:87], v[128:131], v[236:239], v[84:87]
	v_mfma_f32_16x16x32_bf16 v[76:79], v[136:139], v[236:239], v[76:79]
	v_mfma_f32_16x16x32_bf16 v[124:127], v[132:135], v[192:195], v[124:127]
	v_mfma_f32_16x16x32_bf16 v[120:123], v[140:143], v[192:195], v[120:123]
	v_mfma_f32_16x16x32_bf16 v[116:119], v[132:135], v[200:203], v[116:119]
	v_mfma_f32_16x16x32_bf16 v[108:111], v[140:143], v[200:203], v[108:111]
	v_mfma_f32_16x16x32_bf16 v[100:103], v[132:135], v[232:235], v[100:103]
	v_mfma_f32_16x16x32_bf16 v[92:95], v[140:143], v[232:235], v[92:95]
	v_mfma_f32_16x16x32_bf16 v[84:87], v[132:135], v[240:243], v[84:87]
	v_mfma_f32_16x16x32_bf16 v[76:79], v[140:143], v[240:243], v[76:79]
	v_mfma_f32_16x16x32_bf16 v[112:115], v[144:147], v[188:191], v[112:115]
	v_mfma_f32_16x16x32_bf16 v[104:107], v[152:155], v[188:191], v[104:107]
	v_mfma_f32_16x16x32_bf16 v[96:99], v[144:147], v[196:199], v[96:99]
	v_mfma_f32_16x16x32_bf16 v[88:91], v[152:155], v[196:199], v[88:91]
	v_mfma_f32_16x16x32_bf16 v[80:83], v[144:147], v[228:231], v[80:83]
	v_mfma_f32_16x16x32_bf16 v[72:75], v[152:155], v[228:231], v[72:75]
	v_mfma_f32_16x16x32_bf16 v[68:71], v[144:147], v[236:239], v[68:71]
	v_mfma_f32_16x16x32_bf16 v[64:67], v[152:155], v[236:239], v[64:67]
	v_mfma_f32_16x16x32_bf16 v[112:115], v[148:151], v[192:195], v[112:115]
	v_mfma_f32_16x16x32_bf16 v[104:107], v[156:159], v[192:195], v[104:107]
	v_mfma_f32_16x16x32_bf16 v[96:99], v[148:151], v[200:203], v[96:99]
	v_mfma_f32_16x16x32_bf16 v[88:91], v[156:159], v[200:203], v[88:91]
	v_mfma_f32_16x16x32_bf16 v[80:83], v[148:151], v[232:235], v[80:83]
	v_mfma_f32_16x16x32_bf16 v[72:75], v[156:159], v[232:235], v[72:75]
	v_mfma_f32_16x16x32_bf16 v[68:71], v[148:151], v[240:243], v[68:71]
	v_mfma_f32_16x16x32_bf16 v[64:67], v[156:159], v[240:243], v[64:67]
	s_setprio 0
	s_barrier
	s_add_i32 s28, s30, s66
	v_lshl_add_u64 v[174:175], v[174:175], 0, s[4:5]
	s_mov_b32 m0, s28
	ds_read_b128 v[188:191], v223 offset:49152
	ds_read_b128 v[192:195], v223 offset:50176
	ds_read_b128 v[196:199], v223 offset:51200
	ds_read_b128 v[200:203], v223 offset:52224
	ds_read_b128 v[228:231], v223 offset:53248
	ds_read_b128 v[232:235], v223 offset:54272
	ds_read_b128 v[236:239], v223 offset:55296
	ds_read_b128 v[240:243], v223 offset:56320
	global_load_lds_dwordx4 v[174:175], off
	s_add_i32 m0, s28, 0x2000
	s_add_u32 s28, s60, 0x40080
	v_lshl_add_u64 v[174:175], v[176:177], 0, s[4:5]
	s_addc_u32 s29, s61, 0
	s_add_i32 s30, s31, s66
	global_load_lds_dwordx4 v[174:175], off
	v_lshl_add_u64 v[174:175], s[28:29], 0, v[162:163]
	s_mov_b32 m0, s30
	s_nop 0
	global_load_lds_dwordx4 v[174:175], off
	v_lshl_add_u64 v[174:175], s[28:29], 0, v[178:179]
	s_add_i32 m0, s30, 0x2000
	s_nop 0
	global_load_lds_dwordx4 v[174:175], off
	v_lshl_add_u64 v[174:175], v[204:205], 0, s[4:5]
	s_mov_b32 m0, s71
	s_nop 0
	global_load_lds_dwordx4 v[174:175], off
	v_lshl_add_u64 v[174:175], v[244:245], 0, s[4:5]
	s_mov_b32 m0, s72
	s_nop 0
	global_load_lds_dwordx4 v[174:175], off
	s_waitcnt vmcnt(8)
	s_waitcnt lgkmcnt(0)
	s_barrier
	s_setprio 1
	s_waitcnt lgkmcnt(0)
	v_mfma_f32_16x16x32_bf16 v[60:63], v[128:131], v[188:191], v[60:63]
	v_mfma_f32_16x16x32_bf16 v[56:59], v[136:139], v[188:191], v[56:59]
	v_mfma_f32_16x16x32_bf16 v[52:55], v[128:131], v[196:199], v[52:55]
	v_mfma_f32_16x16x32_bf16 v[44:47], v[136:139], v[196:199], v[44:47]
	v_mfma_f32_16x16x32_bf16 v[36:39], v[128:131], v[228:231], v[36:39]
	v_mfma_f32_16x16x32_bf16 v[28:31], v[136:139], v[228:231], v[28:31]
	v_mfma_f32_16x16x32_bf16 v[20:23], v[128:131], v[236:239], v[20:23]
	v_mfma_f32_16x16x32_bf16 v[12:15], v[136:139], v[236:239], v[12:15]
	v_mfma_f32_16x16x32_bf16 v[60:63], v[132:135], v[192:195], v[60:63]
	v_mfma_f32_16x16x32_bf16 v[56:59], v[140:143], v[192:195], v[56:59]
	v_mfma_f32_16x16x32_bf16 v[52:55], v[132:135], v[200:203], v[52:55]
	v_mfma_f32_16x16x32_bf16 v[44:47], v[140:143], v[200:203], v[44:47]
	v_mfma_f32_16x16x32_bf16 v[36:39], v[132:135], v[232:235], v[36:39]
	v_mfma_f32_16x16x32_bf16 v[28:31], v[140:143], v[232:235], v[28:31]
	v_mfma_f32_16x16x32_bf16 v[20:23], v[132:135], v[240:243], v[20:23]
	v_mfma_f32_16x16x32_bf16 v[12:15], v[140:143], v[240:243], v[12:15]
	v_mfma_f32_16x16x32_bf16 v[48:51], v[144:147], v[188:191], v[48:51]
	v_mfma_f32_16x16x32_bf16 v[40:43], v[152:155], v[188:191], v[40:43]
	v_mfma_f32_16x16x32_bf16 v[32:35], v[144:147], v[196:199], v[32:35]
	v_mfma_f32_16x16x32_bf16 v[24:27], v[152:155], v[196:199], v[24:27]
	v_mfma_f32_16x16x32_bf16 v[16:19], v[144:147], v[228:231], v[16:19]
	v_mfma_f32_16x16x32_bf16 v[8:11], v[152:155], v[228:231], v[8:11]
	v_mfma_f32_16x16x32_bf16 v[4:7], v[144:147], v[236:239], v[4:7]
	v_mfma_f32_16x16x32_bf16 v[0:3], v[152:155], v[236:239], v[0:3]
	v_mfma_f32_16x16x32_bf16 v[48:51], v[148:151], v[192:195], v[48:51]
	v_mfma_f32_16x16x32_bf16 v[40:43], v[156:159], v[192:195], v[40:43]
	v_mfma_f32_16x16x32_bf16 v[32:35], v[148:151], v[200:203], v[32:35]
	v_mfma_f32_16x16x32_bf16 v[24:27], v[156:159], v[200:203], v[24:27]
	v_mfma_f32_16x16x32_bf16 v[16:19], v[148:151], v[232:235], v[16:19]
	v_mfma_f32_16x16x32_bf16 v[8:11], v[156:159], v[232:235], v[8:11]
	v_mfma_f32_16x16x32_bf16 v[4:7], v[148:151], v[240:243], v[4:7]
	v_mfma_f32_16x16x32_bf16 v[0:3], v[156:159], v[240:243], v[0:3]
	s_setprio 0
	s_barrier
	s_add_i32 s27, s27, 2
	s_add_u32 s42, s42, 0x100
	s_addc_u32 s43, s43, 0
	s_add_u32 s25, s25, 0x100
	s_addc_u32 s26, s26, 0
	s_cmp_gt_u32 s27, 13
	s_cbranch_scc0 .LBB0_204
	s_and_b64 vcc, exec, s[50:51]
	s_cbranch_vccz .LBB0_207
	s_barrier

.LBB0_502:
	s_add_i32 s62, 0, 0x10000
	s_add_i32 s61, 0, 0x14000
	v_add_u32_e32 v19, s62, v16
	v_add_u32_e32 v20, s61, v16
	ds_read_b128 v[22:25], v19
	ds_read_b128 v[26:29], v19 offset:1024
	ds_read_b128 v[30:33], v19 offset:2048
	ds_read_b128 v[34:37], v19 offset:3072
	ds_read_b128 v[38:41], v20
	ds_read_b128 v[42:45], v20 offset:1024
	ds_read_b128 v[46:49], v20 offset:2048
	ds_read_b128 v[50:53], v20 offset:3072
	s_add_u32 s58, s50, 0x18080
	s_addc_u32 s59, s51, 0
	s_add_i32 s65, s26, 0xc000
	v_lshl_add_u64 v[78:79], s[58:59], 0, v[6:7]
	s_mov_b32 m0, s65
	s_add_i32 s57, s26, 0xe000
	ds_read_b128 v[8:11], v17
	ds_read_b128 v[12:15], v17 offset:1024
	ds_read_b128 v[54:57], v17 offset:2048
	ds_read_b128 v[58:61], v17 offset:3072
	ds_read_b128 v[62:65], v17 offset:4096
	ds_read_b128 v[66:69], v17 offset:5120
	ds_read_b128 v[70:73], v17 offset:6144
	ds_read_b128 v[74:77], v17 offset:7168
	global_load_lds_dwordx4 v[78:79], off
	v_lshl_add_u64 v[78:79], s[58:59], 0, v[2:3]
	s_mov_b32 m0, s57
	s_nop 0
	global_load_lds_dwordx4 v[78:79], off
	s_waitcnt vmcnt(8)
	s_waitcnt lgkmcnt(0)
	s_barrier
	s_setprio 1
	s_waitcnt lgkmcnt(0)
	v_mfma_f32_16x16x32_bf16 v[78:81], v[22:25], v[8:11], 0
	v_mfma_f32_16x16x32_bf16 v[82:85], v[30:33], v[8:11], 0
	v_mfma_f32_16x16x32_bf16 v[86:89], v[22:25], v[54:57], 0
	v_mfma_f32_16x16x32_bf16 v[90:93], v[30:33], v[54:57], 0
	v_mfma_f32_16x16x32_bf16 v[94:97], v[22:25], v[62:65], 0
	v_mfma_f32_16x16x32_bf16 v[98:101], v[30:33], v[62:65], 0
	v_mfma_f32_16x16x32_bf16 v[102:105], v[22:25], v[70:73], 0
	v_mfma_f32_16x16x32_bf16 v[106:109], v[30:33], v[70:73], 0
	v_mfma_f32_16x16x32_bf16 v[78:81], v[26:29], v[12:15], v[78:81]
	v_mfma_f32_16x16x32_bf16 v[82:85], v[34:37], v[12:15], v[82:85]
	v_mfma_f32_16x16x32_bf16 v[86:89], v[26:29], v[58:61], v[86:89]
	v_mfma_f32_16x16x32_bf16 v[90:93], v[34:37], v[58:61], v[90:93]
	v_mfma_f32_16x16x32_bf16 v[94:97], v[26:29], v[66:69], v[94:97]
	v_mfma_f32_16x16x32_bf16 v[98:101], v[34:37], v[66:69], v[98:101]
	v_mfma_f32_16x16x32_bf16 v[102:105], v[26:29], v[74:77], v[102:105]
	v_mfma_f32_16x16x32_bf16 v[106:109], v[34:37], v[74:77], v[106:109]
	v_mfma_f32_16x16x32_bf16 v[110:113], v[38:41], v[8:11], 0
	v_mfma_f32_16x16x32_bf16 v[8:11], v[46:49], v[8:11], 0
	v_mfma_f32_16x16x32_bf16 v[114:117], v[50:53], v[12:15], v[8:11]
	v_mfma_f32_16x16x32_bf16 v[8:11], v[38:41], v[54:57], 0
	v_mfma_f32_16x16x32_bf16 v[118:121], v[42:45], v[58:61], v[8:11]
	v_mfma_f32_16x16x32_bf16 v[8:11], v[46:49], v[54:57], 0
	v_mfma_f32_16x16x32_bf16 v[54:57], v[50:53], v[58:61], v[8:11]
	v_mfma_f32_16x16x32_bf16 v[8:11], v[38:41], v[62:65], 0
	v_mfma_f32_16x16x32_bf16 v[58:61], v[42:45], v[66:69], v[8:11]
	v_mfma_f32_16x16x32_bf16 v[8:11], v[46:49], v[62:65], 0
	v_mfma_f32_16x16x32_bf16 v[62:65], v[50:53], v[66:69], v[8:11]
	v_mfma_f32_16x16x32_bf16 v[8:11], v[38:41], v[70:73], 0
	v_mfma_f32_16x16x32_bf16 v[66:69], v[42:45], v[74:77], v[8:11]
	v_mfma_f32_16x16x32_bf16 v[8:11], v[46:49], v[70:73], 0
	v_mfma_f32_16x16x32_bf16 v[110:113], v[42:45], v[12:15], v[110:113]
	v_mfma_f32_16x16x32_bf16 v[70:73], v[50:53], v[74:77], v[8:11]
	s_setprio 0
	s_barrier
	s_nop 3
	v_lshl_add_u64 v[8:9], s[52:53], 0, v[4:5]
	s_mov_b64 s[68:69], 0x100
	s_add_i32 s62, s62, s25
	v_lshl_add_u64 v[10:11], v[8:9], 0, s[68:69]
	s_mov_b32 m0, s62
	s_add_i32 s58, s62, 0x2000
	ds_read_b128 v[74:77], v17 offset:16384
	ds_read_b128 v[122:125], v17 offset:17408
	ds_read_b128 v[126:129], v17 offset:18432
	ds_read_b128 v[130:133], v17 offset:19456
	ds_read_b128 v[134:137], v17 offset:20480
	ds_read_b128 v[138:141], v17 offset:21504
	ds_read_b128 v[142:145], v17 offset:22528
	ds_read_b128 v[146:149], v17 offset:23552
	global_load_lds_dwordx4 v[10:11], off
	v_lshl_add_u64 v[10:11], s[52:53], 0, v[0:1]
	s_add_u32 s66, s52, 0x18100
	v_lshl_add_u64 v[12:13], v[10:11], 0, s[68:69]
	s_mov_b32 m0, s58
	s_addc_u32 s67, s53, 0
	s_add_i32 s59, s61, s25
	global_load_lds_dwordx4 v[12:13], off
	v_lshl_add_u64 v[12:13], s[66:67], 0, v[4:5]
	s_mov_b32 m0, s59
	s_add_i32 s61, s59, 0x2000
	global_load_lds_dwordx4 v[12:13], off
	v_lshl_add_u64 v[12:13], s[66:67], 0, v[0:1]
	s_mov_b32 m0, s61
	s_nop 0
	global_load_lds_dwordx4 v[12:13], off
	v_lshl_add_u64 v[12:13], s[50:51], 0, v[6:7]
	v_lshl_add_u64 v[14:15], v[12:13], 0, s[68:69]
	s_mov_b32 m0, s26
	s_nop 0
	global_load_lds_dwordx4 v[14:15], off
	v_lshl_add_u64 v[14:15], s[50:51], 0, v[2:3]
	v_lshl_add_u64 v[150:151], v[14:15], 0, s[68:69]
	s_mov_b32 m0, s27
	s_nop 0
	global_load_lds_dwordx4 v[150:151], off
	s_waitcnt vmcnt(8)
	s_waitcnt lgkmcnt(0)
	s_barrier
	s_setprio 1
	s_waitcnt lgkmcnt(0)
	v_mfma_f32_16x16x32_bf16 v[150:153], v[22:25], v[74:77], 0
	v_mfma_f32_16x16x32_bf16 v[178:181], v[22:25], v[126:129], 0
	v_mfma_f32_16x16x32_bf16 v[186:189], v[22:25], v[134:137], 0
	v_mfma_f32_16x16x32_bf16 v[22:25], v[22:25], v[142:145], 0
	v_mfma_f32_16x16x32_bf16 v[150:153], v[26:29], v[122:125], v[150:153]
	v_mfma_f32_16x16x32_bf16 v[154:157], v[30:33], v[74:77], 0
	v_mfma_f32_16x16x32_bf16 v[178:181], v[26:29], v[130:133], v[178:181]
	v_mfma_f32_16x16x32_bf16 v[182:185], v[30:33], v[126:129], 0
	v_mfma_f32_16x16x32_bf16 v[186:189], v[26:29], v[138:141], v[186:189]
	v_mfma_f32_16x16x32_bf16 v[190:193], v[30:33], v[134:137], 0
	v_mfma_f32_16x16x32_bf16 v[24:27], v[26:29], v[146:149], v[22:25]
	v_mfma_f32_16x16x32_bf16 v[28:31], v[30:33], v[142:145], 0
	v_mfma_f32_16x16x32_bf16 v[154:157], v[34:37], v[122:125], v[154:157]
	v_mfma_f32_16x16x32_bf16 v[182:185], v[34:37], v[130:133], v[182:185]
	v_mfma_f32_16x16x32_bf16 v[190:193], v[34:37], v[138:141], v[190:193]
	v_mfma_f32_16x16x32_bf16 v[28:31], v[34:37], v[146:149], v[28:31]
	v_mfma_f32_16x16x32_bf16 v[32:35], v[38:41], v[74:77], 0
	v_mfma_f32_16x16x32_bf16 v[74:77], v[46:49], v[74:77], 0
	v_mfma_f32_16x16x32_bf16 v[32:35], v[42:45], v[122:125], v[32:35]
	v_mfma_f32_16x16x32_bf16 v[74:77], v[50:53], v[122:125], v[74:77]
	v_mfma_f32_16x16x32_bf16 v[122:125], v[38:41], v[126:129], 0
	v_mfma_f32_16x16x32_bf16 v[126:129], v[46:49], v[126:129], 0
	v_mfma_f32_16x16x32_bf16 v[122:125], v[42:45], v[130:133], v[122:125]
	v_mfma_f32_16x16x32_bf16 v[126:129], v[50:53], v[130:133], v[126:129]
	v_mfma_f32_16x16x32_bf16 v[130:133], v[38:41], v[134:137], 0
	v_mfma_f32_16x16x32_bf16 v[36:39], v[38:41], v[142:145], 0
	v_mfma_f32_16x16x32_bf16 v[130:133], v[42:45], v[138:141], v[130:133]
	v_mfma_f32_16x16x32_bf16 v[134:137], v[46:49], v[134:137], 0
	v_mfma_f32_16x16x32_bf16 v[36:39], v[42:45], v[146:149], v[36:39]
	v_mfma_f32_16x16x32_bf16 v[40:43], v[46:49], v[142:145], 0
	v_mfma_f32_16x16x32_bf16 v[134:137], v[50:53], v[138:141], v[134:137]
	v_mfma_f32_16x16x32_bf16 v[40:43], v[50:53], v[146:149], v[40:43]
	s_setprio 0
	s_barrier
	s_add_i32 s63, 0, 0x18000
	s_add_i32 s64, 0, 0x1c000
	v_add_u32_e32 v21, s63, v16
	v_add_u32_e32 v22, s64, v16
	ds_read_b128 v[44:47], v21
	ds_read_b128 v[48:51], v21 offset:1024
	ds_read_b128 v[138:141], v21 offset:2048
	ds_read_b128 v[142:145], v21 offset:3072
	ds_read_b128 v[146:149], v22
	ds_read_b128 v[194:197], v22 offset:1024
	ds_read_b128 v[198:201], v22 offset:2048
	ds_read_b128 v[202:205], v22 offset:3072
	s_add_u32 s66, s50, 0x18100
	s_addc_u32 s67, s51, 0
	s_mov_b32 m0, s28
	v_lshl_add_u64 v[52:53], s[66:67], 0, v[6:7]
	ds_read_b128 v[220:223], v17 offset:32768
	ds_read_b128 v[228:231], v17 offset:33792
	ds_read_b128 v[232:235], v17 offset:34816
	ds_read_b128 v[236:239], v17 offset:35840
	ds_read_b128 v[240:243], v17 offset:36864
	ds_read_b128 v[244:247], v17 offset:37888
	ds_read_b128 v[248:251], v17 offset:38912
	ds_read_b128 v[174:177], v17 offset:39936
	global_load_lds_dwordx4 v[52:53], off
	v_lshl_add_u64 v[52:53], s[66:67], 0, v[2:3]
	s_mov_b32 m0, s29
	s_nop 0
	global_load_lds_dwordx4 v[52:53], off
	s_waitcnt vmcnt(8)
	s_waitcnt lgkmcnt(0)
	s_barrier
	s_setprio 1
	s_waitcnt lgkmcnt(0)
	v_mfma_f32_16x16x32_bf16 v[78:81], v[44:47], v[220:223], v[78:81]
	v_mfma_f32_16x16x32_bf16 v[82:85], v[138:141], v[220:223], v[82:85]
	v_mfma_f32_16x16x32_bf16 v[86:89], v[44:47], v[232:235], v[86:89]
	v_mfma_f32_16x16x32_bf16 v[90:93], v[138:141], v[232:235], v[90:93]
	v_mfma_f32_16x16x32_bf16 v[94:97], v[44:47], v[240:243], v[94:97]
	v_mfma_f32_16x16x32_bf16 v[98:101], v[138:141], v[240:243], v[98:101]
	v_mfma_f32_16x16x32_bf16 v[102:105], v[44:47], v[248:251], v[102:105]
	v_mfma_f32_16x16x32_bf16 v[106:109], v[138:141], v[248:251], v[106:109]
	v_mfma_f32_16x16x32_bf16 v[78:81], v[48:51], v[228:231], v[78:81]
	v_mfma_f32_16x16x32_bf16 v[82:85], v[142:145], v[228:231], v[82:85]
	v_mfma_f32_16x16x32_bf16 v[86:89], v[48:51], v[236:239], v[86:89]
	v_mfma_f32_16x16x32_bf16 v[90:93], v[142:145], v[236:239], v[90:93]
	v_mfma_f32_16x16x32_bf16 v[94:97], v[48:51], v[244:247], v[94:97]
	v_mfma_f32_16x16x32_bf16 v[98:101], v[142:145], v[244:247], v[98:101]
	v_mfma_f32_16x16x32_bf16 v[102:105], v[48:51], v[174:177], v[102:105]
	v_mfma_f32_16x16x32_bf16 v[106:109], v[142:145], v[174:177], v[106:109]
	v_mfma_f32_16x16x32_bf16 v[110:113], v[146:149], v[220:223], v[110:113]
	v_mfma_f32_16x16x32_bf16 v[114:117], v[198:201], v[220:223], v[114:117]
	v_mfma_f32_16x16x32_bf16 v[118:121], v[146:149], v[232:235], v[118:121]
	v_mfma_f32_16x16x32_bf16 v[52:55], v[198:201], v[232:235], v[54:57]
	v_mfma_f32_16x16x32_bf16 v[56:59], v[146:149], v[240:243], v[58:61]
	v_mfma_f32_16x16x32_bf16 v[60:63], v[198:201], v[240:243], v[62:65]
	v_mfma_f32_16x16x32_bf16 v[64:67], v[146:149], v[248:251], v[66:69]
	v_mfma_f32_16x16x32_bf16 v[68:71], v[198:201], v[248:251], v[70:73]
	v_mfma_f32_16x16x32_bf16 v[110:113], v[194:197], v[228:231], v[110:113]
	v_mfma_f32_16x16x32_bf16 v[114:117], v[202:205], v[228:231], v[114:117]
	v_mfma_f32_16x16x32_bf16 v[118:121], v[194:197], v[236:239], v[118:121]
	v_mfma_f32_16x16x32_bf16 v[52:55], v[202:205], v[236:239], v[52:55]
	v_mfma_f32_16x16x32_bf16 v[56:59], v[194:197], v[244:247], v[56:59]
	v_mfma_f32_16x16x32_bf16 v[60:63], v[202:205], v[244:247], v[60:63]
	v_mfma_f32_16x16x32_bf16 v[64:67], v[194:197], v[174:177], v[64:67]
	v_mfma_f32_16x16x32_bf16 v[68:71], v[202:205], v[174:177], v[68:71]
	s_setprio 0
	s_barrier
	s_add_i32 s67, s63, s25
	s_mov_b64 s[70:71], 0x180
	s_add_i32 s63, s67, 0x2000
	v_lshl_add_u64 v[72:73], v[8:9], 0, s[70:71]
	s_mov_b32 m0, s67
	s_add_u32 s68, s52, 0x18180
	ds_read_b128 v[174:177], v17 offset:49152
	ds_read_b128 v[220:223], v17 offset:50176
	ds_read_b128 v[228:231], v17 offset:51200
	ds_read_b128 v[232:235], v17 offset:52224
	ds_read_b128 v[236:239], v17 offset:53248
	ds_read_b128 v[240:243], v17 offset:54272
	ds_read_b128 v[244:247], v17 offset:55296
	ds_read_b128 v[248:251], v17 offset:56320
	global_load_lds_dwordx4 v[72:73], off
	v_lshl_add_u64 v[72:73], v[10:11], 0, s[70:71]
	s_mov_b32 m0, s63
	s_addc_u32 s69, s53, 0
	s_add_i32 s64, s64, s25
	global_load_lds_dwordx4 v[72:73], off
	v_lshl_add_u64 v[72:73], s[68:69], 0, v[4:5]
	s_mov_b32 m0, s64
	s_add_i32 s66, s64, 0x2000
	global_load_lds_dwordx4 v[72:73], off
	v_lshl_add_u64 v[72:73], s[68:69], 0, v[0:1]
	s_mov_b32 m0, s66
	s_nop 0
	global_load_lds_dwordx4 v[72:73], off
	v_lshl_add_u64 v[72:73], v[12:13], 0, s[70:71]
	s_mov_b32 m0, s30
	s_nop 0
	global_load_lds_dwordx4 v[72:73], off
	v_lshl_add_u64 v[72:73], v[14:15], 0, s[70:71]
	s_mov_b32 m0, s31
	s_nop 0
	global_load_lds_dwordx4 v[72:73], off
	s_waitcnt vmcnt(8)
	s_waitcnt lgkmcnt(0)
	s_barrier
	s_setprio 1
	s_waitcnt lgkmcnt(0)
	v_mfma_f32_16x16x32_bf16 v[150:153], v[44:47], v[174:177], v[150:153]
	v_mfma_f32_16x16x32_bf16 v[154:157], v[138:141], v[174:177], v[154:157]
	v_mfma_f32_16x16x32_bf16 v[178:181], v[44:47], v[228:231], v[178:181]
	v_mfma_f32_16x16x32_bf16 v[182:185], v[138:141], v[228:231], v[182:185]
	v_mfma_f32_16x16x32_bf16 v[186:189], v[44:47], v[236:239], v[186:189]
	v_mfma_f32_16x16x32_bf16 v[190:193], v[138:141], v[236:239], v[190:193]
	v_mfma_f32_16x16x32_bf16 v[24:27], v[44:47], v[244:247], v[24:27]
	v_mfma_f32_16x16x32_bf16 v[28:31], v[138:141], v[244:247], v[28:31]
	v_mfma_f32_16x16x32_bf16 v[150:153], v[48:51], v[220:223], v[150:153]
	v_mfma_f32_16x16x32_bf16 v[154:157], v[142:145], v[220:223], v[154:157]
	v_mfma_f32_16x16x32_bf16 v[178:181], v[48:51], v[232:235], v[178:181]
	v_mfma_f32_16x16x32_bf16 v[182:185], v[142:145], v[232:235], v[182:185]
	v_mfma_f32_16x16x32_bf16 v[186:189], v[48:51], v[240:243], v[186:189]
	v_mfma_f32_16x16x32_bf16 v[190:193], v[142:145], v[240:243], v[190:193]
	v_mfma_f32_16x16x32_bf16 v[24:27], v[48:51], v[248:251], v[24:27]
	v_mfma_f32_16x16x32_bf16 v[28:31], v[142:145], v[248:251], v[28:31]
	v_mfma_f32_16x16x32_bf16 v[32:35], v[146:149], v[174:177], v[32:35]
	v_mfma_f32_16x16x32_bf16 v[44:47], v[198:201], v[174:177], v[74:77]
	v_mfma_f32_16x16x32_bf16 v[48:51], v[146:149], v[228:231], v[122:125]
	v_mfma_f32_16x16x32_bf16 v[72:75], v[198:201], v[228:231], v[126:129]
	v_mfma_f32_16x16x32_bf16 v[122:125], v[146:149], v[236:239], v[130:133]
	v_mfma_f32_16x16x32_bf16 v[126:129], v[198:201], v[236:239], v[134:137]
	v_mfma_f32_16x16x32_bf16 v[36:39], v[146:149], v[244:247], v[36:39]
	v_mfma_f32_16x16x32_bf16 v[40:43], v[198:201], v[244:247], v[40:43]
	v_mfma_f32_16x16x32_bf16 v[32:35], v[194:197], v[220:223], v[32:35]
	v_mfma_f32_16x16x32_bf16 v[44:47], v[202:205], v[220:223], v[44:47]
	v_mfma_f32_16x16x32_bf16 v[48:51], v[194:197], v[232:235], v[48:51]
	v_mfma_f32_16x16x32_bf16 v[72:75], v[202:205], v[232:235], v[72:75]
	v_mfma_f32_16x16x32_bf16 v[122:125], v[194:197], v[240:243], v[122:125]
	v_mfma_f32_16x16x32_bf16 v[126:129], v[202:205], v[240:243], v[126:129]
	v_mfma_f32_16x16x32_bf16 v[36:39], v[194:197], v[248:251], v[36:39]
	v_mfma_f32_16x16x32_bf16 v[40:43], v[202:205], v[248:251], v[40:43]
	s_setprio 0
	s_barrier
	ds_read_b128 v[130:133], v19
	ds_read_b128 v[134:137], v19 offset:1024
	ds_read_b128 v[138:141], v19 offset:2048
	ds_read_b128 v[142:145], v19 offset:3072
	ds_read_b128 v[146:149], v20
	ds_read_b128 v[174:177], v20 offset:1024
	ds_read_b128 v[194:197], v20 offset:2048
	ds_read_b128 v[198:201], v20 offset:3072
	s_add_u32 s68, s50, 0x18180
	s_addc_u32 s69, s51, 0
	s_mov_b32 m0, s65
	v_lshl_add_u64 v[76:77], s[68:69], 0, v[6:7]
	ds_read_b128 v[202:205], v17
	ds_read_b128 v[220:223], v17 offset:1024
	ds_read_b128 v[228:231], v17 offset:2048
	ds_read_b128 v[232:235], v17 offset:3072
	ds_read_b128 v[236:239], v17 offset:4096
	ds_read_b128 v[240:243], v17 offset:5120
	ds_read_b128 v[244:247], v17 offset:6144
	ds_read_b128 v[248:251], v17 offset:7168
	global_load_lds_dwordx4 v[76:77], off
	v_lshl_add_u64 v[76:77], s[68:69], 0, v[2:3]
	s_mov_b32 m0, s57
	s_nop 0
	global_load_lds_dwordx4 v[76:77], off
	s_waitcnt vmcnt(8)
	s_waitcnt lgkmcnt(0)
	s_barrier
	s_setprio 1
	s_waitcnt lgkmcnt(0)
	v_mfma_f32_16x16x32_bf16 v[76:79], v[130:133], v[202:205], v[78:81]
	v_mfma_f32_16x16x32_bf16 v[80:83], v[138:141], v[202:205], v[82:85]
	v_mfma_f32_16x16x32_bf16 v[84:87], v[130:133], v[228:231], v[86:89]
	v_mfma_f32_16x16x32_bf16 v[88:91], v[138:141], v[228:231], v[90:93]
	v_mfma_f32_16x16x32_bf16 v[92:95], v[130:133], v[236:239], v[94:97]
	v_mfma_f32_16x16x32_bf16 v[96:99], v[138:141], v[236:239], v[98:101]
	v_mfma_f32_16x16x32_bf16 v[100:103], v[130:133], v[244:247], v[102:105]
	v_mfma_f32_16x16x32_bf16 v[104:107], v[138:141], v[244:247], v[106:109]
	v_mfma_f32_16x16x32_bf16 v[76:79], v[134:137], v[220:223], v[76:79]
	v_mfma_f32_16x16x32_bf16 v[80:83], v[142:145], v[220:223], v[80:83]
	v_mfma_f32_16x16x32_bf16 v[84:87], v[134:137], v[232:235], v[84:87]
	v_mfma_f32_16x16x32_bf16 v[88:91], v[142:145], v[232:235], v[88:91]
	v_mfma_f32_16x16x32_bf16 v[92:95], v[134:137], v[240:243], v[92:95]
	v_mfma_f32_16x16x32_bf16 v[96:99], v[142:145], v[240:243], v[96:99]
	v_mfma_f32_16x16x32_bf16 v[100:103], v[134:137], v[248:251], v[100:103]
	v_mfma_f32_16x16x32_bf16 v[104:107], v[142:145], v[248:251], v[104:107]
	v_mfma_f32_16x16x32_bf16 v[108:111], v[146:149], v[202:205], v[110:113]
	v_mfma_f32_16x16x32_bf16 v[112:115], v[194:197], v[202:205], v[114:117]
	v_mfma_f32_16x16x32_bf16 v[116:119], v[146:149], v[228:231], v[118:121]
	v_mfma_f32_16x16x32_bf16 v[52:55], v[194:197], v[228:231], v[52:55]
	v_mfma_f32_16x16x32_bf16 v[56:59], v[146:149], v[236:239], v[56:59]
	v_mfma_f32_16x16x32_bf16 v[60:63], v[194:197], v[236:239], v[60:63]
	v_mfma_f32_16x16x32_bf16 v[64:67], v[146:149], v[244:247], v[64:67]
	v_mfma_f32_16x16x32_bf16 v[68:71], v[194:197], v[244:247], v[68:71]
	v_mfma_f32_16x16x32_bf16 v[108:111], v[174:177], v[220:223], v[108:111]
	v_mfma_f32_16x16x32_bf16 v[112:115], v[198:201], v[220:223], v[112:115]
	v_mfma_f32_16x16x32_bf16 v[116:119], v[174:177], v[232:235], v[116:119]
	v_mfma_f32_16x16x32_bf16 v[52:55], v[198:201], v[232:235], v[52:55]
	v_mfma_f32_16x16x32_bf16 v[56:59], v[174:177], v[240:243], v[56:59]
	v_mfma_f32_16x16x32_bf16 v[60:63], v[198:201], v[240:243], v[60:63]
	v_mfma_f32_16x16x32_bf16 v[64:67], v[174:177], v[248:251], v[64:67]
	v_mfma_f32_16x16x32_bf16 v[68:71], v[198:201], v[248:251], v[68:71]
	s_setprio 0
	s_barrier
	s_mov_b64 s[70:71], 0x200
	s_mov_b32 m0, s62
	v_lshl_add_u64 v[120:121], v[8:9], 0, s[70:71]
	s_add_u32 s68, s52, 0x18200
	ds_read_b128 v[202:205], v17 offset:16384
	ds_read_b128 v[220:223], v17 offset:17408
	ds_read_b128 v[228:231], v17 offset:18432
	ds_read_b128 v[232:235], v17 offset:19456
	ds_read_b128 v[236:239], v17 offset:20480
	ds_read_b128 v[240:243], v17 offset:21504
	ds_read_b128 v[244:247], v17 offset:22528
	ds_read_b128 v[248:251], v17 offset:23552
	global_load_lds_dwordx4 v[120:121], off
	v_lshl_add_u64 v[120:121], v[10:11], 0, s[70:71]
	s_mov_b32 m0, s58
	s_addc_u32 s69, s53, 0
	global_load_lds_dwordx4 v[120:121], off
	v_lshl_add_u64 v[120:121], s[68:69], 0, v[4:5]
	s_mov_b32 m0, s59
	s_nop 0
	global_load_lds_dwordx4 v[120:121], off
	v_lshl_add_u64 v[120:121], s[68:69], 0, v[0:1]
	s_mov_b32 m0, s61
	s_nop 0
	global_load_lds_dwordx4 v[120:121], off
	v_lshl_add_u64 v[120:121], v[12:13], 0, s[70:71]
	s_mov_b32 m0, s26
	s_nop 0
	global_load_lds_dwordx4 v[120:121], off
	v_lshl_add_u64 v[120:121], v[14:15], 0, s[70:71]
	s_mov_b32 m0, s27
	s_nop 0
	global_load_lds_dwordx4 v[120:121], off
	s_waitcnt vmcnt(8)
	s_waitcnt lgkmcnt(0)
	s_barrier
	s_setprio 1
	s_waitcnt lgkmcnt(0)
	v_mfma_f32_16x16x32_bf16 v[150:153], v[130:133], v[202:205], v[150:153]
	v_mfma_f32_16x16x32_bf16 v[154:157], v[138:141], v[202:205], v[154:157]
	v_mfma_f32_16x16x32_bf16 v[178:181], v[130:133], v[228:231], v[178:181]
	v_mfma_f32_16x16x32_bf16 v[182:185], v[138:141], v[228:231], v[182:185]
	v_mfma_f32_16x16x32_bf16 v[186:189], v[130:133], v[236:239], v[186:189]
	v_mfma_f32_16x16x32_bf16 v[190:193], v[138:141], v[236:239], v[190:193]
	v_mfma_f32_16x16x32_bf16 v[24:27], v[130:133], v[244:247], v[24:27]
	v_mfma_f32_16x16x32_bf16 v[28:31], v[138:141], v[244:247], v[28:31]
	v_mfma_f32_16x16x32_bf16 v[150:153], v[134:137], v[220:223], v[150:153]
	v_mfma_f32_16x16x32_bf16 v[154:157], v[142:145], v[220:223], v[154:157]
	v_mfma_f32_16x16x32_bf16 v[178:181], v[134:137], v[232:235], v[178:181]
	v_mfma_f32_16x16x32_bf16 v[182:185], v[142:145], v[232:235], v[182:185]
	v_mfma_f32_16x16x32_bf16 v[186:189], v[134:137], v[240:243], v[186:189]
	v_mfma_f32_16x16x32_bf16 v[190:193], v[142:145], v[240:243], v[190:193]
	v_mfma_f32_16x16x32_bf16 v[24:27], v[134:137], v[248:251], v[24:27]
	v_mfma_f32_16x16x32_bf16 v[28:31], v[142:145], v[248:251], v[28:31]
	v_mfma_f32_16x16x32_bf16 v[32:35], v[146:149], v[202:205], v[32:35]
	v_mfma_f32_16x16x32_bf16 v[44:47], v[194:197], v[202:205], v[44:47]
	v_mfma_f32_16x16x32_bf16 v[48:51], v[146:149], v[228:231], v[48:51]
	v_mfma_f32_16x16x32_bf16 v[72:75], v[194:197], v[228:231], v[72:75]
	v_mfma_f32_16x16x32_bf16 v[120:123], v[146:149], v[236:239], v[122:125]
	v_mfma_f32_16x16x32_bf16 v[124:127], v[194:197], v[236:239], v[126:129]
	v_mfma_f32_16x16x32_bf16 v[36:39], v[146:149], v[244:247], v[36:39]
	v_mfma_f32_16x16x32_bf16 v[40:43], v[194:197], v[244:247], v[40:43]
	v_mfma_f32_16x16x32_bf16 v[32:35], v[174:177], v[220:223], v[32:35]
	v_mfma_f32_16x16x32_bf16 v[44:47], v[198:201], v[220:223], v[44:47]
	v_mfma_f32_16x16x32_bf16 v[48:51], v[174:177], v[232:235], v[48:51]
	v_mfma_f32_16x16x32_bf16 v[72:75], v[198:201], v[232:235], v[72:75]
	v_mfma_f32_16x16x32_bf16 v[120:123], v[174:177], v[240:243], v[120:123]
	v_mfma_f32_16x16x32_bf16 v[124:127], v[198:201], v[240:243], v[124:127]
	v_mfma_f32_16x16x32_bf16 v[36:39], v[174:177], v[248:251], v[36:39]
	v_mfma_f32_16x16x32_bf16 v[40:43], v[198:201], v[248:251], v[40:43]
	s_setprio 0
	s_barrier
	ds_read_b128 v[128:131], v21
	ds_read_b128 v[132:135], v21 offset:1024
	ds_read_b128 v[136:139], v21 offset:2048
	ds_read_b128 v[140:143], v21 offset:3072
	ds_read_b128 v[144:147], v22
	ds_read_b128 v[174:177], v22 offset:1024
	ds_read_b128 v[194:197], v22 offset:2048
	ds_read_b128 v[198:201], v22 offset:3072
	s_add_u32 s68, s50, 0x18200
	s_addc_u32 s69, s51, 0
	s_mov_b32 m0, s28
	v_lshl_add_u64 v[148:149], s[68:69], 0, v[6:7]
	ds_read_b128 v[202:205], v17 offset:32768
	ds_read_b128 v[220:223], v17 offset:33792
	ds_read_b128 v[228:231], v17 offset:34816
	ds_read_b128 v[232:235], v17 offset:35840
	ds_read_b128 v[236:239], v17 offset:36864
	ds_read_b128 v[240:243], v17 offset:37888
	ds_read_b128 v[244:247], v17 offset:38912
	ds_read_b128 v[248:251], v17 offset:39936
	global_load_lds_dwordx4 v[148:149], off
	v_lshl_add_u64 v[148:149], s[68:69], 0, v[2:3]
	s_mov_b32 m0, s29
	s_nop 0
	global_load_lds_dwordx4 v[148:149], off
	s_waitcnt vmcnt(8)
	s_waitcnt lgkmcnt(0)
	s_barrier
	s_setprio 1
	s_waitcnt lgkmcnt(0)
	v_mfma_f32_16x16x32_bf16 v[76:79], v[128:131], v[202:205], v[76:79]
	v_mfma_f32_16x16x32_bf16 v[80:83], v[136:139], v[202:205], v[80:83]
	v_mfma_f32_16x16x32_bf16 v[84:87], v[128:131], v[228:231], v[84:87]
	v_mfma_f32_16x16x32_bf16 v[88:91], v[136:139], v[228:231], v[88:91]
	v_mfma_f32_16x16x32_bf16 v[92:95], v[128:131], v[236:239], v[92:95]
	v_mfma_f32_16x16x32_bf16 v[96:99], v[136:139], v[236:239], v[96:99]
	v_mfma_f32_16x16x32_bf16 v[100:103], v[128:131], v[244:247], v[100:103]
	v_mfma_f32_16x16x32_bf16 v[104:107], v[136:139], v[244:247], v[104:107]
	v_mfma_f32_16x16x32_bf16 v[76:79], v[132:135], v[220:223], v[76:79]
	v_mfma_f32_16x16x32_bf16 v[80:83], v[140:143], v[220:223], v[80:83]
	v_mfma_f32_16x16x32_bf16 v[84:87], v[132:135], v[232:235], v[84:87]
	v_mfma_f32_16x16x32_bf16 v[88:91], v[140:143], v[232:235], v[88:91]
	v_mfma_f32_16x16x32_bf16 v[92:95], v[132:135], v[240:243], v[92:95]
	v_mfma_f32_16x16x32_bf16 v[96:99], v[140:143], v[240:243], v[96:99]
	v_mfma_f32_16x16x32_bf16 v[100:103], v[132:135], v[248:251], v[100:103]
	v_mfma_f32_16x16x32_bf16 v[104:107], v[140:143], v[248:251], v[104:107]
	v_mfma_f32_16x16x32_bf16 v[108:111], v[144:147], v[202:205], v[108:111]
	v_mfma_f32_16x16x32_bf16 v[112:115], v[194:197], v[202:205], v[112:115]
	v_mfma_f32_16x16x32_bf16 v[116:119], v[144:147], v[228:231], v[116:119]
	v_mfma_f32_16x16x32_bf16 v[52:55], v[194:197], v[228:231], v[52:55]
	v_mfma_f32_16x16x32_bf16 v[56:59], v[144:147], v[236:239], v[56:59]
	v_mfma_f32_16x16x32_bf16 v[60:63], v[194:197], v[236:239], v[60:63]
	v_mfma_f32_16x16x32_bf16 v[64:67], v[144:147], v[244:247], v[64:67]
	v_mfma_f32_16x16x32_bf16 v[68:71], v[194:197], v[244:247], v[68:71]
	v_mfma_f32_16x16x32_bf16 v[108:111], v[174:177], v[220:223], v[108:111]
	v_mfma_f32_16x16x32_bf16 v[112:115], v[198:201], v[220:223], v[112:115]
	v_mfma_f32_16x16x32_bf16 v[116:119], v[174:177], v[232:235], v[116:119]
	v_mfma_f32_16x16x32_bf16 v[52:55], v[198:201], v[232:235], v[52:55]
	v_mfma_f32_16x16x32_bf16 v[56:59], v[174:177], v[240:243], v[56:59]
	v_mfma_f32_16x16x32_bf16 v[60:63], v[198:201], v[240:243], v[60:63]
	v_mfma_f32_16x16x32_bf16 v[64:67], v[174:177], v[248:251], v[64:67]
	v_mfma_f32_16x16x32_bf16 v[68:71], v[198:201], v[248:251], v[68:71]
	s_setprio 0
	s_barrier
	s_mov_b64 s[68:69], 0x280
	s_mov_b32 m0, s67
	v_lshl_add_u64 v[8:9], v[8:9], 0, s[68:69]
	s_add_u32 s52, s52, 0x18280
	ds_read_b128 v[202:205], v17 offset:49152
	ds_read_b128 v[220:223], v17 offset:50176
	ds_read_b128 v[228:231], v17 offset:51200
	ds_read_b128 v[232:235], v17 offset:52224
	ds_read_b128 v[236:239], v17 offset:53248
	ds_read_b128 v[240:243], v17 offset:54272
	ds_read_b128 v[244:247], v17 offset:55296
	ds_read_b128 v[248:251], v17 offset:56320
	global_load_lds_dwordx4 v[8:9], off
	v_lshl_add_u64 v[8:9], v[10:11], 0, s[68:69]
	s_mov_b32 m0, s63
	s_addc_u32 s53, s53, 0
	global_load_lds_dwordx4 v[8:9], off
	v_lshl_add_u64 v[8:9], s[52:53], 0, v[4:5]
	s_mov_b32 m0, s64
	s_nop 0
	global_load_lds_dwordx4 v[8:9], off
	v_lshl_add_u64 v[8:9], s[52:53], 0, v[0:1]
	s_mov_b32 m0, s66
	s_nop 0
	global_load_lds_dwordx4 v[8:9], off
	v_lshl_add_u64 v[8:9], v[12:13], 0, s[68:69]
	s_mov_b32 m0, s30
	s_nop 0
	global_load_lds_dwordx4 v[8:9], off
	v_lshl_add_u64 v[8:9], v[14:15], 0, s[68:69]
	s_mov_b32 m0, s31
	s_nop 0
	global_load_lds_dwordx4 v[8:9], off
	s_waitcnt vmcnt(8)
	s_waitcnt lgkmcnt(0)
	s_barrier
	s_setprio 1
	s_waitcnt lgkmcnt(0)
	v_mfma_f32_16x16x32_bf16 v[8:11], v[128:131], v[202:205], v[150:153]
	v_mfma_f32_16x16x32_bf16 v[12:15], v[136:139], v[202:205], v[154:157]
	v_mfma_f32_16x16x32_bf16 v[148:151], v[128:131], v[228:231], v[178:181]
	v_mfma_f32_16x16x32_bf16 v[152:155], v[136:139], v[228:231], v[182:185]
	v_mfma_f32_16x16x32_bf16 v[156:159], v[128:131], v[236:239], v[186:189]
	v_mfma_f32_16x16x32_bf16 v[178:181], v[136:139], v[236:239], v[190:193]
	v_mfma_f32_16x16x32_bf16 v[24:27], v[128:131], v[244:247], v[24:27]
	v_mfma_f32_16x16x32_bf16 v[28:31], v[136:139], v[244:247], v[28:31]
	v_mfma_f32_16x16x32_bf16 v[8:11], v[132:135], v[220:223], v[8:11]
	v_mfma_f32_16x16x32_bf16 v[12:15], v[140:143], v[220:223], v[12:15]
	v_mfma_f32_16x16x32_bf16 v[148:151], v[132:135], v[232:235], v[148:151]
	v_mfma_f32_16x16x32_bf16 v[152:155], v[140:143], v[232:235], v[152:155]
	v_mfma_f32_16x16x32_bf16 v[156:159], v[132:135], v[240:243], v[156:159]
	v_mfma_f32_16x16x32_bf16 v[178:181], v[140:143], v[240:243], v[178:181]
	v_mfma_f32_16x16x32_bf16 v[24:27], v[132:135], v[248:251], v[24:27]
	v_mfma_f32_16x16x32_bf16 v[28:31], v[140:143], v[248:251], v[28:31]
	v_mfma_f32_16x16x32_bf16 v[32:35], v[144:147], v[202:205], v[32:35]
	v_mfma_f32_16x16x32_bf16 v[44:47], v[194:197], v[202:205], v[44:47]
	v_mfma_f32_16x16x32_bf16 v[48:51], v[144:147], v[228:231], v[48:51]
	v_mfma_f32_16x16x32_bf16 v[72:75], v[194:197], v[228:231], v[72:75]
	v_mfma_f32_16x16x32_bf16 v[120:123], v[144:147], v[236:239], v[120:123]
	v_mfma_f32_16x16x32_bf16 v[124:127], v[194:197], v[236:239], v[124:127]
	v_mfma_f32_16x16x32_bf16 v[36:39], v[144:147], v[244:247], v[36:39]
	v_mfma_f32_16x16x32_bf16 v[40:43], v[194:197], v[244:247], v[40:43]
	v_mfma_f32_16x16x32_bf16 v[32:35], v[174:177], v[220:223], v[32:35]
	v_mfma_f32_16x16x32_bf16 v[44:47], v[198:201], v[220:223], v[44:47]
	v_mfma_f32_16x16x32_bf16 v[48:51], v[174:177], v[232:235], v[48:51]
	v_mfma_f32_16x16x32_bf16 v[72:75], v[198:201], v[232:235], v[72:75]
	v_mfma_f32_16x16x32_bf16 v[120:123], v[174:177], v[240:243], v[120:123]
	v_mfma_f32_16x16x32_bf16 v[124:127], v[198:201], v[240:243], v[124:127]
	v_mfma_f32_16x16x32_bf16 v[36:39], v[174:177], v[248:251], v[36:39]
	v_mfma_f32_16x16x32_bf16 v[40:43], v[198:201], v[248:251], v[40:43]
	s_setprio 0
	s_barrier
	ds_read_b128 v[128:131], v19
	ds_read_b128 v[132:135], v19 offset:1024
	ds_read_b128 v[136:139], v19 offset:2048
	ds_read_b128 v[140:143], v19 offset:3072
	ds_read_b128 v[144:147], v20
	ds_read_b128 v[174:177], v20 offset:1024
	ds_read_b128 v[182:185], v20 offset:2048
	ds_read_b128 v[186:189], v20 offset:3072
	s_add_u32 s50, s50, 0x18280
	s_addc_u32 s51, s51, 0
	s_mov_b32 m0, s65
	v_lshl_add_u64 v[240:241], s[50:51], 0, v[6:7]
	ds_read_b128 v[190:193], v17
	ds_read_b128 v[194:197], v17 offset:1024
	ds_read_b128 v[198:201], v17 offset:2048
	ds_read_b128 v[202:205], v17 offset:3072
	ds_read_b128 v[220:223], v17 offset:4096
	ds_read_b128 v[228:231], v17 offset:5120
	ds_read_b128 v[232:235], v17 offset:6144
	ds_read_b128 v[236:239], v17 offset:7168
	global_load_lds_dwordx4 v[240:241], off
	v_lshl_add_u64 v[240:241], s[50:51], 0, v[2:3]
	s_mov_b32 m0, s57
	s_nop 0
	global_load_lds_dwordx4 v[240:241], off
	s_waitcnt vmcnt(8)
	s_waitcnt lgkmcnt(0)
	s_barrier
	s_setprio 1
	s_waitcnt lgkmcnt(0)
	v_mfma_f32_16x16x32_bf16 v[76:79], v[128:131], v[190:193], v[76:79]
	v_mfma_f32_16x16x32_bf16 v[80:83], v[136:139], v[190:193], v[80:83]
	v_mfma_f32_16x16x32_bf16 v[84:87], v[128:131], v[198:201], v[84:87]
	v_mfma_f32_16x16x32_bf16 v[88:91], v[136:139], v[198:201], v[88:91]
	v_mfma_f32_16x16x32_bf16 v[92:95], v[128:131], v[220:223], v[92:95]
	v_mfma_f32_16x16x32_bf16 v[96:99], v[136:139], v[220:223], v[96:99]
	v_mfma_f32_16x16x32_bf16 v[100:103], v[128:131], v[232:235], v[100:103]
	v_mfma_f32_16x16x32_bf16 v[104:107], v[136:139], v[232:235], v[104:107]
	v_mfma_f32_16x16x32_bf16 v[76:79], v[132:135], v[194:197], v[76:79]
	v_mfma_f32_16x16x32_bf16 v[80:83], v[140:143], v[194:197], v[80:83]
	v_mfma_f32_16x16x32_bf16 v[84:87], v[132:135], v[202:205], v[84:87]
	v_mfma_f32_16x16x32_bf16 v[88:91], v[140:143], v[202:205], v[88:91]
	v_mfma_f32_16x16x32_bf16 v[92:95], v[132:135], v[228:231], v[92:95]
	v_mfma_f32_16x16x32_bf16 v[96:99], v[140:143], v[228:231], v[96:99]
	v_mfma_f32_16x16x32_bf16 v[100:103], v[132:135], v[236:239], v[100:103]
	v_mfma_f32_16x16x32_bf16 v[104:107], v[140:143], v[236:239], v[104:107]
	v_mfma_f32_16x16x32_bf16 v[108:111], v[144:147], v[190:193], v[108:111]
	v_mfma_f32_16x16x32_bf16 v[112:115], v[182:185], v[190:193], v[112:115]
	v_mfma_f32_16x16x32_bf16 v[116:119], v[144:147], v[198:201], v[116:119]
	v_mfma_f32_16x16x32_bf16 v[52:55], v[182:185], v[198:201], v[52:55]
	v_mfma_f32_16x16x32_bf16 v[56:59], v[144:147], v[220:223], v[56:59]
	v_mfma_f32_16x16x32_bf16 v[60:63], v[182:185], v[220:223], v[60:63]
	v_mfma_f32_16x16x32_bf16 v[64:67], v[144:147], v[232:235], v[64:67]
	v_mfma_f32_16x16x32_bf16 v[68:71], v[182:185], v[232:235], v[68:71]
	v_mfma_f32_16x16x32_bf16 v[108:111], v[174:177], v[194:197], v[108:111]
	v_mfma_f32_16x16x32_bf16 v[112:115], v[186:189], v[194:197], v[112:115]
	v_mfma_f32_16x16x32_bf16 v[116:119], v[174:177], v[202:205], v[116:119]
	v_mfma_f32_16x16x32_bf16 v[52:55], v[186:189], v[202:205], v[52:55]
	v_mfma_f32_16x16x32_bf16 v[56:59], v[174:177], v[228:231], v[56:59]
	v_mfma_f32_16x16x32_bf16 v[60:63], v[186:189], v[228:231], v[60:63]
	v_mfma_f32_16x16x32_bf16 v[64:67], v[174:177], v[236:239], v[64:67]
	v_mfma_f32_16x16x32_bf16 v[68:71], v[186:189], v[236:239], v[68:71]
	s_setprio 0
	s_barrier
	s_mov_b32 m0, s62
	v_lshl_add_u64 v[240:241], s[44:45], 0, v[4:5]
	s_add_u32 s50, s44, 0x18000
	ds_read_b128 v[190:193], v17 offset:16384
	ds_read_b128 v[194:197], v17 offset:17408
	ds_read_b128 v[198:201], v17 offset:18432
	ds_read_b128 v[202:205], v17 offset:19456
	ds_read_b128 v[220:223], v17 offset:20480
	ds_read_b128 v[228:231], v17 offset:21504
	ds_read_b128 v[232:235], v17 offset:22528
	ds_read_b128 v[236:239], v17 offset:23552
	global_load_lds_dwordx4 v[240:241], off
	v_lshl_add_u64 v[242:243], s[44:45], 0, v[0:1]
	s_mov_b32 m0, s58
	s_addc_u32 s51, s45, 0
	global_load_lds_dwordx4 v[242:243], off
	v_lshl_add_u64 v[244:245], s[50:51], 0, v[4:5]
	s_mov_b32 m0, s59
	v_lshl_add_u64 v[246:247], s[42:43], 0, v[2:3]
	global_load_lds_dwordx4 v[244:245], off
	v_lshl_add_u64 v[244:245], s[50:51], 0, v[0:1]
	s_mov_b32 m0, s61
	s_nop 0
	global_load_lds_dwordx4 v[244:245], off
	v_lshl_add_u64 v[244:245], s[42:43], 0, v[6:7]
	s_mov_b32 m0, s26
	s_nop 0
	global_load_lds_dwordx4 v[244:245], off
	s_mov_b32 m0, s27
	s_nop 0
	global_load_lds_dwordx4 v[246:247], off
	s_waitcnt vmcnt(8)
	s_waitcnt lgkmcnt(0)
	s_barrier
	s_setprio 1
	s_waitcnt lgkmcnt(0)
	v_mfma_f32_16x16x32_bf16 v[8:11], v[128:131], v[190:193], v[8:11]
	v_mfma_f32_16x16x32_bf16 v[12:15], v[136:139], v[190:193], v[12:15]
	v_mfma_f32_16x16x32_bf16 v[148:151], v[128:131], v[198:201], v[148:151]
	v_mfma_f32_16x16x32_bf16 v[152:155], v[136:139], v[198:201], v[152:155]
	v_mfma_f32_16x16x32_bf16 v[156:159], v[128:131], v[220:223], v[156:159]
	v_mfma_f32_16x16x32_bf16 v[178:181], v[136:139], v[220:223], v[178:181]
	v_mfma_f32_16x16x32_bf16 v[24:27], v[128:131], v[232:235], v[24:27]
	v_mfma_f32_16x16x32_bf16 v[28:31], v[136:139], v[232:235], v[28:31]
	v_mfma_f32_16x16x32_bf16 v[8:11], v[132:135], v[194:197], v[8:11]
	v_mfma_f32_16x16x32_bf16 v[12:15], v[140:143], v[194:197], v[12:15]
	v_mfma_f32_16x16x32_bf16 v[148:151], v[132:135], v[202:205], v[148:151]
	v_mfma_f32_16x16x32_bf16 v[152:155], v[140:143], v[202:205], v[152:155]
	v_mfma_f32_16x16x32_bf16 v[156:159], v[132:135], v[228:231], v[156:159]
	v_mfma_f32_16x16x32_bf16 v[178:181], v[140:143], v[228:231], v[178:181]
	v_mfma_f32_16x16x32_bf16 v[24:27], v[132:135], v[236:239], v[24:27]
	v_mfma_f32_16x16x32_bf16 v[28:31], v[140:143], v[236:239], v[28:31]
	v_mfma_f32_16x16x32_bf16 v[32:35], v[144:147], v[190:193], v[32:35]
	v_mfma_f32_16x16x32_bf16 v[44:47], v[182:185], v[190:193], v[44:47]
	v_mfma_f32_16x16x32_bf16 v[48:51], v[144:147], v[198:201], v[48:51]
	v_mfma_f32_16x16x32_bf16 v[72:75], v[182:185], v[198:201], v[72:75]
	v_mfma_f32_16x16x32_bf16 v[120:123], v[144:147], v[220:223], v[120:123]
	v_mfma_f32_16x16x32_bf16 v[124:127], v[182:185], v[220:223], v[124:127]
	v_mfma_f32_16x16x32_bf16 v[36:39], v[144:147], v[232:235], v[36:39]
	v_mfma_f32_16x16x32_bf16 v[40:43], v[182:185], v[232:235], v[40:43]
	v_mfma_f32_16x16x32_bf16 v[32:35], v[174:177], v[194:197], v[32:35]
	v_mfma_f32_16x16x32_bf16 v[44:47], v[186:189], v[194:197], v[44:47]
	v_mfma_f32_16x16x32_bf16 v[48:51], v[174:177], v[202:205], v[48:51]
	v_mfma_f32_16x16x32_bf16 v[72:75], v[186:189], v[202:205], v[72:75]
	v_mfma_f32_16x16x32_bf16 v[120:123], v[174:177], v[228:231], v[120:123]
	v_mfma_f32_16x16x32_bf16 v[124:127], v[186:189], v[228:231], v[124:127]
	v_mfma_f32_16x16x32_bf16 v[36:39], v[174:177], v[236:239], v[36:39]
	v_mfma_f32_16x16x32_bf16 v[40:43], v[186:189], v[236:239], v[40:43]
	s_setprio 0
	s_barrier
	ds_read_b128 v[128:131], v21
	ds_read_b128 v[132:135], v21 offset:1024
	ds_read_b128 v[136:139], v21 offset:2048
	ds_read_b128 v[140:143], v21 offset:3072
	ds_read_b128 v[144:147], v22
	ds_read_b128 v[174:177], v22 offset:1024
	ds_read_b128 v[182:185], v22 offset:2048
	ds_read_b128 v[20:23], v22 offset:3072
	s_add_u32 s50, s42, 0x18000
	s_addc_u32 s51, s43, 0
	s_mov_b32 m0, s28
	v_lshl_add_u64 v[236:237], s[50:51], 0, v[6:7]
	ds_read_b128 v[186:189], v17 offset:32768
	ds_read_b128 v[190:193], v17 offset:33792
	ds_read_b128 v[194:197], v17 offset:34816
	ds_read_b128 v[198:201], v17 offset:35840
	ds_read_b128 v[202:205], v17 offset:36864
	ds_read_b128 v[220:223], v17 offset:37888
	ds_read_b128 v[228:231], v17 offset:38912
	ds_read_b128 v[232:235], v17 offset:39936
	global_load_lds_dwordx4 v[236:237], off
	v_lshl_add_u64 v[236:237], s[50:51], 0, v[2:3]
	s_mov_b32 m0, s29
	s_nop 0
	global_load_lds_dwordx4 v[236:237], off
	s_waitcnt vmcnt(8)
	s_waitcnt lgkmcnt(0)
	s_barrier
	s_setprio 1
	s_waitcnt lgkmcnt(0)
	v_mfma_f32_16x16x32_bf16 v[76:79], v[128:131], v[186:189], v[76:79]
	v_mfma_f32_16x16x32_bf16 v[80:83], v[136:139], v[186:189], v[80:83]
	v_mfma_f32_16x16x32_bf16 v[84:87], v[128:131], v[194:197], v[84:87]
	v_mfma_f32_16x16x32_bf16 v[88:91], v[136:139], v[194:197], v[88:91]
	v_mfma_f32_16x16x32_bf16 v[92:95], v[128:131], v[202:205], v[92:95]
	v_mfma_f32_16x16x32_bf16 v[96:99], v[136:139], v[202:205], v[96:99]
	v_mfma_f32_16x16x32_bf16 v[100:103], v[128:131], v[228:231], v[100:103]
	v_mfma_f32_16x16x32_bf16 v[104:107], v[136:139], v[228:231], v[104:107]
	v_mfma_f32_16x16x32_bf16 v[76:79], v[132:135], v[190:193], v[76:79]
	v_mfma_f32_16x16x32_bf16 v[80:83], v[140:143], v[190:193], v[80:83]
	v_mfma_f32_16x16x32_bf16 v[84:87], v[132:135], v[198:201], v[84:87]
	v_mfma_f32_16x16x32_bf16 v[88:91], v[140:143], v[198:201], v[88:91]
	v_mfma_f32_16x16x32_bf16 v[92:95], v[132:135], v[220:223], v[92:95]
	v_mfma_f32_16x16x32_bf16 v[96:99], v[140:143], v[220:223], v[96:99]
	v_mfma_f32_16x16x32_bf16 v[100:103], v[132:135], v[232:235], v[100:103]
	v_mfma_f32_16x16x32_bf16 v[104:107], v[140:143], v[232:235], v[104:107]
	v_mfma_f32_16x16x32_bf16 v[108:111], v[144:147], v[186:189], v[108:111]
	v_mfma_f32_16x16x32_bf16 v[112:115], v[182:185], v[186:189], v[112:115]
	v_mfma_f32_16x16x32_bf16 v[116:119], v[144:147], v[194:197], v[116:119]
	v_mfma_f32_16x16x32_bf16 v[52:55], v[182:185], v[194:197], v[52:55]
	v_mfma_f32_16x16x32_bf16 v[56:59], v[144:147], v[202:205], v[56:59]
	v_mfma_f32_16x16x32_bf16 v[60:63], v[182:185], v[202:205], v[60:63]
	v_mfma_f32_16x16x32_bf16 v[64:67], v[144:147], v[228:231], v[64:67]
	v_mfma_f32_16x16x32_bf16 v[68:71], v[182:185], v[228:231], v[68:71]
	v_mfma_f32_16x16x32_bf16 v[108:111], v[174:177], v[190:193], v[108:111]
	v_mfma_f32_16x16x32_bf16 v[112:115], v[20:23], v[190:193], v[112:115]
	v_mfma_f32_16x16x32_bf16 v[116:119], v[174:177], v[198:201], v[116:119]
	v_mfma_f32_16x16x32_bf16 v[52:55], v[20:23], v[198:201], v[52:55]
	v_mfma_f32_16x16x32_bf16 v[56:59], v[174:177], v[220:223], v[56:59]
	v_mfma_f32_16x16x32_bf16 v[60:63], v[20:23], v[220:223], v[60:63]
	v_mfma_f32_16x16x32_bf16 v[64:67], v[174:177], v[232:235], v[64:67]
	v_mfma_f32_16x16x32_bf16 v[68:71], v[20:23], v[232:235], v[68:71]
	s_setprio 0
	s_barrier
	s_mov_b32 m0, s67
	v_lshl_add_u64 v[236:237], v[240:241], 0, s[4:5]
	s_add_u32 s50, s44, 0x18080
	ds_read_b128 v[186:189], v17 offset:49152
	ds_read_b128 v[190:193], v17 offset:50176
	ds_read_b128 v[194:197], v17 offset:51200
	ds_read_b128 v[198:201], v17 offset:52224
	ds_read_b128 v[202:205], v17 offset:53248
	ds_read_b128 v[220:223], v17 offset:54272
	ds_read_b128 v[228:231], v17 offset:55296
	ds_read_b128 v[232:235], v17 offset:56320
	global_load_lds_dwordx4 v[236:237], off
	v_lshl_add_u64 v[236:237], v[242:243], 0, s[4:5]
	s_mov_b32 m0, s63
	s_addc_u32 s51, s45, 0
	global_load_lds_dwordx4 v[236:237], off
	v_lshl_add_u64 v[236:237], s[50:51], 0, v[4:5]
	s_mov_b32 m0, s64
	s_nop 0
	global_load_lds_dwordx4 v[236:237], off
	v_lshl_add_u64 v[236:237], s[50:51], 0, v[0:1]
	s_mov_b32 m0, s66
	s_nop 0
	global_load_lds_dwordx4 v[236:237], off
	v_lshl_add_u64 v[236:237], v[244:245], 0, s[4:5]
	s_mov_b32 m0, s30
	s_nop 0
	global_load_lds_dwordx4 v[236:237], off
	v_lshl_add_u64 v[236:237], v[246:247], 0, s[4:5]
	s_mov_b32 m0, s31
	s_nop 0
	global_load_lds_dwordx4 v[236:237], off
	s_waitcnt vmcnt(8)
	s_waitcnt lgkmcnt(0)
	s_barrier
	s_setprio 1
	s_waitcnt lgkmcnt(0)
	v_mfma_f32_16x16x32_bf16 v[8:11], v[128:131], v[186:189], v[8:11]
	v_mfma_f32_16x16x32_bf16 v[12:15], v[136:139], v[186:189], v[12:15]
	v_mfma_f32_16x16x32_bf16 v[148:151], v[128:131], v[194:197], v[148:151]
	v_mfma_f32_16x16x32_bf16 v[152:155], v[136:139], v[194:197], v[152:155]
	v_mfma_f32_16x16x32_bf16 v[156:159], v[128:131], v[202:205], v[156:159]
	v_mfma_f32_16x16x32_bf16 v[178:181], v[136:139], v[202:205], v[178:181]
	v_mfma_f32_16x16x32_bf16 v[24:27], v[128:131], v[228:231], v[24:27]
	v_mfma_f32_16x16x32_bf16 v[28:31], v[136:139], v[228:231], v[28:31]
	v_mfma_f32_16x16x32_bf16 v[8:11], v[132:135], v[190:193], v[8:11]
	v_mfma_f32_16x16x32_bf16 v[12:15], v[140:143], v[190:193], v[12:15]
	v_mfma_f32_16x16x32_bf16 v[148:151], v[132:135], v[198:201], v[148:151]
	v_mfma_f32_16x16x32_bf16 v[152:155], v[140:143], v[198:201], v[152:155]
	v_mfma_f32_16x16x32_bf16 v[156:159], v[132:135], v[220:223], v[156:159]
	v_mfma_f32_16x16x32_bf16 v[178:181], v[140:143], v[220:223], v[178:181]
	v_mfma_f32_16x16x32_bf16 v[24:27], v[132:135], v[232:235], v[24:27]
	v_mfma_f32_16x16x32_bf16 v[28:31], v[140:143], v[232:235], v[28:31]
	v_mfma_f32_16x16x32_bf16 v[32:35], v[144:147], v[186:189], v[32:35]
	v_mfma_f32_16x16x32_bf16 v[44:47], v[182:185], v[186:189], v[44:47]
	v_mfma_f32_16x16x32_bf16 v[48:51], v[144:147], v[194:197], v[48:51]
	v_mfma_f32_16x16x32_bf16 v[72:75], v[182:185], v[194:197], v[72:75]
	v_mfma_f32_16x16x32_bf16 v[120:123], v[144:147], v[202:205], v[120:123]
	v_mfma_f32_16x16x32_bf16 v[124:127], v[182:185], v[202:205], v[124:127]
	v_mfma_f32_16x16x32_bf16 v[36:39], v[144:147], v[228:231], v[36:39]
	v_mfma_f32_16x16x32_bf16 v[40:43], v[182:185], v[228:231], v[40:43]
	v_mfma_f32_16x16x32_bf16 v[32:35], v[174:177], v[190:193], v[32:35]
	v_mfma_f32_16x16x32_bf16 v[44:47], v[20:23], v[190:193], v[44:47]
	v_mfma_f32_16x16x32_bf16 v[48:51], v[174:177], v[198:201], v[48:51]
	v_mfma_f32_16x16x32_bf16 v[72:75], v[20:23], v[198:201], v[72:75]
	v_mfma_f32_16x16x32_bf16 v[120:123], v[174:177], v[220:223], v[120:123]
	v_mfma_f32_16x16x32_bf16 v[124:127], v[20:23], v[220:223], v[124:127]
	v_mfma_f32_16x16x32_bf16 v[36:39], v[174:177], v[232:235], v[36:39]
	v_mfma_f32_16x16x32_bf16 v[20:23], v[20:23], v[232:235], v[40:43]
	s_setprio 0
	s_barrier
	s_lshl_b32 s50, s55, 8
	s_lshl_b32 s51, s56, 19
	s_add_i32 s50, s50, s51
	v_add_u32_e32 v162, s50, v18
	v_lshl_add_u64 v[128:129], v[162:163], 1, s[46:47]
	v_cvt_pk_bf16_f32 v40, v76, v77
	v_cvt_pk_bf16_f32 v41, v78, v79
	v_cvt_pk_bf16_f32 v42, v80, v81
	v_cvt_pk_bf16_f32 v43, v82, v83
	global_store_dwordx4 v[128:129], v[40:43], off
	v_cvt_pk_bf16_f32 v8, v8, v9
	v_cvt_pk_bf16_f32 v9, v10, v11
	v_cvt_pk_bf16_f32 v40, v108, v109
	v_cvt_pk_bf16_f32 v41, v110, v111
	v_cvt_pk_bf16_f32 v42, v112, v113
	v_cvt_pk_bf16_f32 v43, v114, v115
	global_store_dwordx4 v[128:129], v[40:43], off offset:256
	v_cvt_pk_bf16_f32 v10, v12, v13
	v_cvt_pk_bf16_f32 v11, v14, v15
	v_add_u32_e32 v40, 0x8000, v162
	v_mov_b32_e32 v41, v163
	v_lshl_add_u64 v[76:77], v[40:41], 1, s[46:47]
	v_cvt_pk_bf16_f32 v40, v84, v85
	v_cvt_pk_bf16_f32 v41, v86, v87
	v_cvt_pk_bf16_f32 v42, v88, v89
	v_cvt_pk_bf16_f32 v43, v90, v91
	global_store_dwordx4 v[76:77], v[40:43], off
	s_add_i32 s54, s54, s82
	s_andn2_b64 vcc, exec, s[40:41]
	v_cvt_pk_bf16_f32 v40, v116, v117
	v_cvt_pk_bf16_f32 v41, v118, v119
	v_cvt_pk_bf16_f32 v42, v52, v53
	v_cvt_pk_bf16_f32 v43, v54, v55
	global_store_dwordx4 v[76:77], v[40:43], off offset:256
	s_mov_b32 s55, s6
	s_mov_b32 s56, s7
	v_add_u32_e32 v40, 0x10000, v162
	v_mov_b32_e32 v41, v163
	v_lshl_add_u64 v[52:53], v[40:41], 1, s[46:47]
	v_cvt_pk_bf16_f32 v40, v92, v93
	v_cvt_pk_bf16_f32 v41, v94, v95
	v_cvt_pk_bf16_f32 v42, v96, v97
	v_cvt_pk_bf16_f32 v43, v98, v99
	global_store_dwordx4 v[52:53], v[40:43], off
	s_mov_b64 s[52:53], s[44:45]
	s_mov_b64 s[50:51], s[42:43]
	v_cvt_pk_bf16_f32 v40, v56, v57
	v_cvt_pk_bf16_f32 v41, v58, v59
	v_cvt_pk_bf16_f32 v42, v60, v61
	v_cvt_pk_bf16_f32 v43, v62, v63
	global_store_dwordx4 v[52:53], v[40:43], off offset:256
	s_nop 1
	v_add_u32_e32 v40, 0x18000, v162
	v_mov_b32_e32 v41, v163
	v_lshl_add_u64 v[52:53], v[40:41], 1, s[46:47]
	v_cvt_pk_bf16_f32 v40, v100, v101
	v_cvt_pk_bf16_f32 v41, v102, v103
	v_cvt_pk_bf16_f32 v42, v104, v105
	v_cvt_pk_bf16_f32 v43, v106, v107
	global_store_dwordx4 v[52:53], v[40:43], off
	s_nop 1
	v_cvt_pk_bf16_f32 v40, v64, v65
	v_cvt_pk_bf16_f32 v41, v66, v67
	v_cvt_pk_bf16_f32 v42, v68, v69
	v_cvt_pk_bf16_f32 v43, v70, v71
	global_store_dwordx4 v[52:53], v[40:43], off offset:256
	s_nop 1
	v_add_u32_e32 v40, 0x40000, v162
	v_mov_b32_e32 v41, v163
	v_lshl_add_u64 v[40:41], v[40:41], 1, s[46:47]
	global_store_dwordx4 v[40:41], v[8:11], off
	s_nop 1
	v_cvt_pk_bf16_f32 v8, v32, v33
	v_cvt_pk_bf16_f32 v9, v34, v35
	v_cvt_pk_bf16_f32 v10, v44, v45
	v_cvt_pk_bf16_f32 v11, v46, v47
	global_store_dwordx4 v[40:41], v[8:11], off offset:256
	s_nop 1
	v_add_u32_e32 v8, 0x48000, v162
	v_mov_b32_e32 v9, v163
	v_lshl_add_u64 v[12:13], v[8:9], 1, s[46:47]
	v_cvt_pk_bf16_f32 v8, v148, v149
	v_cvt_pk_bf16_f32 v9, v150, v151
	v_cvt_pk_bf16_f32 v10, v152, v153
	v_cvt_pk_bf16_f32 v11, v154, v155
	global_store_dwordx4 v[12:13], v[8:11], off
	s_nop 1
	v_cvt_pk_bf16_f32 v8, v48, v49
	v_cvt_pk_bf16_f32 v9, v50, v51
	v_cvt_pk_bf16_f32 v10, v72, v73
	v_cvt_pk_bf16_f32 v11, v74, v75
	global_store_dwordx4 v[12:13], v[8:11], off offset:256
	s_nop 1
	v_add_u32_e32 v8, 0x50000, v162
	v_mov_b32_e32 v9, v163
	v_lshl_add_u64 v[12:13], v[8:9], 1, s[46:47]
	v_cvt_pk_bf16_f32 v8, v156, v157
	v_cvt_pk_bf16_f32 v9, v158, v159
	v_cvt_pk_bf16_f32 v10, v178, v179
	v_cvt_pk_bf16_f32 v11, v180, v181
	global_store_dwordx4 v[12:13], v[8:11], off
	v_add_u32_e32 v162, 0x58000, v162
	s_nop 0
	v_cvt_pk_bf16_f32 v8, v120, v121
	v_cvt_pk_bf16_f32 v9, v122, v123
	v_cvt_pk_bf16_f32 v10, v124, v125
	v_cvt_pk_bf16_f32 v11, v126, v127
	global_store_dwordx4 v[12:13], v[8:11], off offset:256
	v_lshl_add_u64 v[12:13], v[162:163], 1, s[46:47]
	s_nop 0
	v_cvt_pk_bf16_f32 v8, v24, v25
	v_cvt_pk_bf16_f32 v9, v26, v27
	v_cvt_pk_bf16_f32 v10, v28, v29
	v_cvt_pk_bf16_f32 v11, v30, v31
	global_store_dwordx4 v[12:13], v[8:11], off
	s_nop 1
	v_cvt_pk_bf16_f32 v8, v36, v37
	v_cvt_pk_bf16_f32 v9, v38, v39
	v_cvt_pk_bf16_f32 v10, v20, v21
	v_cvt_pk_bf16_f32 v11, v22, v23
	global_store_dwordx4 v[12:13], v[8:11], off offset:256
	s_cbranch_vccz .LBB0_513

.LBB0_771:
	s_add_u32 s55, s60, 0xfffc0080
	s_addc_u32 s62, s61, -1
	s_add_i32 s72, 0, 0x10000
	s_cmp_eq_u32 s53, 12
	s_cselect_b32 s65, s6, s62
	s_cselect_b32 s64, s7, s55
	s_cselect_b32 s63, s28, s31
	s_cselect_b32 s62, s29, s30
	s_add_i32 s55, 0, 0x14000
	v_add_u32_e32 v156, s72, v145
	v_add_u32_e32 v162, s55, v145
	ds_read_b128 v[140:143], v156
	ds_read_b128 v[148:151], v156 offset:1024
	ds_read_b128 v[152:155], v156 offset:2048
	ds_read_b128 v[156:159], v156 offset:3072
	ds_read_b128 v[174:177], v162
	ds_read_b128 v[178:181], v162 offset:1024
	ds_read_b128 v[182:185], v162 offset:2048
	ds_read_b128 v[186:189], v162 offset:3072
	v_lshl_add_u64 v[240:241], s[60:61], 0, v[136:137]
	s_add_i32 m0, s25, 0xc000
	ds_read_b128 v[190:193], v147
	ds_read_b128 v[194:197], v147 offset:1024
	ds_read_b128 v[198:201], v147 offset:2048
	ds_read_b128 v[202:205], v147 offset:3072
	ds_read_b128 v[220:223], v147 offset:4096
	ds_read_b128 v[228:231], v147 offset:5120
	ds_read_b128 v[232:235], v147 offset:6144
	ds_read_b128 v[236:239], v147 offset:7168
	global_load_lds_dwordx4 v[240:241], off
	v_lshl_add_u64 v[240:241], s[60:61], 0, v[138:139]
	s_add_i32 m0, s25, 0xe000
	s_nop 0
	global_load_lds_dwordx4 v[240:241], off
	s_waitcnt vmcnt(8)
	s_waitcnt lgkmcnt(0)
	s_barrier
	s_setprio 1
	s_waitcnt lgkmcnt(0)
	v_mfma_f32_16x16x32_bf16 v[124:127], v[140:143], v[190:193], v[124:127]
	v_mfma_f32_16x16x32_bf16 v[120:123], v[152:155], v[190:193], v[120:123]
	v_mfma_f32_16x16x32_bf16 v[108:111], v[140:143], v[198:201], v[108:111]
	v_mfma_f32_16x16x32_bf16 v[104:107], v[152:155], v[198:201], v[104:107]
	v_mfma_f32_16x16x32_bf16 v[92:95], v[140:143], v[220:223], v[92:95]
	v_mfma_f32_16x16x32_bf16 v[88:91], v[152:155], v[220:223], v[88:91]
	v_mfma_f32_16x16x32_bf16 v[76:79], v[140:143], v[232:235], v[76:79]
	v_mfma_f32_16x16x32_bf16 v[72:75], v[152:155], v[232:235], v[72:75]
	v_mfma_f32_16x16x32_bf16 v[124:127], v[148:151], v[194:197], v[124:127]
	v_mfma_f32_16x16x32_bf16 v[120:123], v[156:159], v[194:197], v[120:123]
	v_mfma_f32_16x16x32_bf16 v[108:111], v[148:151], v[202:205], v[108:111]
	v_mfma_f32_16x16x32_bf16 v[104:107], v[156:159], v[202:205], v[104:107]
	v_mfma_f32_16x16x32_bf16 v[92:95], v[148:151], v[228:231], v[92:95]
	v_mfma_f32_16x16x32_bf16 v[88:91], v[156:159], v[228:231], v[88:91]
	v_mfma_f32_16x16x32_bf16 v[76:79], v[148:151], v[236:239], v[76:79]
	v_mfma_f32_16x16x32_bf16 v[72:75], v[156:159], v[236:239], v[72:75]
	v_mfma_f32_16x16x32_bf16 v[116:119], v[174:177], v[190:193], v[116:119]
	v_mfma_f32_16x16x32_bf16 v[112:115], v[182:185], v[190:193], v[112:115]
	v_mfma_f32_16x16x32_bf16 v[100:103], v[174:177], v[198:201], v[100:103]
	v_mfma_f32_16x16x32_bf16 v[96:99], v[182:185], v[198:201], v[96:99]
	v_mfma_f32_16x16x32_bf16 v[84:87], v[174:177], v[220:223], v[84:87]
	v_mfma_f32_16x16x32_bf16 v[80:83], v[182:185], v[220:223], v[80:83]
	v_mfma_f32_16x16x32_bf16 v[68:71], v[174:177], v[232:235], v[68:71]
	v_mfma_f32_16x16x32_bf16 v[64:67], v[182:185], v[232:235], v[64:67]
	v_mfma_f32_16x16x32_bf16 v[116:119], v[178:181], v[194:197], v[116:119]
	v_mfma_f32_16x16x32_bf16 v[112:115], v[186:189], v[194:197], v[112:115]
	v_mfma_f32_16x16x32_bf16 v[100:103], v[178:181], v[202:205], v[100:103]
	v_mfma_f32_16x16x32_bf16 v[96:99], v[186:189], v[202:205], v[96:99]
	v_mfma_f32_16x16x32_bf16 v[84:87], v[178:181], v[228:231], v[84:87]
	v_mfma_f32_16x16x32_bf16 v[80:83], v[186:189], v[228:231], v[80:83]
	v_mfma_f32_16x16x32_bf16 v[68:71], v[178:181], v[236:239], v[68:71]
	v_mfma_f32_16x16x32_bf16 v[64:67], v[186:189], v[236:239], v[64:67]
	s_setprio 0
	s_barrier
	s_add_i32 s72, s72, s24
	v_lshl_add_u64 v[240:241], s[62:63], 0, v[132:133]
	s_mov_b32 m0, s72
	ds_read_b128 v[190:193], v147 offset:16384
	ds_read_b128 v[194:197], v147 offset:17408
	ds_read_b128 v[198:201], v147 offset:18432
	ds_read_b128 v[202:205], v147 offset:19456
	ds_read_b128 v[220:223], v147 offset:20480
	ds_read_b128 v[228:231], v147 offset:21504
	ds_read_b128 v[232:235], v147 offset:22528
	ds_read_b128 v[236:239], v147 offset:23552
	global_load_lds_dwordx4 v[240:241], off
	s_add_i32 m0, s72, 0x2000
	s_add_u32 s72, s62, 0x40000
	v_lshl_add_u64 v[242:243], s[62:63], 0, v[128:129]
	s_addc_u32 s73, s63, 0
	s_add_i32 s55, s55, s24
	global_load_lds_dwordx4 v[242:243], off
	v_lshl_add_u64 v[244:245], s[72:73], 0, v[132:133]
	s_mov_b32 m0, s55
	v_lshl_add_u64 v[246:247], s[64:65], 0, v[130:131]
	global_load_lds_dwordx4 v[244:245], off
	v_lshl_add_u64 v[244:245], s[72:73], 0, v[128:129]
	s_add_i32 m0, s55, 0x2000
	s_nop 0
	global_load_lds_dwordx4 v[244:245], off
	v_lshl_add_u64 v[244:245], s[64:65], 0, v[134:135]
	s_mov_b32 m0, s25
	s_nop 0
	global_load_lds_dwordx4 v[244:245], off
	s_mov_b32 m0, s66
	s_nop 0
	global_load_lds_dwordx4 v[246:247], off
	s_waitcnt vmcnt(8)
	s_waitcnt lgkmcnt(0)
	s_barrier
	s_setprio 1
	s_waitcnt lgkmcnt(0)
	v_mfma_f32_16x16x32_bf16 v[60:63], v[140:143], v[190:193], v[60:63]
	v_mfma_f32_16x16x32_bf16 v[56:59], v[152:155], v[190:193], v[56:59]
	v_mfma_f32_16x16x32_bf16 v[44:47], v[140:143], v[198:201], v[44:47]
	v_mfma_f32_16x16x32_bf16 v[40:43], v[152:155], v[198:201], v[40:43]
	v_mfma_f32_16x16x32_bf16 v[28:31], v[140:143], v[220:223], v[28:31]
	v_mfma_f32_16x16x32_bf16 v[24:27], v[152:155], v[220:223], v[24:27]
	v_mfma_f32_16x16x32_bf16 v[12:15], v[140:143], v[232:235], v[12:15]
	v_mfma_f32_16x16x32_bf16 v[8:11], v[152:155], v[232:235], v[8:11]
	v_mfma_f32_16x16x32_bf16 v[60:63], v[148:151], v[194:197], v[60:63]
	v_mfma_f32_16x16x32_bf16 v[56:59], v[156:159], v[194:197], v[56:59]
	v_mfma_f32_16x16x32_bf16 v[44:47], v[148:151], v[202:205], v[44:47]
	v_mfma_f32_16x16x32_bf16 v[40:43], v[156:159], v[202:205], v[40:43]
	v_mfma_f32_16x16x32_bf16 v[28:31], v[148:151], v[228:231], v[28:31]
	v_mfma_f32_16x16x32_bf16 v[24:27], v[156:159], v[228:231], v[24:27]
	v_mfma_f32_16x16x32_bf16 v[12:15], v[148:151], v[236:239], v[12:15]
	v_mfma_f32_16x16x32_bf16 v[8:11], v[156:159], v[236:239], v[8:11]
	v_mfma_f32_16x16x32_bf16 v[52:55], v[174:177], v[190:193], v[52:55]
	v_mfma_f32_16x16x32_bf16 v[48:51], v[182:185], v[190:193], v[48:51]
	v_mfma_f32_16x16x32_bf16 v[36:39], v[174:177], v[198:201], v[36:39]
	v_mfma_f32_16x16x32_bf16 v[32:35], v[182:185], v[198:201], v[32:35]
	v_mfma_f32_16x16x32_bf16 v[20:23], v[174:177], v[220:223], v[20:23]
	v_mfma_f32_16x16x32_bf16 v[16:19], v[182:185], v[220:223], v[16:19]
	v_mfma_f32_16x16x32_bf16 v[4:7], v[174:177], v[232:235], v[4:7]
	v_mfma_f32_16x16x32_bf16 v[0:3], v[182:185], v[232:235], v[0:3]
	v_mfma_f32_16x16x32_bf16 v[52:55], v[178:181], v[194:197], v[52:55]
	v_mfma_f32_16x16x32_bf16 v[48:51], v[186:189], v[194:197], v[48:51]
	v_mfma_f32_16x16x32_bf16 v[36:39], v[178:181], v[202:205], v[36:39]
	v_mfma_f32_16x16x32_bf16 v[32:35], v[186:189], v[202:205], v[32:35]
	v_mfma_f32_16x16x32_bf16 v[20:23], v[178:181], v[228:231], v[20:23]
	v_mfma_f32_16x16x32_bf16 v[16:19], v[186:189], v[228:231], v[16:19]
	v_mfma_f32_16x16x32_bf16 v[4:7], v[178:181], v[236:239], v[4:7]
	v_mfma_f32_16x16x32_bf16 v[0:3], v[186:189], v[236:239], v[0:3]
	s_setprio 0
	s_barrier
	s_add_i32 s55, 0, 0x18000
	s_add_i32 s72, 0, 0x1c000
	v_add_u32_e32 v156, s55, v145
	v_add_u32_e32 v162, s72, v145
	ds_read_b128 v[140:143], v156
	ds_read_b128 v[148:151], v156 offset:1024
	ds_read_b128 v[152:155], v156 offset:2048
	ds_read_b128 v[156:159], v156 offset:3072
	ds_read_b128 v[174:177], v162
	ds_read_b128 v[178:181], v162 offset:1024
	ds_read_b128 v[182:185], v162 offset:2048
	ds_read_b128 v[186:189], v162 offset:3072
	s_add_u32 s64, s64, 0x40000
	s_addc_u32 s65, s65, 0
	s_mov_b32 m0, s67
	v_lshl_add_u64 v[248:249], s[64:65], 0, v[134:135]
	ds_read_b128 v[190:193], v147 offset:32768
	ds_read_b128 v[194:197], v147 offset:33792
	ds_read_b128 v[198:201], v147 offset:34816
	ds_read_b128 v[202:205], v147 offset:35840
	ds_read_b128 v[220:223], v147 offset:36864
	ds_read_b128 v[228:231], v147 offset:37888
	ds_read_b128 v[232:235], v147 offset:38912
	ds_read_b128 v[236:239], v147 offset:39936
	global_load_lds_dwordx4 v[248:249], off
	v_lshl_add_u64 v[248:249], s[64:65], 0, v[130:131]
	s_mov_b32 m0, s68
	s_nop 0
	global_load_lds_dwordx4 v[248:249], off
	s_waitcnt vmcnt(8)
	s_waitcnt lgkmcnt(0)
	s_barrier
	s_setprio 1
	s_waitcnt lgkmcnt(0)
	v_mfma_f32_16x16x32_bf16 v[124:127], v[140:143], v[190:193], v[124:127]
	v_mfma_f32_16x16x32_bf16 v[120:123], v[152:155], v[190:193], v[120:123]
	v_mfma_f32_16x16x32_bf16 v[108:111], v[140:143], v[198:201], v[108:111]
	v_mfma_f32_16x16x32_bf16 v[104:107], v[152:155], v[198:201], v[104:107]
	v_mfma_f32_16x16x32_bf16 v[92:95], v[140:143], v[220:223], v[92:95]
	v_mfma_f32_16x16x32_bf16 v[88:91], v[152:155], v[220:223], v[88:91]
	v_mfma_f32_16x16x32_bf16 v[76:79], v[140:143], v[232:235], v[76:79]
	v_mfma_f32_16x16x32_bf16 v[72:75], v[152:155], v[232:235], v[72:75]
	v_mfma_f32_16x16x32_bf16 v[124:127], v[148:151], v[194:197], v[124:127]
	v_mfma_f32_16x16x32_bf16 v[120:123], v[156:159], v[194:197], v[120:123]
	v_mfma_f32_16x16x32_bf16 v[108:111], v[148:151], v[202:205], v[108:111]
	v_mfma_f32_16x16x32_bf16 v[104:107], v[156:159], v[202:205], v[104:107]
	v_mfma_f32_16x16x32_bf16 v[92:95], v[148:151], v[228:231], v[92:95]
	v_mfma_f32_16x16x32_bf16 v[88:91], v[156:159], v[228:231], v[88:91]
	v_mfma_f32_16x16x32_bf16 v[76:79], v[148:151], v[236:239], v[76:79]
	v_mfma_f32_16x16x32_bf16 v[72:75], v[156:159], v[236:239], v[72:75]
	v_mfma_f32_16x16x32_bf16 v[116:119], v[174:177], v[190:193], v[116:119]
	v_mfma_f32_16x16x32_bf16 v[112:115], v[182:185], v[190:193], v[112:115]
	v_mfma_f32_16x16x32_bf16 v[100:103], v[174:177], v[198:201], v[100:103]
	v_mfma_f32_16x16x32_bf16 v[96:99], v[182:185], v[198:201], v[96:99]
	v_mfma_f32_16x16x32_bf16 v[84:87], v[174:177], v[220:223], v[84:87]
	v_mfma_f32_16x16x32_bf16 v[80:83], v[182:185], v[220:223], v[80:83]
	v_mfma_f32_16x16x32_bf16 v[68:71], v[174:177], v[232:235], v[68:71]
	v_mfma_f32_16x16x32_bf16 v[64:67], v[182:185], v[232:235], v[64:67]
	v_mfma_f32_16x16x32_bf16 v[116:119], v[178:181], v[194:197], v[116:119]
	v_mfma_f32_16x16x32_bf16 v[112:115], v[186:189], v[194:197], v[112:115]
	v_mfma_f32_16x16x32_bf16 v[100:103], v[178:181], v[202:205], v[100:103]
	v_mfma_f32_16x16x32_bf16 v[96:99], v[186:189], v[202:205], v[96:99]
	v_mfma_f32_16x16x32_bf16 v[84:87], v[178:181], v[228:231], v[84:87]
	v_mfma_f32_16x16x32_bf16 v[80:83], v[186:189], v[228:231], v[80:83]
	v_mfma_f32_16x16x32_bf16 v[68:71], v[178:181], v[236:239], v[68:71]
	v_mfma_f32_16x16x32_bf16 v[64:67], v[186:189], v[236:239], v[64:67]
	s_setprio 0
	s_barrier
	s_add_i32 s55, s55, s24
	v_lshl_add_u64 v[240:241], v[240:241], 0, s[4:5]
	s_mov_b32 m0, s55
	ds_read_b128 v[190:193], v147 offset:49152
	ds_read_b128 v[194:197], v147 offset:50176
	ds_read_b128 v[198:201], v147 offset:51200
	ds_read_b128 v[202:205], v147 offset:52224
	ds_read_b128 v[220:223], v147 offset:53248
	ds_read_b128 v[228:231], v147 offset:54272
	ds_read_b128 v[232:235], v147 offset:55296
	ds_read_b128 v[236:239], v147 offset:56320
	global_load_lds_dwordx4 v[240:241], off
	s_add_i32 m0, s55, 0x2000
	s_add_u32 s62, s62, 0x40080
	v_lshl_add_u64 v[240:241], v[242:243], 0, s[4:5]
	s_addc_u32 s63, s63, 0
	s_add_i32 s55, s72, s24
	global_load_lds_dwordx4 v[240:241], off
	v_lshl_add_u64 v[240:241], s[62:63], 0, v[132:133]
	s_mov_b32 m0, s55
	s_nop 0
	global_load_lds_dwordx4 v[240:241], off
	v_lshl_add_u64 v[240:241], s[62:63], 0, v[128:129]
	s_add_i32 m0, s55, 0x2000
	s_nop 0
	global_load_lds_dwordx4 v[240:241], off
	v_lshl_add_u64 v[240:241], v[244:245], 0, s[4:5]
	s_mov_b32 m0, s69
	s_nop 0
	global_load_lds_dwordx4 v[240:241], off
	v_lshl_add_u64 v[240:241], v[246:247], 0, s[4:5]
	s_mov_b32 m0, s70
	s_nop 0
	global_load_lds_dwordx4 v[240:241], off
	s_waitcnt vmcnt(8)
	s_waitcnt lgkmcnt(0)
	s_barrier
	s_setprio 1
	s_waitcnt lgkmcnt(0)
	v_mfma_f32_16x16x32_bf16 v[60:63], v[140:143], v[190:193], v[60:63]
	v_mfma_f32_16x16x32_bf16 v[56:59], v[152:155], v[190:193], v[56:59]
	v_mfma_f32_16x16x32_bf16 v[44:47], v[140:143], v[198:201], v[44:47]
	v_mfma_f32_16x16x32_bf16 v[40:43], v[152:155], v[198:201], v[40:43]
	v_mfma_f32_16x16x32_bf16 v[28:31], v[140:143], v[220:223], v[28:31]
	v_mfma_f32_16x16x32_bf16 v[24:27], v[152:155], v[220:223], v[24:27]
	v_mfma_f32_16x16x32_bf16 v[12:15], v[140:143], v[232:235], v[12:15]
	v_mfma_f32_16x16x32_bf16 v[8:11], v[152:155], v[232:235], v[8:11]
	v_mfma_f32_16x16x32_bf16 v[60:63], v[148:151], v[194:197], v[60:63]
	v_mfma_f32_16x16x32_bf16 v[56:59], v[156:159], v[194:197], v[56:59]
	v_mfma_f32_16x16x32_bf16 v[44:47], v[148:151], v[202:205], v[44:47]
	v_mfma_f32_16x16x32_bf16 v[40:43], v[156:159], v[202:205], v[40:43]
	v_mfma_f32_16x16x32_bf16 v[28:31], v[148:151], v[228:231], v[28:31]
	v_mfma_f32_16x16x32_bf16 v[24:27], v[156:159], v[228:231], v[24:27]
	v_mfma_f32_16x16x32_bf16 v[12:15], v[148:151], v[236:239], v[12:15]
	v_mfma_f32_16x16x32_bf16 v[8:11], v[156:159], v[236:239], v[8:11]
	v_mfma_f32_16x16x32_bf16 v[52:55], v[174:177], v[190:193], v[52:55]
	v_mfma_f32_16x16x32_bf16 v[48:51], v[182:185], v[190:193], v[48:51]
	v_mfma_f32_16x16x32_bf16 v[36:39], v[174:177], v[198:201], v[36:39]
	v_mfma_f32_16x16x32_bf16 v[32:35], v[182:185], v[198:201], v[32:35]
	v_mfma_f32_16x16x32_bf16 v[20:23], v[174:177], v[220:223], v[20:23]
	v_mfma_f32_16x16x32_bf16 v[16:19], v[182:185], v[220:223], v[16:19]
	v_mfma_f32_16x16x32_bf16 v[4:7], v[174:177], v[232:235], v[4:7]
	v_mfma_f32_16x16x32_bf16 v[0:3], v[182:185], v[232:235], v[0:3]
	v_mfma_f32_16x16x32_bf16 v[52:55], v[178:181], v[194:197], v[52:55]
	v_mfma_f32_16x16x32_bf16 v[48:51], v[186:189], v[194:197], v[48:51]
	v_mfma_f32_16x16x32_bf16 v[36:39], v[178:181], v[202:205], v[36:39]
	v_mfma_f32_16x16x32_bf16 v[32:35], v[186:189], v[202:205], v[32:35]
	v_mfma_f32_16x16x32_bf16 v[20:23], v[178:181], v[228:231], v[20:23]
	v_mfma_f32_16x16x32_bf16 v[16:19], v[186:189], v[228:231], v[16:19]
	v_mfma_f32_16x16x32_bf16 v[4:7], v[178:181], v[236:239], v[4:7]
	v_mfma_f32_16x16x32_bf16 v[0:3], v[186:189], v[236:239], v[0:3]
	s_setprio 0
	s_barrier
	s_add_i32 s53, s53, 2
	s_add_u32 s60, s60, 0x100
	s_addc_u32 s61, s61, 0
	s_add_u32 s30, s30, 0x100
	s_addc_u32 s31, s31, 0
	s_cmp_gt_u32 s53, 13
	s_cbranch_scc0 .LBB0_771
	s_and_b64 vcc, exec, s[48:49]
	s_mov_b64 s[30:31], s[34:35]
	s_cbranch_vccz .LBB0_774
	s_barrier

.LBB0_858:
	s_add_u32 s61, s66, 0xfffe0080
	s_addc_u32 s68, s67, -1
	s_add_i32 s83, 0, 0x10000
	s_cmp_eq_u32 s59, 4
	s_cselect_b32 s71, s6, s68
	s_cselect_b32 s70, s7, s61
	v_add_u32_e32 v136, s83, v157
	s_cselect_b32 s69, s28, s31
	s_cselect_b32 s68, s29, s30
	s_add_i32 s61, 0, 0x14000
	ds_read_b128 v[128:131], v136
	ds_read_b128 v[132:135], v136 offset:1024
	ds_read_b128 v[148:151], v136 offset:2048
	ds_read_b128 v[152:155], v136 offset:3072
	v_add_u32_e32 v136, s61, v157
	ds_read_b128 v[174:177], v136
	ds_read_b128 v[178:181], v136 offset:1024
	ds_read_b128 v[182:185], v136 offset:2048
	ds_read_b128 v[186:189], v136 offset:3072
	v_lshl_add_u64 v[136:137], s[66:67], 0, v[144:145]
	s_add_i32 m0, s25, 0xc000
	ds_read_b128 v[190:193], v159
	ds_read_b128 v[194:197], v159 offset:1024
	ds_read_b128 v[198:201], v159 offset:2048
	ds_read_b128 v[202:205], v159 offset:3072
	ds_read_b128 v[220:223], v159 offset:4096
	ds_read_b128 v[228:231], v159 offset:5120
	ds_read_b128 v[232:235], v159 offset:6144
	ds_read_b128 v[236:239], v159 offset:7168
	global_load_lds_dwordx4 v[136:137], off
	v_lshl_add_u64 v[136:137], s[66:67], 0, v[146:147]
	s_add_i32 m0, s25, 0xe000
	s_nop 0
	global_load_lds_dwordx4 v[136:137], off
	s_waitcnt vmcnt(8)
	s_waitcnt lgkmcnt(0)
	s_barrier
	s_setprio 1
	s_waitcnt lgkmcnt(0)
	v_mfma_f32_16x16x32_bf16 v[124:127], v[128:131], v[190:193], v[124:127]
	v_mfma_f32_16x16x32_bf16 v[120:123], v[148:151], v[190:193], v[120:123]
	v_mfma_f32_16x16x32_bf16 v[108:111], v[128:131], v[198:201], v[108:111]
	v_mfma_f32_16x16x32_bf16 v[104:107], v[148:151], v[198:201], v[104:107]
	v_mfma_f32_16x16x32_bf16 v[92:95], v[128:131], v[220:223], v[92:95]
	v_mfma_f32_16x16x32_bf16 v[88:91], v[148:151], v[220:223], v[88:91]
	v_mfma_f32_16x16x32_bf16 v[76:79], v[128:131], v[232:235], v[76:79]
	v_mfma_f32_16x16x32_bf16 v[72:75], v[148:151], v[232:235], v[72:75]
	v_mfma_f32_16x16x32_bf16 v[124:127], v[132:135], v[194:197], v[124:127]
	v_mfma_f32_16x16x32_bf16 v[120:123], v[152:155], v[194:197], v[120:123]
	v_mfma_f32_16x16x32_bf16 v[108:111], v[132:135], v[202:205], v[108:111]
	v_mfma_f32_16x16x32_bf16 v[104:107], v[152:155], v[202:205], v[104:107]
	v_mfma_f32_16x16x32_bf16 v[92:95], v[132:135], v[228:231], v[92:95]
	v_mfma_f32_16x16x32_bf16 v[88:91], v[152:155], v[228:231], v[88:91]
	v_mfma_f32_16x16x32_bf16 v[76:79], v[132:135], v[236:239], v[76:79]
	v_mfma_f32_16x16x32_bf16 v[72:75], v[152:155], v[236:239], v[72:75]
	v_mfma_f32_16x16x32_bf16 v[116:119], v[174:177], v[190:193], v[116:119]
	v_mfma_f32_16x16x32_bf16 v[112:115], v[182:185], v[190:193], v[112:115]
	v_mfma_f32_16x16x32_bf16 v[100:103], v[174:177], v[198:201], v[100:103]
	v_mfma_f32_16x16x32_bf16 v[96:99], v[182:185], v[198:201], v[96:99]
	v_mfma_f32_16x16x32_bf16 v[84:87], v[174:177], v[220:223], v[84:87]
	v_mfma_f32_16x16x32_bf16 v[80:83], v[182:185], v[220:223], v[80:83]
	v_mfma_f32_16x16x32_bf16 v[68:71], v[174:177], v[232:235], v[68:71]
	v_mfma_f32_16x16x32_bf16 v[64:67], v[182:185], v[232:235], v[64:67]
	v_mfma_f32_16x16x32_bf16 v[116:119], v[178:181], v[194:197], v[116:119]
	v_mfma_f32_16x16x32_bf16 v[112:115], v[186:189], v[194:197], v[112:115]
	v_mfma_f32_16x16x32_bf16 v[100:103], v[178:181], v[202:205], v[100:103]
	v_mfma_f32_16x16x32_bf16 v[96:99], v[186:189], v[202:205], v[96:99]
	v_mfma_f32_16x16x32_bf16 v[84:87], v[178:181], v[228:231], v[84:87]
	v_mfma_f32_16x16x32_bf16 v[80:83], v[186:189], v[228:231], v[80:83]
	v_mfma_f32_16x16x32_bf16 v[68:71], v[178:181], v[236:239], v[68:71]
	v_mfma_f32_16x16x32_bf16 v[64:67], v[186:189], v[236:239], v[64:67]
	s_setprio 0
	s_barrier
	s_add_i32 s83, s83, s22
	v_lshl_add_u64 v[136:137], s[68:69], 0, v[162:163]
	s_mov_b32 m0, s83
	ds_read_b128 v[190:193], v159 offset:16384
	ds_read_b128 v[194:197], v159 offset:17408
	ds_read_b128 v[198:201], v159 offset:18432
	ds_read_b128 v[202:205], v159 offset:19456
	ds_read_b128 v[220:223], v159 offset:20480
	ds_read_b128 v[228:231], v159 offset:21504
	ds_read_b128 v[232:235], v159 offset:22528
	ds_read_b128 v[236:239], v159 offset:23552
	global_load_lds_dwordx4 v[136:137], off
	s_add_i32 m0, s83, 0x2000
	s_add_u32 s84, s68, 0x20000
	v_lshl_add_u64 v[240:241], s[68:69], 0, v[138:139]
	s_addc_u32 s85, s69, 0
	s_add_i32 s61, s61, s22
	global_load_lds_dwordx4 v[240:241], off
	v_lshl_add_u64 v[242:243], s[84:85], 0, v[162:163]
	s_mov_b32 m0, s61
	v_lshl_add_u64 v[244:245], s[70:71], 0, v[140:141]
	global_load_lds_dwordx4 v[242:243], off
	v_lshl_add_u64 v[242:243], s[84:85], 0, v[138:139]
	s_add_i32 m0, s61, 0x2000
	s_nop 0
	global_load_lds_dwordx4 v[242:243], off
	v_lshl_add_u64 v[242:243], s[70:71], 0, v[142:143]
	s_mov_b32 m0, s25
	s_nop 0
	global_load_lds_dwordx4 v[242:243], off
	s_mov_b32 m0, s72
	s_nop 0
	global_load_lds_dwordx4 v[244:245], off
	s_waitcnt vmcnt(8)
	s_waitcnt lgkmcnt(0)
	s_barrier
	s_setprio 1
	s_waitcnt lgkmcnt(0)
	v_mfma_f32_16x16x32_bf16 v[60:63], v[128:131], v[190:193], v[60:63]
	v_mfma_f32_16x16x32_bf16 v[56:59], v[148:151], v[190:193], v[56:59]
	v_mfma_f32_16x16x32_bf16 v[44:47], v[128:131], v[198:201], v[44:47]
	v_mfma_f32_16x16x32_bf16 v[40:43], v[148:151], v[198:201], v[40:43]
	v_mfma_f32_16x16x32_bf16 v[28:31], v[128:131], v[220:223], v[28:31]
	v_mfma_f32_16x16x32_bf16 v[24:27], v[148:151], v[220:223], v[24:27]
	v_mfma_f32_16x16x32_bf16 v[12:15], v[128:131], v[232:235], v[12:15]
	v_mfma_f32_16x16x32_bf16 v[8:11], v[148:151], v[232:235], v[8:11]
	v_mfma_f32_16x16x32_bf16 v[60:63], v[132:135], v[194:197], v[60:63]
	v_mfma_f32_16x16x32_bf16 v[56:59], v[152:155], v[194:197], v[56:59]
	v_mfma_f32_16x16x32_bf16 v[44:47], v[132:135], v[202:205], v[44:47]
	v_mfma_f32_16x16x32_bf16 v[40:43], v[152:155], v[202:205], v[40:43]
	v_mfma_f32_16x16x32_bf16 v[28:31], v[132:135], v[228:231], v[28:31]
	v_mfma_f32_16x16x32_bf16 v[24:27], v[152:155], v[228:231], v[24:27]
	v_mfma_f32_16x16x32_bf16 v[12:15], v[132:135], v[236:239], v[12:15]
	v_mfma_f32_16x16x32_bf16 v[8:11], v[152:155], v[236:239], v[8:11]
	v_mfma_f32_16x16x32_bf16 v[52:55], v[174:177], v[190:193], v[52:55]
	v_mfma_f32_16x16x32_bf16 v[48:51], v[182:185], v[190:193], v[48:51]
	v_mfma_f32_16x16x32_bf16 v[36:39], v[174:177], v[198:201], v[36:39]
	v_mfma_f32_16x16x32_bf16 v[32:35], v[182:185], v[198:201], v[32:35]
	v_mfma_f32_16x16x32_bf16 v[20:23], v[174:177], v[220:223], v[20:23]
	v_mfma_f32_16x16x32_bf16 v[16:19], v[182:185], v[220:223], v[16:19]
	v_mfma_f32_16x16x32_bf16 v[4:7], v[174:177], v[232:235], v[4:7]
	v_mfma_f32_16x16x32_bf16 v[0:3], v[182:185], v[232:235], v[0:3]
	v_mfma_f32_16x16x32_bf16 v[52:55], v[178:181], v[194:197], v[52:55]
	v_mfma_f32_16x16x32_bf16 v[48:51], v[186:189], v[194:197], v[48:51]
	v_mfma_f32_16x16x32_bf16 v[36:39], v[178:181], v[202:205], v[36:39]
	v_mfma_f32_16x16x32_bf16 v[32:35], v[186:189], v[202:205], v[32:35]
	v_mfma_f32_16x16x32_bf16 v[20:23], v[178:181], v[228:231], v[20:23]
	v_mfma_f32_16x16x32_bf16 v[16:19], v[186:189], v[228:231], v[16:19]
	v_mfma_f32_16x16x32_bf16 v[4:7], v[178:181], v[236:239], v[4:7]
	v_mfma_f32_16x16x32_bf16 v[0:3], v[186:189], v[236:239], v[0:3]
	s_setprio 0
	s_barrier
	s_add_i32 s61, 0, 0x18000
	s_add_i32 s83, 0, 0x1c000
	v_add_u32_e32 v152, s61, v157
	v_add_u32_e32 v186, s83, v157
	ds_read_b128 v[128:131], v152
	ds_read_b128 v[132:135], v152 offset:1024
	ds_read_b128 v[148:151], v152 offset:2048
	ds_read_b128 v[152:155], v152 offset:3072
	ds_read_b128 v[174:177], v186
	ds_read_b128 v[178:181], v186 offset:1024
	ds_read_b128 v[182:185], v186 offset:2048
	ds_read_b128 v[186:189], v186 offset:3072
	s_add_u32 s70, s70, 0x20000
	s_addc_u32 s71, s71, 0
	s_mov_b32 m0, s73
	v_lshl_add_u64 v[246:247], s[70:71], 0, v[142:143]
	ds_read_b128 v[190:193], v159 offset:32768
	ds_read_b128 v[194:197], v159 offset:33792
	ds_read_b128 v[198:201], v159 offset:34816
	ds_read_b128 v[202:205], v159 offset:35840
	ds_read_b128 v[220:223], v159 offset:36864
	ds_read_b128 v[228:231], v159 offset:37888
	ds_read_b128 v[232:235], v159 offset:38912
	ds_read_b128 v[236:239], v159 offset:39936
	global_load_lds_dwordx4 v[246:247], off
	v_lshl_add_u64 v[246:247], s[70:71], 0, v[140:141]
	s_mov_b32 m0, s74
	s_nop 0
	global_load_lds_dwordx4 v[246:247], off
	s_waitcnt vmcnt(8)
	s_waitcnt lgkmcnt(0)
	s_barrier
	s_setprio 1
	s_waitcnt lgkmcnt(0)
	v_mfma_f32_16x16x32_bf16 v[124:127], v[128:131], v[190:193], v[124:127]
	v_mfma_f32_16x16x32_bf16 v[120:123], v[148:151], v[190:193], v[120:123]
	v_mfma_f32_16x16x32_bf16 v[108:111], v[128:131], v[198:201], v[108:111]
	v_mfma_f32_16x16x32_bf16 v[104:107], v[148:151], v[198:201], v[104:107]
	v_mfma_f32_16x16x32_bf16 v[92:95], v[128:131], v[220:223], v[92:95]
	v_mfma_f32_16x16x32_bf16 v[88:91], v[148:151], v[220:223], v[88:91]
	v_mfma_f32_16x16x32_bf16 v[76:79], v[128:131], v[232:235], v[76:79]
	v_mfma_f32_16x16x32_bf16 v[72:75], v[148:151], v[232:235], v[72:75]
	v_mfma_f32_16x16x32_bf16 v[124:127], v[132:135], v[194:197], v[124:127]
	v_mfma_f32_16x16x32_bf16 v[120:123], v[152:155], v[194:197], v[120:123]
	v_mfma_f32_16x16x32_bf16 v[108:111], v[132:135], v[202:205], v[108:111]
	v_mfma_f32_16x16x32_bf16 v[104:107], v[152:155], v[202:205], v[104:107]
	v_mfma_f32_16x16x32_bf16 v[92:95], v[132:135], v[228:231], v[92:95]
	v_mfma_f32_16x16x32_bf16 v[88:91], v[152:155], v[228:231], v[88:91]
	v_mfma_f32_16x16x32_bf16 v[76:79], v[132:135], v[236:239], v[76:79]
	v_mfma_f32_16x16x32_bf16 v[72:75], v[152:155], v[236:239], v[72:75]
	v_mfma_f32_16x16x32_bf16 v[116:119], v[174:177], v[190:193], v[116:119]
	v_mfma_f32_16x16x32_bf16 v[112:115], v[182:185], v[190:193], v[112:115]
	v_mfma_f32_16x16x32_bf16 v[100:103], v[174:177], v[198:201], v[100:103]
	v_mfma_f32_16x16x32_bf16 v[96:99], v[182:185], v[198:201], v[96:99]
	v_mfma_f32_16x16x32_bf16 v[84:87], v[174:177], v[220:223], v[84:87]
	v_mfma_f32_16x16x32_bf16 v[80:83], v[182:185], v[220:223], v[80:83]
	v_mfma_f32_16x16x32_bf16 v[68:71], v[174:177], v[232:235], v[68:71]
	v_mfma_f32_16x16x32_bf16 v[64:67], v[182:185], v[232:235], v[64:67]
	v_mfma_f32_16x16x32_bf16 v[116:119], v[178:181], v[194:197], v[116:119]
	v_mfma_f32_16x16x32_bf16 v[112:115], v[186:189], v[194:197], v[112:115]
	v_mfma_f32_16x16x32_bf16 v[100:103], v[178:181], v[202:205], v[100:103]
	v_mfma_f32_16x16x32_bf16 v[96:99], v[186:189], v[202:205], v[96:99]
	v_mfma_f32_16x16x32_bf16 v[84:87], v[178:181], v[228:231], v[84:87]
	v_mfma_f32_16x16x32_bf16 v[80:83], v[186:189], v[228:231], v[80:83]
	v_mfma_f32_16x16x32_bf16 v[68:71], v[178:181], v[236:239], v[68:71]
	v_mfma_f32_16x16x32_bf16 v[64:67], v[186:189], v[236:239], v[64:67]
	s_setprio 0
	s_barrier
	s_add_i32 s61, s61, s22
	v_lshl_add_u64 v[136:137], v[136:137], 0, s[4:5]
	s_mov_b32 m0, s61
	ds_read_b128 v[190:193], v159 offset:49152
	ds_read_b128 v[194:197], v159 offset:50176
	ds_read_b128 v[198:201], v159 offset:51200
	ds_read_b128 v[202:205], v159 offset:52224
	ds_read_b128 v[220:223], v159 offset:53248
	ds_read_b128 v[228:231], v159 offset:54272
	ds_read_b128 v[232:235], v159 offset:55296
	ds_read_b128 v[236:239], v159 offset:56320
	global_load_lds_dwordx4 v[136:137], off
	s_add_i32 m0, s61, 0x2000
	s_add_u32 s68, s68, 0x20080
	v_lshl_add_u64 v[136:137], v[240:241], 0, s[4:5]
	s_addc_u32 s69, s69, 0
	s_add_i32 s61, s83, s22
	global_load_lds_dwordx4 v[136:137], off
	v_lshl_add_u64 v[136:137], s[68:69], 0, v[162:163]
	s_mov_b32 m0, s61
	s_nop 0
	global_load_lds_dwordx4 v[136:137], off
	v_lshl_add_u64 v[136:137], s[68:69], 0, v[138:139]
	s_add_i32 m0, s61, 0x2000
	s_nop 0
	global_load_lds_dwordx4 v[136:137], off
	v_lshl_add_u64 v[136:137], v[242:243], 0, s[4:5]
	s_mov_b32 m0, s75
	s_nop 0
	global_load_lds_dwordx4 v[136:137], off
	v_lshl_add_u64 v[136:137], v[244:245], 0, s[4:5]
	s_mov_b32 m0, s76
	s_nop 0
	global_load_lds_dwordx4 v[136:137], off
	s_waitcnt vmcnt(8)
	s_waitcnt lgkmcnt(0)
	s_barrier
	s_setprio 1
	s_waitcnt lgkmcnt(0)
	v_mfma_f32_16x16x32_bf16 v[60:63], v[128:131], v[190:193], v[60:63]
	v_mfma_f32_16x16x32_bf16 v[56:59], v[148:151], v[190:193], v[56:59]
	v_mfma_f32_16x16x32_bf16 v[44:47], v[128:131], v[198:201], v[44:47]
	v_mfma_f32_16x16x32_bf16 v[40:43], v[148:151], v[198:201], v[40:43]
	v_mfma_f32_16x16x32_bf16 v[28:31], v[128:131], v[220:223], v[28:31]
	v_mfma_f32_16x16x32_bf16 v[24:27], v[148:151], v[220:223], v[24:27]
	v_mfma_f32_16x16x32_bf16 v[12:15], v[128:131], v[232:235], v[12:15]
	v_mfma_f32_16x16x32_bf16 v[8:11], v[148:151], v[232:235], v[8:11]
	v_mfma_f32_16x16x32_bf16 v[60:63], v[132:135], v[194:197], v[60:63]
	v_mfma_f32_16x16x32_bf16 v[56:59], v[152:155], v[194:197], v[56:59]
	v_mfma_f32_16x16x32_bf16 v[44:47], v[132:135], v[202:205], v[44:47]
	v_mfma_f32_16x16x32_bf16 v[40:43], v[152:155], v[202:205], v[40:43]
	v_mfma_f32_16x16x32_bf16 v[28:31], v[132:135], v[228:231], v[28:31]
	v_mfma_f32_16x16x32_bf16 v[24:27], v[152:155], v[228:231], v[24:27]
	v_mfma_f32_16x16x32_bf16 v[12:15], v[132:135], v[236:239], v[12:15]
	v_mfma_f32_16x16x32_bf16 v[8:11], v[152:155], v[236:239], v[8:11]
	v_mfma_f32_16x16x32_bf16 v[52:55], v[174:177], v[190:193], v[52:55]
	v_mfma_f32_16x16x32_bf16 v[48:51], v[182:185], v[190:193], v[48:51]
	v_mfma_f32_16x16x32_bf16 v[36:39], v[174:177], v[198:201], v[36:39]
	v_mfma_f32_16x16x32_bf16 v[32:35], v[182:185], v[198:201], v[32:35]
	v_mfma_f32_16x16x32_bf16 v[20:23], v[174:177], v[220:223], v[20:23]
	v_mfma_f32_16x16x32_bf16 v[16:19], v[182:185], v[220:223], v[16:19]
	v_mfma_f32_16x16x32_bf16 v[4:7], v[174:177], v[232:235], v[4:7]
	v_mfma_f32_16x16x32_bf16 v[0:3], v[182:185], v[232:235], v[0:3]
	v_mfma_f32_16x16x32_bf16 v[52:55], v[178:181], v[194:197], v[52:55]
	v_mfma_f32_16x16x32_bf16 v[48:51], v[186:189], v[194:197], v[48:51]
	v_mfma_f32_16x16x32_bf16 v[36:39], v[178:181], v[202:205], v[36:39]
	v_mfma_f32_16x16x32_bf16 v[32:35], v[186:189], v[202:205], v[32:35]
	v_mfma_f32_16x16x32_bf16 v[20:23], v[178:181], v[228:231], v[20:23]
	v_mfma_f32_16x16x32_bf16 v[16:19], v[186:189], v[228:231], v[16:19]
	v_mfma_f32_16x16x32_bf16 v[4:7], v[178:181], v[236:239], v[4:7]
	v_mfma_f32_16x16x32_bf16 v[0:3], v[186:189], v[236:239], v[0:3]
	s_setprio 0
	s_barrier
	s_add_i32 s59, s59, 2
	s_add_u32 s66, s66, 0x100
	s_addc_u32 s67, s67, 0
	s_add_u32 s30, s30, 0x100
	s_addc_u32 s31, s31, 0
	s_cmp_gt_u32 s59, 5
	s_cbranch_scc0 .LBB0_858
	s_and_b64 vcc, exec, s[56:57]
	s_cbranch_vccz .LBB0_861
	s_barrier

.LBB0_975:
	s_add_u32 s29, s60, 0xfffc0080
	s_addc_u32 s30, s61, -1
	s_add_i32 s31, 0, 0x10000
	s_cmp_eq_u32 s28, 12
	s_cselect_b32 s65, s6, s30
	s_cselect_b32 s64, s7, s29
	v_add_u32_e32 v142, s31, v145
	s_cselect_b32 s63, s24, s27
	s_cselect_b32 s62, s25, s26
	s_add_i32 s29, 0, 0x14000
	ds_read_b128 v[138:141], v142
	ds_read_b128 v[148:151], v142 offset:1024
	ds_read_b128 v[152:155], v142 offset:2048
	ds_read_b128 v[156:159], v142 offset:3072
	v_add_u32_e32 v142, s29, v145
	ds_read_b128 v[174:177], v142
	ds_read_b128 v[178:181], v142 offset:1024
	ds_read_b128 v[182:185], v142 offset:2048
	ds_read_b128 v[186:189], v142 offset:3072
	v_lshl_add_u64 v[142:143], s[60:61], 0, v[134:135]
	s_add_i32 m0, s69, 0xc000
	ds_read_b128 v[190:193], v147
	ds_read_b128 v[194:197], v147 offset:1024
	ds_read_b128 v[198:201], v147 offset:2048
	ds_read_b128 v[202:205], v147 offset:3072
	ds_read_b128 v[220:223], v147 offset:4096
	ds_read_b128 v[228:231], v147 offset:5120
	ds_read_b128 v[232:235], v147 offset:6144
	ds_read_b128 v[236:239], v147 offset:7168
	global_load_lds_dwordx4 v[142:143], off
	v_lshl_add_u64 v[142:143], s[60:61], 0, v[136:137]
	s_add_i32 m0, s69, 0xe000
	s_nop 0
	global_load_lds_dwordx4 v[142:143], off
	s_waitcnt vmcnt(8)
	s_waitcnt lgkmcnt(0)
	s_barrier
	s_setprio 1
	s_waitcnt lgkmcnt(0)
	v_mfma_f32_16x16x32_bf16 v[124:127], v[138:141], v[190:193], v[124:127]
	v_mfma_f32_16x16x32_bf16 v[120:123], v[152:155], v[190:193], v[120:123]
	v_mfma_f32_16x16x32_bf16 v[108:111], v[138:141], v[198:201], v[108:111]
	v_mfma_f32_16x16x32_bf16 v[104:107], v[152:155], v[198:201], v[104:107]
	v_mfma_f32_16x16x32_bf16 v[92:95], v[138:141], v[220:223], v[92:95]
	v_mfma_f32_16x16x32_bf16 v[88:91], v[152:155], v[220:223], v[88:91]
	v_mfma_f32_16x16x32_bf16 v[76:79], v[138:141], v[232:235], v[76:79]
	v_mfma_f32_16x16x32_bf16 v[72:75], v[152:155], v[232:235], v[72:75]
	v_mfma_f32_16x16x32_bf16 v[124:127], v[148:151], v[194:197], v[124:127]
	v_mfma_f32_16x16x32_bf16 v[120:123], v[156:159], v[194:197], v[120:123]
	v_mfma_f32_16x16x32_bf16 v[108:111], v[148:151], v[202:205], v[108:111]
	v_mfma_f32_16x16x32_bf16 v[104:107], v[156:159], v[202:205], v[104:107]
	v_mfma_f32_16x16x32_bf16 v[92:95], v[148:151], v[228:231], v[92:95]
	v_mfma_f32_16x16x32_bf16 v[88:91], v[156:159], v[228:231], v[88:91]
	v_mfma_f32_16x16x32_bf16 v[76:79], v[148:151], v[236:239], v[76:79]
	v_mfma_f32_16x16x32_bf16 v[72:75], v[156:159], v[236:239], v[72:75]
	v_mfma_f32_16x16x32_bf16 v[116:119], v[174:177], v[190:193], v[116:119]
	v_mfma_f32_16x16x32_bf16 v[112:115], v[182:185], v[190:193], v[112:115]
	v_mfma_f32_16x16x32_bf16 v[100:103], v[174:177], v[198:201], v[100:103]
	v_mfma_f32_16x16x32_bf16 v[96:99], v[182:185], v[198:201], v[96:99]
	v_mfma_f32_16x16x32_bf16 v[84:87], v[174:177], v[220:223], v[84:87]
	v_mfma_f32_16x16x32_bf16 v[80:83], v[182:185], v[220:223], v[80:83]
	v_mfma_f32_16x16x32_bf16 v[68:71], v[174:177], v[232:235], v[68:71]
	v_mfma_f32_16x16x32_bf16 v[64:67], v[182:185], v[232:235], v[64:67]
	v_mfma_f32_16x16x32_bf16 v[116:119], v[178:181], v[194:197], v[116:119]
	v_mfma_f32_16x16x32_bf16 v[112:115], v[186:189], v[194:197], v[112:115]
	v_mfma_f32_16x16x32_bf16 v[100:103], v[178:181], v[202:205], v[100:103]
	v_mfma_f32_16x16x32_bf16 v[96:99], v[186:189], v[202:205], v[96:99]
	v_mfma_f32_16x16x32_bf16 v[84:87], v[178:181], v[228:231], v[84:87]
	v_mfma_f32_16x16x32_bf16 v[80:83], v[186:189], v[228:231], v[80:83]
	v_mfma_f32_16x16x32_bf16 v[68:71], v[178:181], v[236:239], v[68:71]
	v_mfma_f32_16x16x32_bf16 v[64:67], v[186:189], v[236:239], v[64:67]
	s_setprio 0
	s_barrier
	s_add_i32 s30, s31, s68
	v_lshl_add_u64 v[142:143], s[62:63], 0, v[162:163]
	s_mov_b32 m0, s30
	ds_read_b128 v[190:193], v147 offset:16384
	ds_read_b128 v[194:197], v147 offset:17408
	ds_read_b128 v[198:201], v147 offset:18432
	ds_read_b128 v[202:205], v147 offset:19456
	ds_read_b128 v[220:223], v147 offset:20480
	ds_read_b128 v[228:231], v147 offset:21504
	ds_read_b128 v[232:235], v147 offset:22528
	ds_read_b128 v[236:239], v147 offset:23552
	global_load_lds_dwordx4 v[142:143], off
	s_add_i32 m0, s30, 0x2000
	s_add_u32 s30, s62, 0x40000
	v_lshl_add_u64 v[240:241], s[62:63], 0, v[128:129]
	s_addc_u32 s31, s63, 0
	s_add_i32 s29, s29, s68
	global_load_lds_dwordx4 v[240:241], off
	v_lshl_add_u64 v[242:243], s[30:31], 0, v[162:163]
	s_mov_b32 m0, s29
	v_lshl_add_u64 v[244:245], s[64:65], 0, v[130:131]
	global_load_lds_dwordx4 v[242:243], off
	v_lshl_add_u64 v[242:243], s[30:31], 0, v[128:129]
	s_add_i32 m0, s29, 0x2000
	s_nop 0
	global_load_lds_dwordx4 v[242:243], off
	v_lshl_add_u64 v[242:243], s[64:65], 0, v[132:133]
	s_mov_b32 m0, s69
	s_nop 0
	global_load_lds_dwordx4 v[242:243], off
	s_mov_b32 m0, s70
	s_nop 0
	global_load_lds_dwordx4 v[244:245], off
	s_waitcnt vmcnt(8)
	s_waitcnt lgkmcnt(0)
	s_barrier
	s_setprio 1
	s_waitcnt lgkmcnt(0)
	v_mfma_f32_16x16x32_bf16 v[60:63], v[138:141], v[190:193], v[60:63]
	v_mfma_f32_16x16x32_bf16 v[56:59], v[152:155], v[190:193], v[56:59]
	v_mfma_f32_16x16x32_bf16 v[44:47], v[138:141], v[198:201], v[44:47]
	v_mfma_f32_16x16x32_bf16 v[40:43], v[152:155], v[198:201], v[40:43]
	v_mfma_f32_16x16x32_bf16 v[28:31], v[138:141], v[220:223], v[28:31]
	v_mfma_f32_16x16x32_bf16 v[24:27], v[152:155], v[220:223], v[24:27]
	v_mfma_f32_16x16x32_bf16 v[12:15], v[138:141], v[232:235], v[12:15]
	v_mfma_f32_16x16x32_bf16 v[8:11], v[152:155], v[232:235], v[8:11]
	v_mfma_f32_16x16x32_bf16 v[60:63], v[148:151], v[194:197], v[60:63]
	v_mfma_f32_16x16x32_bf16 v[56:59], v[156:159], v[194:197], v[56:59]
	v_mfma_f32_16x16x32_bf16 v[44:47], v[148:151], v[202:205], v[44:47]
	v_mfma_f32_16x16x32_bf16 v[40:43], v[156:159], v[202:205], v[40:43]
	v_mfma_f32_16x16x32_bf16 v[28:31], v[148:151], v[228:231], v[28:31]
	v_mfma_f32_16x16x32_bf16 v[24:27], v[156:159], v[228:231], v[24:27]
	v_mfma_f32_16x16x32_bf16 v[12:15], v[148:151], v[236:239], v[12:15]
	v_mfma_f32_16x16x32_bf16 v[8:11], v[156:159], v[236:239], v[8:11]
	v_mfma_f32_16x16x32_bf16 v[52:55], v[174:177], v[190:193], v[52:55]
	v_mfma_f32_16x16x32_bf16 v[48:51], v[182:185], v[190:193], v[48:51]
	v_mfma_f32_16x16x32_bf16 v[36:39], v[174:177], v[198:201], v[36:39]
	v_mfma_f32_16x16x32_bf16 v[32:35], v[182:185], v[198:201], v[32:35]
	v_mfma_f32_16x16x32_bf16 v[20:23], v[174:177], v[220:223], v[20:23]
	v_mfma_f32_16x16x32_bf16 v[16:19], v[182:185], v[220:223], v[16:19]
	v_mfma_f32_16x16x32_bf16 v[4:7], v[174:177], v[232:235], v[4:7]
	v_mfma_f32_16x16x32_bf16 v[0:3], v[182:185], v[232:235], v[0:3]
	v_mfma_f32_16x16x32_bf16 v[52:55], v[178:181], v[194:197], v[52:55]
	v_mfma_f32_16x16x32_bf16 v[48:51], v[186:189], v[194:197], v[48:51]
	v_mfma_f32_16x16x32_bf16 v[36:39], v[178:181], v[202:205], v[36:39]
	v_mfma_f32_16x16x32_bf16 v[32:35], v[186:189], v[202:205], v[32:35]
	v_mfma_f32_16x16x32_bf16 v[20:23], v[178:181], v[228:231], v[20:23]
	v_mfma_f32_16x16x32_bf16 v[16:19], v[186:189], v[228:231], v[16:19]
	v_mfma_f32_16x16x32_bf16 v[4:7], v[178:181], v[236:239], v[4:7]
	v_mfma_f32_16x16x32_bf16 v[0:3], v[186:189], v[236:239], v[0:3]
	s_setprio 0
	s_barrier
	s_add_i32 s29, 0, 0x18000
	s_add_i32 s53, 0, 0x1c000
	v_add_u32_e32 v156, s29, v145
	v_add_u32_e32 v186, s53, v145
	ds_read_b128 v[138:141], v156
	ds_read_b128 v[148:151], v156 offset:1024
	ds_read_b128 v[152:155], v156 offset:2048
	ds_read_b128 v[156:159], v156 offset:3072
	ds_read_b128 v[174:177], v186
	ds_read_b128 v[178:181], v186 offset:1024
	ds_read_b128 v[182:185], v186 offset:2048
	ds_read_b128 v[186:189], v186 offset:3072
	s_add_u32 s30, s64, 0x40000
	s_addc_u32 s31, s65, 0
	s_mov_b32 m0, s71
	v_lshl_add_u64 v[246:247], s[30:31], 0, v[132:133]
	ds_read_b128 v[190:193], v147 offset:32768
	ds_read_b128 v[194:197], v147 offset:33792
	ds_read_b128 v[198:201], v147 offset:34816
	ds_read_b128 v[202:205], v147 offset:35840
	ds_read_b128 v[220:223], v147 offset:36864
	ds_read_b128 v[228:231], v147 offset:37888
	ds_read_b128 v[232:235], v147 offset:38912
	ds_read_b128 v[236:239], v147 offset:39936
	global_load_lds_dwordx4 v[246:247], off
	v_lshl_add_u64 v[246:247], s[30:31], 0, v[130:131]
	s_mov_b32 m0, s72
	s_nop 0
	global_load_lds_dwordx4 v[246:247], off
	s_waitcnt vmcnt(8)
	s_waitcnt lgkmcnt(0)
	s_barrier
	s_setprio 1
	s_waitcnt lgkmcnt(0)
	v_mfma_f32_16x16x32_bf16 v[124:127], v[138:141], v[190:193], v[124:127]
	v_mfma_f32_16x16x32_bf16 v[120:123], v[152:155], v[190:193], v[120:123]
	v_mfma_f32_16x16x32_bf16 v[108:111], v[138:141], v[198:201], v[108:111]
	v_mfma_f32_16x16x32_bf16 v[104:107], v[152:155], v[198:201], v[104:107]
	v_mfma_f32_16x16x32_bf16 v[92:95], v[138:141], v[220:223], v[92:95]
	v_mfma_f32_16x16x32_bf16 v[88:91], v[152:155], v[220:223], v[88:91]
	v_mfma_f32_16x16x32_bf16 v[76:79], v[138:141], v[232:235], v[76:79]
	v_mfma_f32_16x16x32_bf16 v[72:75], v[152:155], v[232:235], v[72:75]
	v_mfma_f32_16x16x32_bf16 v[124:127], v[148:151], v[194:197], v[124:127]
	v_mfma_f32_16x16x32_bf16 v[120:123], v[156:159], v[194:197], v[120:123]
	v_mfma_f32_16x16x32_bf16 v[108:111], v[148:151], v[202:205], v[108:111]
	v_mfma_f32_16x16x32_bf16 v[104:107], v[156:159], v[202:205], v[104:107]
	v_mfma_f32_16x16x32_bf16 v[92:95], v[148:151], v[228:231], v[92:95]
	v_mfma_f32_16x16x32_bf16 v[88:91], v[156:159], v[228:231], v[88:91]
	v_mfma_f32_16x16x32_bf16 v[76:79], v[148:151], v[236:239], v[76:79]
	v_mfma_f32_16x16x32_bf16 v[72:75], v[156:159], v[236:239], v[72:75]
	v_mfma_f32_16x16x32_bf16 v[116:119], v[174:177], v[190:193], v[116:119]
	v_mfma_f32_16x16x32_bf16 v[112:115], v[182:185], v[190:193], v[112:115]
	v_mfma_f32_16x16x32_bf16 v[100:103], v[174:177], v[198:201], v[100:103]
	v_mfma_f32_16x16x32_bf16 v[96:99], v[182:185], v[198:201], v[96:99]
	v_mfma_f32_16x16x32_bf16 v[84:87], v[174:177], v[220:223], v[84:87]
	v_mfma_f32_16x16x32_bf16 v[80:83], v[182:185], v[220:223], v[80:83]
	v_mfma_f32_16x16x32_bf16 v[68:71], v[174:177], v[232:235], v[68:71]
	v_mfma_f32_16x16x32_bf16 v[64:67], v[182:185], v[232:235], v[64:67]
	v_mfma_f32_16x16x32_bf16 v[116:119], v[178:181], v[194:197], v[116:119]
	v_mfma_f32_16x16x32_bf16 v[112:115], v[186:189], v[194:197], v[112:115]
	v_mfma_f32_16x16x32_bf16 v[100:103], v[178:181], v[202:205], v[100:103]
	v_mfma_f32_16x16x32_bf16 v[96:99], v[186:189], v[202:205], v[96:99]
	v_mfma_f32_16x16x32_bf16 v[84:87], v[178:181], v[228:231], v[84:87]
	v_mfma_f32_16x16x32_bf16 v[80:83], v[186:189], v[228:231], v[80:83]
	v_mfma_f32_16x16x32_bf16 v[68:71], v[178:181], v[236:239], v[68:71]
	v_mfma_f32_16x16x32_bf16 v[64:67], v[186:189], v[236:239], v[64:67]
	s_setprio 0
	s_barrier
	s_add_i32 s29, s29, s68
	v_lshl_add_u64 v[142:143], v[142:143], 0, s[4:5]
	s_mov_b32 m0, s29
	ds_read_b128 v[190:193], v147 offset:49152
	ds_read_b128 v[194:197], v147 offset:50176
	ds_read_b128 v[198:201], v147 offset:51200
	ds_read_b128 v[202:205], v147 offset:52224
	ds_read_b128 v[220:223], v147 offset:53248
	ds_read_b128 v[228:231], v147 offset:54272
	ds_read_b128 v[232:235], v147 offset:55296
	ds_read_b128 v[236:239], v147 offset:56320
	global_load_lds_dwordx4 v[142:143], off
	s_add_i32 m0, s29, 0x2000
	s_add_u32 s30, s62, 0x40080
	v_lshl_add_u64 v[142:143], v[240:241], 0, s[4:5]
	s_addc_u32 s31, s63, 0
	s_add_i32 s29, s53, s68
	global_load_lds_dwordx4 v[142:143], off
	v_lshl_add_u64 v[142:143], s[30:31], 0, v[162:163]
	s_mov_b32 m0, s29
	s_nop 0
	global_load_lds_dwordx4 v[142:143], off
	v_lshl_add_u64 v[142:143], s[30:31], 0, v[128:129]
	s_add_i32 m0, s29, 0x2000
	s_nop 0
	global_load_lds_dwordx4 v[142:143], off
	v_lshl_add_u64 v[142:143], v[242:243], 0, s[4:5]
	s_mov_b32 m0, s74
	s_nop 0
	global_load_lds_dwordx4 v[142:143], off
	v_lshl_add_u64 v[142:143], v[244:245], 0, s[4:5]
	s_mov_b32 m0, s75
	s_nop 0
	global_load_lds_dwordx4 v[142:143], off
	s_waitcnt vmcnt(8)
	s_waitcnt lgkmcnt(0)
	s_barrier
	s_setprio 1
	s_waitcnt lgkmcnt(0)
	v_mfma_f32_16x16x32_bf16 v[60:63], v[138:141], v[190:193], v[60:63]
	v_mfma_f32_16x16x32_bf16 v[56:59], v[152:155], v[190:193], v[56:59]
	v_mfma_f32_16x16x32_bf16 v[44:47], v[138:141], v[198:201], v[44:47]
	v_mfma_f32_16x16x32_bf16 v[40:43], v[152:155], v[198:201], v[40:43]
	v_mfma_f32_16x16x32_bf16 v[28:31], v[138:141], v[220:223], v[28:31]
	v_mfma_f32_16x16x32_bf16 v[24:27], v[152:155], v[220:223], v[24:27]
	v_mfma_f32_16x16x32_bf16 v[12:15], v[138:141], v[232:235], v[12:15]
	v_mfma_f32_16x16x32_bf16 v[8:11], v[152:155], v[232:235], v[8:11]
	v_mfma_f32_16x16x32_bf16 v[60:63], v[148:151], v[194:197], v[60:63]
	v_mfma_f32_16x16x32_bf16 v[56:59], v[156:159], v[194:197], v[56:59]
	v_mfma_f32_16x16x32_bf16 v[44:47], v[148:151], v[202:205], v[44:47]
	v_mfma_f32_16x16x32_bf16 v[40:43], v[156:159], v[202:205], v[40:43]
	v_mfma_f32_16x16x32_bf16 v[28:31], v[148:151], v[228:231], v[28:31]
	v_mfma_f32_16x16x32_bf16 v[24:27], v[156:159], v[228:231], v[24:27]
	v_mfma_f32_16x16x32_bf16 v[12:15], v[148:151], v[236:239], v[12:15]
	v_mfma_f32_16x16x32_bf16 v[8:11], v[156:159], v[236:239], v[8:11]
	v_mfma_f32_16x16x32_bf16 v[52:55], v[174:177], v[190:193], v[52:55]
	v_mfma_f32_16x16x32_bf16 v[48:51], v[182:185], v[190:193], v[48:51]
	v_mfma_f32_16x16x32_bf16 v[36:39], v[174:177], v[198:201], v[36:39]
	v_mfma_f32_16x16x32_bf16 v[32:35], v[182:185], v[198:201], v[32:35]
	v_mfma_f32_16x16x32_bf16 v[20:23], v[174:177], v[220:223], v[20:23]
	v_mfma_f32_16x16x32_bf16 v[16:19], v[182:185], v[220:223], v[16:19]
	v_mfma_f32_16x16x32_bf16 v[4:7], v[174:177], v[232:235], v[4:7]
	v_mfma_f32_16x16x32_bf16 v[0:3], v[182:185], v[232:235], v[0:3]
	v_mfma_f32_16x16x32_bf16 v[52:55], v[178:181], v[194:197], v[52:55]
	v_mfma_f32_16x16x32_bf16 v[48:51], v[186:189], v[194:197], v[48:51]
	v_mfma_f32_16x16x32_bf16 v[36:39], v[178:181], v[202:205], v[36:39]
	v_mfma_f32_16x16x32_bf16 v[32:35], v[186:189], v[202:205], v[32:35]
	v_mfma_f32_16x16x32_bf16 v[20:23], v[178:181], v[228:231], v[20:23]
	v_mfma_f32_16x16x32_bf16 v[16:19], v[186:189], v[228:231], v[16:19]
	v_mfma_f32_16x16x32_bf16 v[4:7], v[178:181], v[236:239], v[4:7]
	v_mfma_f32_16x16x32_bf16 v[0:3], v[186:189], v[236:239], v[0:3]
	s_setprio 0
	s_barrier
	s_add_i32 s28, s28, 2
	s_add_u32 s60, s60, 0x100
	s_addc_u32 s61, s61, 0
	s_add_u32 s26, s26, 0x100
	s_addc_u32 s27, s27, 0
	s_cmp_gt_u32 s28, 13
	s_cbranch_scc0 .LBB0_975
	s_and_b64 vcc, exec, s[50:51]
	s_cbranch_vccz .LBB0_978
	s_barrier

.LBB0_1066:
	s_add_u32 s29, s58, 0xfffc0080
	s_addc_u32 s30, s59, -1
	s_add_i32 s31, 0, 0x10000
	s_cmp_eq_u32 s28, 12
	s_cselect_b32 s63, s6, s30
	s_cselect_b32 s62, s7, s29
	v_add_u32_e32 v142, s31, v144
	s_cselect_b32 s61, s24, s27
	s_cselect_b32 s60, s25, s26
	s_add_i32 s29, 0, 0x14000
	ds_read_b128 v[138:141], v142
	ds_read_b128 v[148:151], v142 offset:1024
	ds_read_b128 v[152:155], v142 offset:2048
	ds_read_b128 v[156:159], v142 offset:3072
	v_add_u32_e32 v142, s29, v144
	ds_read_b128 v[174:177], v142
	ds_read_b128 v[178:181], v142 offset:1024
	ds_read_b128 v[182:185], v142 offset:2048
	ds_read_b128 v[186:189], v142 offset:3072
	v_lshl_add_u64 v[240:241], s[58:59], 0, v[134:135]
	s_add_i32 m0, s67, 0xc000
	ds_read_b128 v[190:193], v146
	ds_read_b128 v[194:197], v146 offset:1024
	ds_read_b128 v[198:201], v146 offset:2048
	ds_read_b128 v[202:205], v146 offset:3072
	ds_read_b128 v[220:223], v146 offset:4096
	ds_read_b128 v[228:231], v146 offset:5120
	ds_read_b128 v[232:235], v146 offset:6144
	ds_read_b128 v[236:239], v146 offset:7168
	global_load_lds_dwordx4 v[240:241], off
	v_lshl_add_u64 v[240:241], s[58:59], 0, v[136:137]
	s_add_i32 m0, s67, 0xe000
	s_nop 0
	global_load_lds_dwordx4 v[240:241], off
	s_waitcnt vmcnt(8)
	s_waitcnt lgkmcnt(0)
	s_barrier
	s_setprio 1
	s_waitcnt lgkmcnt(0)
	v_mfma_f32_16x16x32_bf16 v[124:127], v[138:141], v[190:193], v[124:127]
	v_mfma_f32_16x16x32_bf16 v[120:123], v[152:155], v[190:193], v[120:123]
	v_mfma_f32_16x16x32_bf16 v[108:111], v[138:141], v[198:201], v[108:111]
	v_mfma_f32_16x16x32_bf16 v[104:107], v[152:155], v[198:201], v[104:107]
	v_mfma_f32_16x16x32_bf16 v[92:95], v[138:141], v[220:223], v[92:95]
	v_mfma_f32_16x16x32_bf16 v[88:91], v[152:155], v[220:223], v[88:91]
	v_mfma_f32_16x16x32_bf16 v[76:79], v[138:141], v[232:235], v[76:79]
	v_mfma_f32_16x16x32_bf16 v[72:75], v[152:155], v[232:235], v[72:75]
	v_mfma_f32_16x16x32_bf16 v[124:127], v[148:151], v[194:197], v[124:127]
	v_mfma_f32_16x16x32_bf16 v[120:123], v[156:159], v[194:197], v[120:123]
	v_mfma_f32_16x16x32_bf16 v[108:111], v[148:151], v[202:205], v[108:111]
	v_mfma_f32_16x16x32_bf16 v[104:107], v[156:159], v[202:205], v[104:107]
	v_mfma_f32_16x16x32_bf16 v[92:95], v[148:151], v[228:231], v[92:95]
	v_mfma_f32_16x16x32_bf16 v[88:91], v[156:159], v[228:231], v[88:91]
	v_mfma_f32_16x16x32_bf16 v[76:79], v[148:151], v[236:239], v[76:79]
	v_mfma_f32_16x16x32_bf16 v[72:75], v[156:159], v[236:239], v[72:75]
	v_mfma_f32_16x16x32_bf16 v[116:119], v[174:177], v[190:193], v[116:119]
	v_mfma_f32_16x16x32_bf16 v[112:115], v[182:185], v[190:193], v[112:115]
	v_mfma_f32_16x16x32_bf16 v[100:103], v[174:177], v[198:201], v[100:103]
	v_mfma_f32_16x16x32_bf16 v[96:99], v[182:185], v[198:201], v[96:99]
	v_mfma_f32_16x16x32_bf16 v[84:87], v[174:177], v[220:223], v[84:87]
	v_mfma_f32_16x16x32_bf16 v[80:83], v[182:185], v[220:223], v[80:83]
	v_mfma_f32_16x16x32_bf16 v[68:71], v[174:177], v[232:235], v[68:71]
	v_mfma_f32_16x16x32_bf16 v[64:67], v[182:185], v[232:235], v[64:67]
	v_mfma_f32_16x16x32_bf16 v[116:119], v[178:181], v[194:197], v[116:119]
	v_mfma_f32_16x16x32_bf16 v[112:115], v[186:189], v[194:197], v[112:115]
	v_mfma_f32_16x16x32_bf16 v[100:103], v[178:181], v[202:205], v[100:103]
	v_mfma_f32_16x16x32_bf16 v[96:99], v[186:189], v[202:205], v[96:99]
	v_mfma_f32_16x16x32_bf16 v[84:87], v[178:181], v[228:231], v[84:87]
	v_mfma_f32_16x16x32_bf16 v[80:83], v[186:189], v[228:231], v[80:83]
	v_mfma_f32_16x16x32_bf16 v[68:71], v[178:181], v[236:239], v[68:71]
	v_mfma_f32_16x16x32_bf16 v[64:67], v[186:189], v[236:239], v[64:67]
	s_setprio 0
	s_barrier
	s_add_i32 s30, s31, s66
	v_lshl_add_u64 v[240:241], s[60:61], 0, v[162:163]
	s_mov_b32 m0, s30
	ds_read_b128 v[190:193], v146 offset:16384
	ds_read_b128 v[194:197], v146 offset:17408
	ds_read_b128 v[198:201], v146 offset:18432
	ds_read_b128 v[202:205], v146 offset:19456
	ds_read_b128 v[220:223], v146 offset:20480
	ds_read_b128 v[228:231], v146 offset:21504
	ds_read_b128 v[232:235], v146 offset:22528
	ds_read_b128 v[236:239], v146 offset:23552
	global_load_lds_dwordx4 v[240:241], off
	s_add_i32 m0, s30, 0x2000
	s_add_u32 s30, s60, 0x40000
	v_lshl_add_u64 v[242:243], s[60:61], 0, v[128:129]
	s_addc_u32 s31, s61, 0
	s_add_i32 s29, s29, s66
	global_load_lds_dwordx4 v[242:243], off
	v_lshl_add_u64 v[244:245], s[30:31], 0, v[162:163]
	s_mov_b32 m0, s29
	v_lshl_add_u64 v[246:247], s[62:63], 0, v[130:131]
	global_load_lds_dwordx4 v[244:245], off
	v_lshl_add_u64 v[244:245], s[30:31], 0, v[128:129]
	s_add_i32 m0, s29, 0x2000
	s_nop 0
	global_load_lds_dwordx4 v[244:245], off
	v_lshl_add_u64 v[244:245], s[62:63], 0, v[132:133]
	s_mov_b32 m0, s67
	s_nop 0
	global_load_lds_dwordx4 v[244:245], off
	s_mov_b32 m0, s68
	s_nop 0
	global_load_lds_dwordx4 v[246:247], off
	s_waitcnt vmcnt(8)
	s_waitcnt lgkmcnt(0)
	s_barrier
	s_setprio 1
	s_waitcnt lgkmcnt(0)
	v_mfma_f32_16x16x32_bf16 v[60:63], v[138:141], v[190:193], v[60:63]
	v_mfma_f32_16x16x32_bf16 v[56:59], v[152:155], v[190:193], v[56:59]
	v_mfma_f32_16x16x32_bf16 v[44:47], v[138:141], v[198:201], v[44:47]
	v_mfma_f32_16x16x32_bf16 v[40:43], v[152:155], v[198:201], v[40:43]
	v_mfma_f32_16x16x32_bf16 v[28:31], v[138:141], v[220:223], v[28:31]
	v_mfma_f32_16x16x32_bf16 v[24:27], v[152:155], v[220:223], v[24:27]
	v_mfma_f32_16x16x32_bf16 v[12:15], v[138:141], v[232:235], v[12:15]
	v_mfma_f32_16x16x32_bf16 v[8:11], v[152:155], v[232:235], v[8:11]
	v_mfma_f32_16x16x32_bf16 v[60:63], v[148:151], v[194:197], v[60:63]
	v_mfma_f32_16x16x32_bf16 v[56:59], v[156:159], v[194:197], v[56:59]
	v_mfma_f32_16x16x32_bf16 v[44:47], v[148:151], v[202:205], v[44:47]
	v_mfma_f32_16x16x32_bf16 v[40:43], v[156:159], v[202:205], v[40:43]
	v_mfma_f32_16x16x32_bf16 v[28:31], v[148:151], v[228:231], v[28:31]
	v_mfma_f32_16x16x32_bf16 v[24:27], v[156:159], v[228:231], v[24:27]
	v_mfma_f32_16x16x32_bf16 v[12:15], v[148:151], v[236:239], v[12:15]
	v_mfma_f32_16x16x32_bf16 v[8:11], v[156:159], v[236:239], v[8:11]
	v_mfma_f32_16x16x32_bf16 v[52:55], v[174:177], v[190:193], v[52:55]
	v_mfma_f32_16x16x32_bf16 v[48:51], v[182:185], v[190:193], v[48:51]
	v_mfma_f32_16x16x32_bf16 v[36:39], v[174:177], v[198:201], v[36:39]
	v_mfma_f32_16x16x32_bf16 v[32:35], v[182:185], v[198:201], v[32:35]
	v_mfma_f32_16x16x32_bf16 v[20:23], v[174:177], v[220:223], v[20:23]
	v_mfma_f32_16x16x32_bf16 v[16:19], v[182:185], v[220:223], v[16:19]
	v_mfma_f32_16x16x32_bf16 v[4:7], v[174:177], v[232:235], v[4:7]
	v_mfma_f32_16x16x32_bf16 v[0:3], v[182:185], v[232:235], v[0:3]
	v_mfma_f32_16x16x32_bf16 v[52:55], v[178:181], v[194:197], v[52:55]
	v_mfma_f32_16x16x32_bf16 v[48:51], v[186:189], v[194:197], v[48:51]
	v_mfma_f32_16x16x32_bf16 v[36:39], v[178:181], v[202:205], v[36:39]
	v_mfma_f32_16x16x32_bf16 v[32:35], v[186:189], v[202:205], v[32:35]
	v_mfma_f32_16x16x32_bf16 v[20:23], v[178:181], v[228:231], v[20:23]
	v_mfma_f32_16x16x32_bf16 v[16:19], v[186:189], v[228:231], v[16:19]
	v_mfma_f32_16x16x32_bf16 v[4:7], v[178:181], v[236:239], v[4:7]
	v_mfma_f32_16x16x32_bf16 v[0:3], v[186:189], v[236:239], v[0:3]
	s_setprio 0
	s_barrier
	s_add_i32 s29, 0, 0x18000
	v_add_u32_e32 v142, s29, v144
	s_add_i32 s51, 0, 0x1c000
	ds_read_b128 v[138:141], v142
	ds_read_b128 v[148:151], v142 offset:1024
	ds_read_b128 v[152:155], v142 offset:2048
	ds_read_b128 v[156:159], v142 offset:3072
	v_add_u32_e32 v142, s51, v144
	ds_read_b128 v[174:177], v142
	ds_read_b128 v[178:181], v142 offset:1024
	ds_read_b128 v[182:185], v142 offset:2048
	ds_read_b128 v[186:189], v142 offset:3072
	s_add_u32 s30, s62, 0x40000
	s_addc_u32 s31, s63, 0
	s_mov_b32 m0, s69
	v_lshl_add_u64 v[248:249], s[30:31], 0, v[132:133]
	ds_read_b128 v[190:193], v146 offset:32768
	ds_read_b128 v[194:197], v146 offset:33792
	ds_read_b128 v[198:201], v146 offset:34816
	ds_read_b128 v[202:205], v146 offset:35840
	ds_read_b128 v[220:223], v146 offset:36864
	ds_read_b128 v[228:231], v146 offset:37888
	ds_read_b128 v[232:235], v146 offset:38912
	ds_read_b128 v[236:239], v146 offset:39936
	global_load_lds_dwordx4 v[248:249], off
	v_lshl_add_u64 v[248:249], s[30:31], 0, v[130:131]
	s_mov_b32 m0, s70
	s_nop 0
	global_load_lds_dwordx4 v[248:249], off
	s_waitcnt vmcnt(8)
	s_waitcnt lgkmcnt(0)
	s_barrier
	s_setprio 1
	s_waitcnt lgkmcnt(0)
	v_mfma_f32_16x16x32_bf16 v[124:127], v[138:141], v[190:193], v[124:127]
	v_mfma_f32_16x16x32_bf16 v[120:123], v[152:155], v[190:193], v[120:123]
	v_mfma_f32_16x16x32_bf16 v[108:111], v[138:141], v[198:201], v[108:111]
	v_mfma_f32_16x16x32_bf16 v[104:107], v[152:155], v[198:201], v[104:107]
	v_mfma_f32_16x16x32_bf16 v[92:95], v[138:141], v[220:223], v[92:95]
	v_mfma_f32_16x16x32_bf16 v[88:91], v[152:155], v[220:223], v[88:91]
	v_mfma_f32_16x16x32_bf16 v[76:79], v[138:141], v[232:235], v[76:79]
	v_mfma_f32_16x16x32_bf16 v[72:75], v[152:155], v[232:235], v[72:75]
	v_mfma_f32_16x16x32_bf16 v[124:127], v[148:151], v[194:197], v[124:127]
	v_mfma_f32_16x16x32_bf16 v[120:123], v[156:159], v[194:197], v[120:123]
	v_mfma_f32_16x16x32_bf16 v[108:111], v[148:151], v[202:205], v[108:111]
	v_mfma_f32_16x16x32_bf16 v[104:107], v[156:159], v[202:205], v[104:107]
	v_mfma_f32_16x16x32_bf16 v[92:95], v[148:151], v[228:231], v[92:95]
	v_mfma_f32_16x16x32_bf16 v[88:91], v[156:159], v[228:231], v[88:91]
	v_mfma_f32_16x16x32_bf16 v[76:79], v[148:151], v[236:239], v[76:79]
	v_mfma_f32_16x16x32_bf16 v[72:75], v[156:159], v[236:239], v[72:75]
	v_mfma_f32_16x16x32_bf16 v[116:119], v[174:177], v[190:193], v[116:119]
	v_mfma_f32_16x16x32_bf16 v[112:115], v[182:185], v[190:193], v[112:115]
	v_mfma_f32_16x16x32_bf16 v[100:103], v[174:177], v[198:201], v[100:103]
	v_mfma_f32_16x16x32_bf16 v[96:99], v[182:185], v[198:201], v[96:99]
	v_mfma_f32_16x16x32_bf16 v[84:87], v[174:177], v[220:223], v[84:87]
	v_mfma_f32_16x16x32_bf16 v[80:83], v[182:185], v[220:223], v[80:83]
	v_mfma_f32_16x16x32_bf16 v[68:71], v[174:177], v[232:235], v[68:71]
	v_mfma_f32_16x16x32_bf16 v[64:67], v[182:185], v[232:235], v[64:67]
	v_mfma_f32_16x16x32_bf16 v[116:119], v[178:181], v[194:197], v[116:119]
	v_mfma_f32_16x16x32_bf16 v[112:115], v[186:189], v[194:197], v[112:115]
	v_mfma_f32_16x16x32_bf16 v[100:103], v[178:181], v[202:205], v[100:103]
	v_mfma_f32_16x16x32_bf16 v[96:99], v[186:189], v[202:205], v[96:99]
	v_mfma_f32_16x16x32_bf16 v[84:87], v[178:181], v[228:231], v[84:87]
	v_mfma_f32_16x16x32_bf16 v[80:83], v[186:189], v[228:231], v[80:83]
	v_mfma_f32_16x16x32_bf16 v[68:71], v[178:181], v[236:239], v[68:71]
	v_mfma_f32_16x16x32_bf16 v[64:67], v[186:189], v[236:239], v[64:67]
	s_setprio 0
	s_barrier
	s_add_i32 s29, s29, s66
	v_lshl_add_u64 v[240:241], v[240:241], 0, s[4:5]
	s_mov_b32 m0, s29
	ds_read_b128 v[190:193], v146 offset:49152
	ds_read_b128 v[194:197], v146 offset:50176
	ds_read_b128 v[198:201], v146 offset:51200
	ds_read_b128 v[202:205], v146 offset:52224
	ds_read_b128 v[220:223], v146 offset:53248
	ds_read_b128 v[228:231], v146 offset:54272
	ds_read_b128 v[232:235], v146 offset:55296
	ds_read_b128 v[236:239], v146 offset:56320
	global_load_lds_dwordx4 v[240:241], off
	s_add_i32 m0, s29, 0x2000
	s_add_u32 s30, s60, 0x40080
	v_lshl_add_u64 v[240:241], v[242:243], 0, s[4:5]
	s_addc_u32 s31, s61, 0
	s_add_i32 s29, s51, s66
	global_load_lds_dwordx4 v[240:241], off
	v_lshl_add_u64 v[240:241], s[30:31], 0, v[162:163]
	s_mov_b32 m0, s29
	s_nop 0
	global_load_lds_dwordx4 v[240:241], off
	v_lshl_add_u64 v[240:241], s[30:31], 0, v[128:129]
	s_add_i32 m0, s29, 0x2000
	s_nop 0
	global_load_lds_dwordx4 v[240:241], off
	v_lshl_add_u64 v[240:241], v[244:245], 0, s[4:5]
	s_mov_b32 m0, s71
	s_nop 0
	global_load_lds_dwordx4 v[240:241], off
	v_lshl_add_u64 v[240:241], v[246:247], 0, s[4:5]
	s_mov_b32 m0, s72
	s_nop 0
	global_load_lds_dwordx4 v[240:241], off
	s_waitcnt vmcnt(8)
	s_waitcnt lgkmcnt(0)
	s_barrier
	s_setprio 1
	s_waitcnt lgkmcnt(0)
	v_mfma_f32_16x16x32_bf16 v[60:63], v[138:141], v[190:193], v[60:63]
	v_mfma_f32_16x16x32_bf16 v[56:59], v[152:155], v[190:193], v[56:59]
	v_mfma_f32_16x16x32_bf16 v[44:47], v[138:141], v[198:201], v[44:47]
	v_mfma_f32_16x16x32_bf16 v[40:43], v[152:155], v[198:201], v[40:43]
	v_mfma_f32_16x16x32_bf16 v[28:31], v[138:141], v[220:223], v[28:31]
	v_mfma_f32_16x16x32_bf16 v[24:27], v[152:155], v[220:223], v[24:27]
	v_mfma_f32_16x16x32_bf16 v[12:15], v[138:141], v[232:235], v[12:15]
	v_mfma_f32_16x16x32_bf16 v[8:11], v[152:155], v[232:235], v[8:11]
	v_mfma_f32_16x16x32_bf16 v[60:63], v[148:151], v[194:197], v[60:63]
	v_mfma_f32_16x16x32_bf16 v[56:59], v[156:159], v[194:197], v[56:59]
	v_mfma_f32_16x16x32_bf16 v[44:47], v[148:151], v[202:205], v[44:47]
	v_mfma_f32_16x16x32_bf16 v[40:43], v[156:159], v[202:205], v[40:43]
	v_mfma_f32_16x16x32_bf16 v[28:31], v[148:151], v[228:231], v[28:31]
	v_mfma_f32_16x16x32_bf16 v[24:27], v[156:159], v[228:231], v[24:27]
	v_mfma_f32_16x16x32_bf16 v[12:15], v[148:151], v[236:239], v[12:15]
	v_mfma_f32_16x16x32_bf16 v[8:11], v[156:159], v[236:239], v[8:11]
	v_mfma_f32_16x16x32_bf16 v[52:55], v[174:177], v[190:193], v[52:55]
	v_mfma_f32_16x16x32_bf16 v[48:51], v[182:185], v[190:193], v[48:51]
	v_mfma_f32_16x16x32_bf16 v[36:39], v[174:177], v[198:201], v[36:39]
	v_mfma_f32_16x16x32_bf16 v[32:35], v[182:185], v[198:201], v[32:35]
	v_mfma_f32_16x16x32_bf16 v[20:23], v[174:177], v[220:223], v[20:23]
	v_mfma_f32_16x16x32_bf16 v[16:19], v[182:185], v[220:223], v[16:19]
	v_mfma_f32_16x16x32_bf16 v[4:7], v[174:177], v[232:235], v[4:7]
	v_mfma_f32_16x16x32_bf16 v[0:3], v[182:185], v[232:235], v[0:3]
	v_mfma_f32_16x16x32_bf16 v[52:55], v[178:181], v[194:197], v[52:55]
	v_mfma_f32_16x16x32_bf16 v[48:51], v[186:189], v[194:197], v[48:51]
	v_mfma_f32_16x16x32_bf16 v[36:39], v[178:181], v[202:205], v[36:39]
	v_mfma_f32_16x16x32_bf16 v[32:35], v[186:189], v[202:205], v[32:35]
	v_mfma_f32_16x16x32_bf16 v[20:23], v[178:181], v[228:231], v[20:23]
	v_mfma_f32_16x16x32_bf16 v[16:19], v[186:189], v[228:231], v[16:19]
	v_mfma_f32_16x16x32_bf16 v[4:7], v[178:181], v[236:239], v[4:7]
	v_mfma_f32_16x16x32_bf16 v[0:3], v[186:189], v[236:239], v[0:3]
	s_setprio 0
	s_barrier
	s_add_i32 s28, s28, 2
	s_add_u32 s58, s58, 0x100
	s_addc_u32 s59, s59, 0
	s_add_u32 s26, s26, 0x100
	s_addc_u32 s27, s27, 0
	s_cmp_gt_u32 s28, 13
	s_cbranch_scc0 .LBB0_1066
	s_and_b64 vcc, exec, s[48:49]
	s_cbranch_vccz .LBB0_1069
	s_barrier

.LBB0_1280:
	s_add_u32 s60, s58, 0x100
	s_addc_u32 s61, s59, 0
	s_add_i32 s25, 0, 0x10000
	s_cmp_eq_u32 s24, 40
	s_cselect_b32 s65, s45, s61
	s_cselect_b32 s64, s44, s60
	v_add_u32_e32 v142, s25, v145
	s_cselect_b32 s63, s57, s7
	s_cselect_b32 s62, s56, s6
	s_add_i32 s28, 0, 0x14000
	ds_read_b128 v[138:141], v142
	ds_read_b128 v[148:151], v142 offset:1024
	ds_read_b128 v[152:155], v142 offset:2048
	ds_read_b128 v[156:159], v142 offset:3072
	v_add_u32_e32 v142, s28, v145
	ds_read_b128 v[174:177], v142
	ds_read_b128 v[178:181], v142 offset:1024
	ds_read_b128 v[182:185], v142 offset:2048
	ds_read_b128 v[186:189], v142 offset:3072
	v_lshl_add_u64 v[142:143], s[58:59], 0, v[134:135]
	s_add_i32 m0, s68, 0xc000
	ds_read_b128 v[190:193], v147
	ds_read_b128 v[194:197], v147 offset:1024
	ds_read_b128 v[198:201], v147 offset:2048
	ds_read_b128 v[202:205], v147 offset:3072
	ds_read_b128 v[220:223], v147 offset:4096
	ds_read_b128 v[228:231], v147 offset:5120
	ds_read_b128 v[232:235], v147 offset:6144
	ds_read_b128 v[236:239], v147 offset:7168
	global_load_lds_dwordx4 v[142:143], off
	v_lshl_add_u64 v[142:143], s[58:59], 0, v[136:137]
	s_add_i32 m0, s68, 0xe000
	s_nop 0
	global_load_lds_dwordx4 v[142:143], off
	s_waitcnt vmcnt(8)
	s_waitcnt lgkmcnt(0)
	s_barrier
	s_setprio 1
	s_waitcnt lgkmcnt(0)
	v_mfma_f32_16x16x32_bf16 v[124:127], v[138:141], v[190:193], v[124:127]
	v_mfma_f32_16x16x32_bf16 v[120:123], v[152:155], v[190:193], v[120:123]
	v_mfma_f32_16x16x32_bf16 v[108:111], v[138:141], v[198:201], v[108:111]
	v_mfma_f32_16x16x32_bf16 v[104:107], v[152:155], v[198:201], v[104:107]
	v_mfma_f32_16x16x32_bf16 v[92:95], v[138:141], v[220:223], v[92:95]
	v_mfma_f32_16x16x32_bf16 v[88:91], v[152:155], v[220:223], v[88:91]
	v_mfma_f32_16x16x32_bf16 v[76:79], v[138:141], v[232:235], v[76:79]
	v_mfma_f32_16x16x32_bf16 v[72:75], v[152:155], v[232:235], v[72:75]
	v_mfma_f32_16x16x32_bf16 v[124:127], v[148:151], v[194:197], v[124:127]
	v_mfma_f32_16x16x32_bf16 v[120:123], v[156:159], v[194:197], v[120:123]
	v_mfma_f32_16x16x32_bf16 v[108:111], v[148:151], v[202:205], v[108:111]
	v_mfma_f32_16x16x32_bf16 v[104:107], v[156:159], v[202:205], v[104:107]
	v_mfma_f32_16x16x32_bf16 v[92:95], v[148:151], v[228:231], v[92:95]
	v_mfma_f32_16x16x32_bf16 v[88:91], v[156:159], v[228:231], v[88:91]
	v_mfma_f32_16x16x32_bf16 v[76:79], v[148:151], v[236:239], v[76:79]
	v_mfma_f32_16x16x32_bf16 v[72:75], v[156:159], v[236:239], v[72:75]
	v_mfma_f32_16x16x32_bf16 v[116:119], v[174:177], v[190:193], v[116:119]
	v_mfma_f32_16x16x32_bf16 v[112:115], v[182:185], v[190:193], v[112:115]
	v_mfma_f32_16x16x32_bf16 v[100:103], v[174:177], v[198:201], v[100:103]
	v_mfma_f32_16x16x32_bf16 v[96:99], v[182:185], v[198:201], v[96:99]
	v_mfma_f32_16x16x32_bf16 v[84:87], v[174:177], v[220:223], v[84:87]
	v_mfma_f32_16x16x32_bf16 v[80:83], v[182:185], v[220:223], v[80:83]
	v_mfma_f32_16x16x32_bf16 v[68:71], v[174:177], v[232:235], v[68:71]
	v_mfma_f32_16x16x32_bf16 v[64:67], v[182:185], v[232:235], v[64:67]
	v_mfma_f32_16x16x32_bf16 v[116:119], v[178:181], v[194:197], v[116:119]
	v_mfma_f32_16x16x32_bf16 v[112:115], v[186:189], v[194:197], v[112:115]
	v_mfma_f32_16x16x32_bf16 v[100:103], v[178:181], v[202:205], v[100:103]
	v_mfma_f32_16x16x32_bf16 v[96:99], v[186:189], v[202:205], v[96:99]
	v_mfma_f32_16x16x32_bf16 v[84:87], v[178:181], v[228:231], v[84:87]
	v_mfma_f32_16x16x32_bf16 v[80:83], v[186:189], v[228:231], v[80:83]
	v_mfma_f32_16x16x32_bf16 v[68:71], v[178:181], v[236:239], v[68:71]
	v_mfma_f32_16x16x32_bf16 v[64:67], v[186:189], v[236:239], v[64:67]
	s_setprio 0
	s_barrier
	s_add_i32 s25, s25, s67
	v_lshl_add_u64 v[142:143], s[62:63], 0, v[162:163]
	s_mov_b32 m0, s25
	ds_read_b128 v[190:193], v147 offset:16384
	ds_read_b128 v[194:197], v147 offset:17408
	ds_read_b128 v[198:201], v147 offset:18432
	ds_read_b128 v[202:205], v147 offset:19456
	ds_read_b128 v[220:223], v147 offset:20480
	ds_read_b128 v[228:231], v147 offset:21504
	ds_read_b128 v[232:235], v147 offset:22528
	ds_read_b128 v[236:239], v147 offset:23552
	global_load_lds_dwordx4 v[142:143], off
	s_add_i32 m0, s25, 0x2000
	s_add_u32 s26, s62, 0xb0000
	v_lshl_add_u64 v[240:241], s[62:63], 0, v[128:129]
	s_addc_u32 s27, s63, 0
	s_add_i32 s25, s28, s67
	global_load_lds_dwordx4 v[240:241], off
	v_lshl_add_u64 v[242:243], s[26:27], 0, v[162:163]
	s_mov_b32 m0, s25
	v_lshl_add_u64 v[244:245], s[64:65], 0, v[130:131]
	global_load_lds_dwordx4 v[242:243], off
	v_lshl_add_u64 v[242:243], s[26:27], 0, v[128:129]
	s_add_i32 m0, s25, 0x2000
	s_nop 0
	global_load_lds_dwordx4 v[242:243], off
	v_lshl_add_u64 v[242:243], s[64:65], 0, v[132:133]
	s_mov_b32 m0, s68
	s_nop 0
	global_load_lds_dwordx4 v[242:243], off
	s_mov_b32 m0, s69
	s_nop 0
	global_load_lds_dwordx4 v[244:245], off
	s_waitcnt vmcnt(8)
	s_waitcnt lgkmcnt(0)
	s_barrier
	s_setprio 1
	s_waitcnt lgkmcnt(0)
	v_mfma_f32_16x16x32_bf16 v[60:63], v[138:141], v[190:193], v[60:63]
	v_mfma_f32_16x16x32_bf16 v[56:59], v[152:155], v[190:193], v[56:59]
	v_mfma_f32_16x16x32_bf16 v[44:47], v[138:141], v[198:201], v[44:47]
	v_mfma_f32_16x16x32_bf16 v[40:43], v[152:155], v[198:201], v[40:43]
	v_mfma_f32_16x16x32_bf16 v[28:31], v[138:141], v[220:223], v[28:31]
	v_mfma_f32_16x16x32_bf16 v[24:27], v[152:155], v[220:223], v[24:27]
	v_mfma_f32_16x16x32_bf16 v[12:15], v[138:141], v[232:235], v[12:15]
	v_mfma_f32_16x16x32_bf16 v[8:11], v[152:155], v[232:235], v[8:11]
	v_mfma_f32_16x16x32_bf16 v[60:63], v[148:151], v[194:197], v[60:63]
	v_mfma_f32_16x16x32_bf16 v[56:59], v[156:159], v[194:197], v[56:59]
	v_mfma_f32_16x16x32_bf16 v[44:47], v[148:151], v[202:205], v[44:47]
	v_mfma_f32_16x16x32_bf16 v[40:43], v[156:159], v[202:205], v[40:43]
	v_mfma_f32_16x16x32_bf16 v[28:31], v[148:151], v[228:231], v[28:31]
	v_mfma_f32_16x16x32_bf16 v[24:27], v[156:159], v[228:231], v[24:27]
	v_mfma_f32_16x16x32_bf16 v[12:15], v[148:151], v[236:239], v[12:15]
	v_mfma_f32_16x16x32_bf16 v[8:11], v[156:159], v[236:239], v[8:11]
	v_mfma_f32_16x16x32_bf16 v[52:55], v[174:177], v[190:193], v[52:55]
	v_mfma_f32_16x16x32_bf16 v[48:51], v[182:185], v[190:193], v[48:51]
	v_mfma_f32_16x16x32_bf16 v[36:39], v[174:177], v[198:201], v[36:39]
	v_mfma_f32_16x16x32_bf16 v[32:35], v[182:185], v[198:201], v[32:35]
	v_mfma_f32_16x16x32_bf16 v[20:23], v[174:177], v[220:223], v[20:23]
	v_mfma_f32_16x16x32_bf16 v[16:19], v[182:185], v[220:223], v[16:19]
	v_mfma_f32_16x16x32_bf16 v[4:7], v[174:177], v[232:235], v[4:7]
	v_mfma_f32_16x16x32_bf16 v[0:3], v[182:185], v[232:235], v[0:3]
	v_mfma_f32_16x16x32_bf16 v[52:55], v[178:181], v[194:197], v[52:55]
	v_mfma_f32_16x16x32_bf16 v[48:51], v[186:189], v[194:197], v[48:51]
	v_mfma_f32_16x16x32_bf16 v[36:39], v[178:181], v[202:205], v[36:39]
	v_mfma_f32_16x16x32_bf16 v[32:35], v[186:189], v[202:205], v[32:35]
	v_mfma_f32_16x16x32_bf16 v[20:23], v[178:181], v[228:231], v[20:23]
	v_mfma_f32_16x16x32_bf16 v[16:19], v[186:189], v[228:231], v[16:19]
	v_mfma_f32_16x16x32_bf16 v[4:7], v[178:181], v[236:239], v[4:7]
	v_mfma_f32_16x16x32_bf16 v[0:3], v[186:189], v[236:239], v[0:3]
	s_setprio 0
	s_barrier
	s_add_i32 s25, 0, 0x18000
	s_add_i32 s28, 0, 0x1c000
	v_add_u32_e32 v156, s25, v145
	v_add_u32_e32 v186, s28, v145
	ds_read_b128 v[138:141], v156
	ds_read_b128 v[148:151], v156 offset:1024
	ds_read_b128 v[152:155], v156 offset:2048
	ds_read_b128 v[156:159], v156 offset:3072
	ds_read_b128 v[174:177], v186
	ds_read_b128 v[178:181], v186 offset:1024
	ds_read_b128 v[182:185], v186 offset:2048
	ds_read_b128 v[186:189], v186 offset:3072
	s_add_u32 s26, s64, 0xb0000
	s_addc_u32 s27, s65, 0
	s_mov_b32 m0, s70
	v_lshl_add_u64 v[246:247], s[26:27], 0, v[132:133]
	ds_read_b128 v[190:193], v147 offset:32768
	ds_read_b128 v[194:197], v147 offset:33792
	ds_read_b128 v[198:201], v147 offset:34816
	ds_read_b128 v[202:205], v147 offset:35840
	ds_read_b128 v[220:223], v147 offset:36864
	ds_read_b128 v[228:231], v147 offset:37888
	ds_read_b128 v[232:235], v147 offset:38912
	ds_read_b128 v[236:239], v147 offset:39936
	global_load_lds_dwordx4 v[246:247], off
	v_lshl_add_u64 v[246:247], s[26:27], 0, v[130:131]
	s_mov_b32 m0, s71
	s_nop 0
	global_load_lds_dwordx4 v[246:247], off
	s_waitcnt vmcnt(8)
	s_waitcnt lgkmcnt(0)
	s_barrier
	s_setprio 1
	s_waitcnt lgkmcnt(0)
	v_mfma_f32_16x16x32_bf16 v[124:127], v[138:141], v[190:193], v[124:127]
	v_mfma_f32_16x16x32_bf16 v[120:123], v[152:155], v[190:193], v[120:123]
	v_mfma_f32_16x16x32_bf16 v[108:111], v[138:141], v[198:201], v[108:111]
	v_mfma_f32_16x16x32_bf16 v[104:107], v[152:155], v[198:201], v[104:107]
	v_mfma_f32_16x16x32_bf16 v[92:95], v[138:141], v[220:223], v[92:95]
	v_mfma_f32_16x16x32_bf16 v[88:91], v[152:155], v[220:223], v[88:91]
	v_mfma_f32_16x16x32_bf16 v[76:79], v[138:141], v[232:235], v[76:79]
	v_mfma_f32_16x16x32_bf16 v[72:75], v[152:155], v[232:235], v[72:75]
	v_mfma_f32_16x16x32_bf16 v[124:127], v[148:151], v[194:197], v[124:127]
	v_mfma_f32_16x16x32_bf16 v[120:123], v[156:159], v[194:197], v[120:123]
	v_mfma_f32_16x16x32_bf16 v[108:111], v[148:151], v[202:205], v[108:111]
	v_mfma_f32_16x16x32_bf16 v[104:107], v[156:159], v[202:205], v[104:107]
	v_mfma_f32_16x16x32_bf16 v[92:95], v[148:151], v[228:231], v[92:95]
	v_mfma_f32_16x16x32_bf16 v[88:91], v[156:159], v[228:231], v[88:91]
	v_mfma_f32_16x16x32_bf16 v[76:79], v[148:151], v[236:239], v[76:79]
	v_mfma_f32_16x16x32_bf16 v[72:75], v[156:159], v[236:239], v[72:75]
	v_mfma_f32_16x16x32_bf16 v[116:119], v[174:177], v[190:193], v[116:119]
	v_mfma_f32_16x16x32_bf16 v[112:115], v[182:185], v[190:193], v[112:115]
	v_mfma_f32_16x16x32_bf16 v[100:103], v[174:177], v[198:201], v[100:103]
	v_mfma_f32_16x16x32_bf16 v[96:99], v[182:185], v[198:201], v[96:99]
	v_mfma_f32_16x16x32_bf16 v[84:87], v[174:177], v[220:223], v[84:87]
	v_mfma_f32_16x16x32_bf16 v[80:83], v[182:185], v[220:223], v[80:83]
	v_mfma_f32_16x16x32_bf16 v[68:71], v[174:177], v[232:235], v[68:71]
	v_mfma_f32_16x16x32_bf16 v[64:67], v[182:185], v[232:235], v[64:67]
	v_mfma_f32_16x16x32_bf16 v[116:119], v[178:181], v[194:197], v[116:119]
	v_mfma_f32_16x16x32_bf16 v[112:115], v[186:189], v[194:197], v[112:115]
	v_mfma_f32_16x16x32_bf16 v[100:103], v[178:181], v[202:205], v[100:103]
	v_mfma_f32_16x16x32_bf16 v[96:99], v[186:189], v[202:205], v[96:99]
	v_mfma_f32_16x16x32_bf16 v[84:87], v[178:181], v[228:231], v[84:87]
	v_mfma_f32_16x16x32_bf16 v[80:83], v[186:189], v[228:231], v[80:83]
	v_mfma_f32_16x16x32_bf16 v[68:71], v[178:181], v[236:239], v[68:71]
	v_mfma_f32_16x16x32_bf16 v[64:67], v[186:189], v[236:239], v[64:67]
	s_setprio 0
	s_barrier
	s_add_i32 s25, s25, s67
	v_lshl_add_u64 v[142:143], v[142:143], 0, s[4:5]
	s_mov_b32 m0, s25
	ds_read_b128 v[190:193], v147 offset:49152
	ds_read_b128 v[194:197], v147 offset:50176
	ds_read_b128 v[198:201], v147 offset:51200
	ds_read_b128 v[202:205], v147 offset:52224
	ds_read_b128 v[220:223], v147 offset:53248
	ds_read_b128 v[228:231], v147 offset:54272
	ds_read_b128 v[232:235], v147 offset:55296
	ds_read_b128 v[236:239], v147 offset:56320
	global_load_lds_dwordx4 v[142:143], off
	s_add_i32 m0, s25, 0x2000
	s_add_u32 s26, s62, 0xb0080
	v_lshl_add_u64 v[142:143], v[240:241], 0, s[4:5]
	s_addc_u32 s27, s63, 0
	s_add_i32 s25, s28, s67
	global_load_lds_dwordx4 v[142:143], off
	v_lshl_add_u64 v[142:143], s[26:27], 0, v[162:163]
	s_mov_b32 m0, s25
	s_nop 0
	global_load_lds_dwordx4 v[142:143], off
	v_lshl_add_u64 v[142:143], s[26:27], 0, v[128:129]
	s_add_i32 m0, s25, 0x2000
	s_nop 0
	global_load_lds_dwordx4 v[142:143], off
	v_lshl_add_u64 v[142:143], v[242:243], 0, s[4:5]
	s_mov_b32 m0, s73
	s_nop 0
	global_load_lds_dwordx4 v[142:143], off
	v_lshl_add_u64 v[142:143], v[244:245], 0, s[4:5]
	s_mov_b32 m0, s74
	s_nop 0
	global_load_lds_dwordx4 v[142:143], off
	s_waitcnt vmcnt(8)
	s_waitcnt lgkmcnt(0)
	s_barrier
	s_setprio 1
	s_waitcnt lgkmcnt(0)
	v_mfma_f32_16x16x32_bf16 v[60:63], v[138:141], v[190:193], v[60:63]
	v_mfma_f32_16x16x32_bf16 v[56:59], v[152:155], v[190:193], v[56:59]
	v_mfma_f32_16x16x32_bf16 v[44:47], v[138:141], v[198:201], v[44:47]
	v_mfma_f32_16x16x32_bf16 v[40:43], v[152:155], v[198:201], v[40:43]
	v_mfma_f32_16x16x32_bf16 v[28:31], v[138:141], v[220:223], v[28:31]
	v_mfma_f32_16x16x32_bf16 v[24:27], v[152:155], v[220:223], v[24:27]
	v_mfma_f32_16x16x32_bf16 v[12:15], v[138:141], v[232:235], v[12:15]
	v_mfma_f32_16x16x32_bf16 v[8:11], v[152:155], v[232:235], v[8:11]
	v_mfma_f32_16x16x32_bf16 v[60:63], v[148:151], v[194:197], v[60:63]
	v_mfma_f32_16x16x32_bf16 v[56:59], v[156:159], v[194:197], v[56:59]
	v_mfma_f32_16x16x32_bf16 v[44:47], v[148:151], v[202:205], v[44:47]
	v_mfma_f32_16x16x32_bf16 v[40:43], v[156:159], v[202:205], v[40:43]
	v_mfma_f32_16x16x32_bf16 v[28:31], v[148:151], v[228:231], v[28:31]
	v_mfma_f32_16x16x32_bf16 v[24:27], v[156:159], v[228:231], v[24:27]
	v_mfma_f32_16x16x32_bf16 v[12:15], v[148:151], v[236:239], v[12:15]
	v_mfma_f32_16x16x32_bf16 v[8:11], v[156:159], v[236:239], v[8:11]
	v_mfma_f32_16x16x32_bf16 v[52:55], v[174:177], v[190:193], v[52:55]
	v_mfma_f32_16x16x32_bf16 v[48:51], v[182:185], v[190:193], v[48:51]
	v_mfma_f32_16x16x32_bf16 v[36:39], v[174:177], v[198:201], v[36:39]
	v_mfma_f32_16x16x32_bf16 v[32:35], v[182:185], v[198:201], v[32:35]
	v_mfma_f32_16x16x32_bf16 v[20:23], v[174:177], v[220:223], v[20:23]
	v_mfma_f32_16x16x32_bf16 v[16:19], v[182:185], v[220:223], v[16:19]
	v_mfma_f32_16x16x32_bf16 v[4:7], v[174:177], v[232:235], v[4:7]
	v_mfma_f32_16x16x32_bf16 v[0:3], v[182:185], v[232:235], v[0:3]
	v_mfma_f32_16x16x32_bf16 v[52:55], v[178:181], v[194:197], v[52:55]
	v_mfma_f32_16x16x32_bf16 v[48:51], v[186:189], v[194:197], v[48:51]
	v_mfma_f32_16x16x32_bf16 v[36:39], v[178:181], v[202:205], v[36:39]
	v_mfma_f32_16x16x32_bf16 v[32:35], v[186:189], v[202:205], v[32:35]
	v_mfma_f32_16x16x32_bf16 v[20:23], v[178:181], v[228:231], v[20:23]
	v_mfma_f32_16x16x32_bf16 v[16:19], v[186:189], v[228:231], v[16:19]
	v_mfma_f32_16x16x32_bf16 v[4:7], v[178:181], v[236:239], v[4:7]
	v_mfma_f32_16x16x32_bf16 v[0:3], v[186:189], v[236:239], v[0:3]
	s_setprio 0
	s_barrier
	s_add_i32 s24, s24, 2
	s_add_u32 s6, s6, 0x100
	s_addc_u32 s7, s7, 0
	s_cmp_gt_u32 s24, 41
	s_mov_b64 s[58:59], s[60:61]
	s_cbranch_scc0 .LBB0_1280
	s_and_b64 vcc, exec, s[54:55]
	s_cbranch_vccz .LBB0_1283
	s_barrier
